# GEMM phase prologues keep their vmcnt(6); the first tile's peeled iteration retires the prologue loads with a flagged vmcnt(6) in phase 2
# speedup vs baseline: 1.0065x; 1.0065x over previous
_Z8yoco_fwd4Args:
	s_mov_b32 s99, 0
	s_mov_b32 s98, 0
	s_load_dwordx2 s[38:39], s[0:1], 0xd0
	s_load_dword s14, s[0:1], 0xd8
	s_add_u32 s4, s0, 0xd0
	s_addc_u32 s5, s1, 0
	v_and_b32_e32 v168, 0x3ff, v0
	v_writelane_b32 v244, s4, 0
	v_cmp_gt_u32_e32 vcc, 2, v168
	s_nop 0
	v_writelane_b32 v244, s5, 1
	s_and_saveexec_b64 s[6:7], vcc
	v_lshl_add_u32 v1, v168, 2, 0
	v_add_u32_e32 v1, 0x20040, v1
	v_mov_b32_e32 v2, 0
	ds_write_b32 v1, v2
	s_or_b64 exec, exec, s[6:7]
	s_cmp_lg_u32 s2, 0
	s_mov_b32 s16, 0
	s_cbranch_scc1 .LBB0_10
	s_mov_b64 s[4:5], s[0:1]
	s_load_dwordx2 s[4:5], s[4:5], 0xc8
	v_sub_u32_e32 v1, 0xd7f, v168
	v_lshrrev_b32_e32 v2, 9, v1
	v_add_u32_e32 v1, 2, v2
	v_add_u32_e32 v169, 0x200, v168
	s_waitcnt lgkmcnt(0)
	s_add_u32 s6, s4, 0x4000
	v_and_b32_e32 v3, 14, v1
	s_addc_u32 s7, s5, 0
	v_mov_b32_e32 v1, v2
	s_mov_b64 s[8:9], 0
	s_mov_b32 s17, 1
	v_mov_b32_e32 v5, 0
	s_mov_b32 s10, s16
	v_mov_b64_e32 v[6:7], v[168:169]
	s_branch .LBB0_5

.LBB0_177:
	s_add_u32 s6, s4, 0x100000
	s_addc_u32 s7, s5, 0
	s_add_u32 s4, s4, 0x10000000
	s_addc_u32 s5, s5, 0
	s_lshl_b32 s8, s8, 5
	s_and_b32 s16, s8, 0x60
	s_mov_b64 s[8:9], 0x80
	s_add_i32 m0, s23, 0x18000
	v_lshl_add_u64 v[6:7], v[6:7], 0, s[8:9]
	s_lshl_b32 s46, s1, 6
	s_lshl_b32 s1, s1, 13
	s_lshl_b32 s13, s16, 7
	s_waitcnt vmcnt(2)
	s_barrier
	global_load_lds_dwordx4 v[6:7], off
	v_lshl_add_u64 v[4:5], v[4:5], 0, s[8:9]
	s_add_i32 m0, s23, 0x1a000
	s_add_i32 s47, s23, 0x8000
	s_add_i32 s48, s23, 0xa000
	global_load_lds_dwordx4 v[4:5], off
	v_lshl_add_u64 v[0:1], v[0:1], 0, s[8:9]
	s_mov_b32 m0, s47
	s_add_u32 s14, s26, 0x40080
	global_load_lds_dwordx4 v[0:1], off
	v_lshl_add_u64 v[0:1], v[2:3], 0, s[8:9]
	s_mov_b32 m0, s48
	s_addc_u32 s15, s27, 0
	global_load_lds_dwordx4 v[0:1], off
	s_add_i32 m0, s23, 0x1c000
	v_lshl_add_u64 v[0:1], s[14:15], 0, v[130:131]
	global_load_lds_dwordx4 v[0:1], off
	v_lshl_add_u64 v[0:1], s[14:15], 0, v[134:135]
	s_add_i32 m0, s23, 0x1e000
	v_and_b32_e32 v151, 15, v8
	global_load_lds_dwordx4 v[0:1], off
	v_lshrrev_b32_e32 v0, 1, v8
	v_and_b32_e32 v1, 24, v0
	v_lshlrev_b32_e32 v0, 1, v1
	v_lshlrev_b32_e32 v2, 2, v8
	v_or_b32_e32 v155, s16, v1
	v_lshlrev_b32_e32 v1, 14, v9
	v_lshl_or_b32 v0, v151, 6, v0
	v_and_b32_e32 v2, 32, v2
	v_lshlrev_b32_e32 v136, 5, v151
	v_and_b32_e32 v1, 0xffff8000, v1
	v_bitop3_b32 v4, v0, s1, v2 bitop3:0xde
	v_bitop3_b32 v153, v0, s13, v2 bitop3:0xde
	v_lshl_add_u64 v[2:3], s[4:5], 0, v[136:137]
	v_and_b32_e32 v136, 16, v8
	v_lshl_add_u32 v1, v10, 11, v1
	v_lshl_add_u64 v[138:139], v[2:3], 0, v[136:137]
	v_lshl_add_u64 v[140:141], s[4:5], 0, v[136:137]
	v_add3_u32 v136, v1, v11, v12
	v_lshlrev_b32_e32 v1, 14, v13
	s_ashr_i32 s49, s38, 31
	v_and_b32_e32 v1, 0xffff8000, v1
	s_mov_b64 s[14:15], 0x40080
	s_waitcnt vmcnt(6)
	s_mov_b32 s99, 1
	s_cmpk_lt_u32 s0, 0x100
	v_mov_b32_e32 v0, 0x100
	v_lshl_add_u32 v1, v14, 11, v1
	s_sext_i32_i8 s54, s12
	s_cselect_b64 s[12:13], -1, 0
	v_lshl_or_b32 v0, v151, 4, v0
	v_lshl_add_u64 v[142:143], v[136:137], 0, s[14:15]
	v_add3_u32 v136, v1, v15, v16
	s_add_i32 s51, 0, 0x10000
	s_add_i32 s52, 0, 0x14000
	s_mov_b32 s50, s38
	v_lshl_add_u64 v[144:145], v[136:137], 0, s[14:15]
	v_mov_b64_e32 v[146:147], 0x400
	v_mov_b64_e32 v[148:149], 0x3ff
	v_add_u32_e32 v157, s51, v153
	v_add_u32_e32 v158, s52, v153
	v_add_u32_e32 v159, 0, v4
	s_mov_b32 s53, 0x280000
	v_lshlrev_b32_e32 v136, 1, v0
	v_mov_b32_e32 v160, 0x500
	s_barrier
	s_branch .LBB0_180

.Lrestag_187:
	ds_read_b128 v[162:165], v157
	ds_read_b128 v[170:173], v157 offset:1024
	ds_read_b128 v[174:177], v157 offset:2048
	ds_read_b128 v[178:181], v157 offset:3072
	ds_read_b128 v[182:185], v158
	ds_read_b128 v[186:189], v158 offset:1024
	ds_read_b128 v[190:193], v158 offset:2048
	ds_read_b128 v[194:197], v158 offset:3072
	s_add_u32 s26, s24, 0x100
	s_addc_u32 s27, s25, 0
	s_cmp_eq_u32 s59, 12
	s_cselect_b32 s31, s17, s27
	s_cselect_b32 s30, s55, s26
	s_cselect_b32 s29, s15, s58
	s_cselect_b32 s28, s56, s57
	s_add_i32 m0, s23, 0xc000
	ds_read_b128 v[198:201], v159
	ds_read_b128 v[202:205], v159 offset:1024
	ds_read_b128 v[206:209], v159 offset:2048
	ds_read_b128 v[210:213], v159 offset:3072
	ds_read_b128 v[214:217], v159 offset:4096
	ds_read_b128 v[218:221], v159 offset:5120
	ds_read_b128 v[222:225], v159 offset:6144
	ds_read_b128 v[226:229], v159 offset:7168
	global_load_lds_dwordx4 v142, s[24:25]
	s_add_i32 m0, s23, 0xe000
	s_nop 0
	global_load_lds_dwordx4 v144, s[24:25]
	s_nop 0
	s_waitcnt lgkmcnt(0)
	s_setprio 1
	s_barrier
	v_mfma_f32_16x16x32_bf16 v[124:127], v[162:165], v[198:201], 0
	v_mfma_f32_16x16x32_bf16 v[120:123], v[174:177], v[198:201], 0
	v_mfma_f32_16x16x32_bf16 v[112:115], v[162:165], v[206:209], 0
	v_mfma_f32_16x16x32_bf16 v[104:107], v[174:177], v[206:209], 0
	v_mfma_f32_16x16x32_bf16 v[96:99], v[162:165], v[214:217], 0
	v_mfma_f32_16x16x32_bf16 v[88:91], v[174:177], v[214:217], 0
	v_mfma_f32_16x16x32_bf16 v[80:83], v[162:165], v[222:225], 0
	v_mfma_f32_16x16x32_bf16 v[72:75], v[174:177], v[222:225], 0
	v_mfma_f32_16x16x32_bf16 v[124:127], v[170:173], v[202:205], v[124:127]
	v_mfma_f32_16x16x32_bf16 v[120:123], v[178:181], v[202:205], v[120:123]
	v_mfma_f32_16x16x32_bf16 v[112:115], v[170:173], v[210:213], v[112:115]
	v_mfma_f32_16x16x32_bf16 v[104:107], v[178:181], v[210:213], v[104:107]
	v_mfma_f32_16x16x32_bf16 v[96:99], v[170:173], v[218:221], v[96:99]
	v_mfma_f32_16x16x32_bf16 v[88:91], v[178:181], v[218:221], v[88:91]
	v_mfma_f32_16x16x32_bf16 v[80:83], v[170:173], v[226:229], v[80:83]
	v_mfma_f32_16x16x32_bf16 v[72:75], v[178:181], v[226:229], v[72:75]
	v_mfma_f32_16x16x32_bf16 v[116:119], v[182:185], v[198:201], 0
	v_mfma_f32_16x16x32_bf16 v[108:111], v[190:193], v[198:201], 0
	v_mfma_f32_16x16x32_bf16 v[100:103], v[182:185], v[206:209], 0
	v_mfma_f32_16x16x32_bf16 v[92:95], v[190:193], v[206:209], 0
	v_mfma_f32_16x16x32_bf16 v[84:87], v[182:185], v[214:217], 0
	v_mfma_f32_16x16x32_bf16 v[76:79], v[190:193], v[214:217], 0
	v_mfma_f32_16x16x32_bf16 v[68:71], v[182:185], v[222:225], 0
	v_mfma_f32_16x16x32_bf16 v[64:67], v[190:193], v[222:225], 0
	v_mfma_f32_16x16x32_bf16 v[116:119], v[186:189], v[202:205], v[116:119]
	v_mfma_f32_16x16x32_bf16 v[108:111], v[194:197], v[202:205], v[108:111]
	v_mfma_f32_16x16x32_bf16 v[100:103], v[186:189], v[210:213], v[100:103]
	v_mfma_f32_16x16x32_bf16 v[92:95], v[194:197], v[210:213], v[92:95]
	v_mfma_f32_16x16x32_bf16 v[84:87], v[186:189], v[218:221], v[84:87]
	v_mfma_f32_16x16x32_bf16 v[76:79], v[194:197], v[218:221], v[76:79]
	v_mfma_f32_16x16x32_bf16 v[68:71], v[186:189], v[226:229], v[68:71]
	v_mfma_f32_16x16x32_bf16 v[64:67], v[194:197], v[226:229], v[64:67]
	s_barrier
	s_setprio 0
	s_add_i32 s0, s51, s41
	v_lshl_add_u64 v[166:167], s[28:29], 0, v[130:131]
	s_mov_b32 m0, s0
	ds_read_b128 v[198:201], v159 offset:16384
	ds_read_b128 v[202:205], v159 offset:17408
	ds_read_b128 v[206:209], v159 offset:18432
	ds_read_b128 v[210:213], v159 offset:19456
	ds_read_b128 v[214:217], v159 offset:20480
	ds_read_b128 v[218:221], v159 offset:21504
	ds_read_b128 v[222:225], v159 offset:22528
	ds_read_b128 v[226:229], v159 offset:23552
	global_load_lds_dwordx4 v[166:167], off
	s_add_i32 m0, s0, 0x2000
	s_add_u32 s0, s28, 0x40000
	v_lshl_add_u64 v[230:231], s[28:29], 0, v[134:135]
	s_addc_u32 s1, s29, 0
	s_add_i32 s24, s52, s41
	global_load_lds_dwordx4 v[230:231], off
	s_mov_b32 m0, s24
	v_lshl_add_u64 v[234:235], s[30:31], 0, v[132:133]
	global_load_lds_dwordx4 v130, s[0:1]
	s_add_i32 m0, s24, 0x2000
	s_nop 0
	global_load_lds_dwordx4 v134, s[0:1]
	v_lshl_add_u64 v[232:233], s[30:31], 0, v[128:129]
	s_cmp_eq_u32 s99, 1
	s_cbranch_scc0 .Lft_187
	s_waitcnt vmcnt(6)
	s_mov_b32 s99, 0
.Lft_187:
	s_waitcnt lgkmcnt(0)
	s_setprio 1
	s_barrier
	v_mfma_f32_16x16x32_bf16 v[60:63], v[162:165], v[198:201], 0
	v_mfma_f32_16x16x32_bf16 v[56:59], v[174:177], v[198:201], 0
	v_mfma_f32_16x16x32_bf16 v[48:51], v[162:165], v[206:209], 0
	v_mfma_f32_16x16x32_bf16 v[40:43], v[174:177], v[206:209], 0
	v_mfma_f32_16x16x32_bf16 v[32:35], v[162:165], v[214:217], 0
	v_mfma_f32_16x16x32_bf16 v[24:27], v[174:177], v[214:217], 0
	v_mfma_f32_16x16x32_bf16 v[16:19], v[162:165], v[222:225], 0
	v_mfma_f32_16x16x32_bf16 v[8:11], v[174:177], v[222:225], 0
	v_mfma_f32_16x16x32_bf16 v[60:63], v[170:173], v[202:205], v[60:63]
	v_mfma_f32_16x16x32_bf16 v[56:59], v[178:181], v[202:205], v[56:59]
	v_mfma_f32_16x16x32_bf16 v[48:51], v[170:173], v[210:213], v[48:51]
	v_mfma_f32_16x16x32_bf16 v[40:43], v[178:181], v[210:213], v[40:43]
	v_mfma_f32_16x16x32_bf16 v[32:35], v[170:173], v[218:221], v[32:35]
	v_mfma_f32_16x16x32_bf16 v[24:27], v[178:181], v[218:221], v[24:27]
	v_mfma_f32_16x16x32_bf16 v[16:19], v[170:173], v[226:229], v[16:19]
	v_mfma_f32_16x16x32_bf16 v[8:11], v[178:181], v[226:229], v[8:11]
	v_mfma_f32_16x16x32_bf16 v[52:55], v[182:185], v[198:201], 0
	v_mfma_f32_16x16x32_bf16 v[44:47], v[190:193], v[198:201], 0
	v_mfma_f32_16x16x32_bf16 v[36:39], v[182:185], v[206:209], 0
	v_mfma_f32_16x16x32_bf16 v[28:31], v[190:193], v[206:209], 0
	v_mfma_f32_16x16x32_bf16 v[20:23], v[182:185], v[214:217], 0
	v_mfma_f32_16x16x32_bf16 v[12:15], v[190:193], v[214:217], 0
	v_mfma_f32_16x16x32_bf16 v[4:7], v[182:185], v[222:225], 0
	v_mfma_f32_16x16x32_bf16 v[0:3], v[190:193], v[222:225], 0
	v_mfma_f32_16x16x32_bf16 v[52:55], v[186:189], v[202:205], v[52:55]
	v_mfma_f32_16x16x32_bf16 v[44:47], v[194:197], v[202:205], v[44:47]
	v_mfma_f32_16x16x32_bf16 v[36:39], v[186:189], v[210:213], v[36:39]
	v_mfma_f32_16x16x32_bf16 v[28:31], v[194:197], v[210:213], v[28:31]
	v_mfma_f32_16x16x32_bf16 v[20:23], v[186:189], v[218:221], v[20:23]
	v_mfma_f32_16x16x32_bf16 v[12:15], v[194:197], v[218:221], v[12:15]
	v_mfma_f32_16x16x32_bf16 v[4:7], v[186:189], v[226:229], v[4:7]
	v_mfma_f32_16x16x32_bf16 v[0:3], v[194:197], v[226:229], v[0:3]
	s_barrier
	s_setprio 0
	s_add_i32 s24, 0, 0x18000
	v_add_u32_e32 v150, s24, v153
	s_add_i32 s25, 0, 0x1c000
	ds_read_b128 v[162:165], v150
	ds_read_b128 v[170:173], v150 offset:1024
	ds_read_b128 v[174:177], v150 offset:2048
	ds_read_b128 v[178:181], v150 offset:3072
	v_add_u32_e32 v150, s25, v153
	ds_read_b128 v[182:185], v150
	ds_read_b128 v[186:189], v150 offset:1024
	ds_read_b128 v[190:193], v150 offset:2048
	ds_read_b128 v[194:197], v150 offset:3072
	s_add_u32 s0, s30, 0x40000
	s_addc_u32 s1, s31, 0
	s_mov_b32 m0, s43
	ds_read_b128 v[198:201], v159 offset:32768
	ds_read_b128 v[202:205], v159 offset:33792
	ds_read_b128 v[206:209], v159 offset:34816
	ds_read_b128 v[210:213], v159 offset:35840
	ds_read_b128 v[214:217], v159 offset:36864
	ds_read_b128 v[218:221], v159 offset:37888
	ds_read_b128 v[222:225], v159 offset:38912
	ds_read_b128 v[226:229], v159 offset:39936
	global_load_lds_dwordx4 v128, s[0:1]
	s_mov_b32 m0, s44
	s_nop 0
	global_load_lds_dwordx4 v132, s[0:1]
	s_mov_b32 m0, s23
	s_nop 0
	global_load_lds_dwordx4 v[232:233], off
	s_mov_b32 m0, s42
	s_nop 0
	global_load_lds_dwordx4 v[234:235], off
	s_waitcnt vmcnt(8)
	s_waitcnt lgkmcnt(0)
	s_setprio 1
	s_barrier
	v_mfma_f32_16x16x32_bf16 v[124:127], v[162:165], v[198:201], v[124:127]
	v_mfma_f32_16x16x32_bf16 v[120:123], v[174:177], v[198:201], v[120:123]
	v_mfma_f32_16x16x32_bf16 v[112:115], v[162:165], v[206:209], v[112:115]
	v_mfma_f32_16x16x32_bf16 v[104:107], v[174:177], v[206:209], v[104:107]
	v_mfma_f32_16x16x32_bf16 v[96:99], v[162:165], v[214:217], v[96:99]
	v_mfma_f32_16x16x32_bf16 v[88:91], v[174:177], v[214:217], v[88:91]
	v_mfma_f32_16x16x32_bf16 v[80:83], v[162:165], v[222:225], v[80:83]
	v_mfma_f32_16x16x32_bf16 v[72:75], v[174:177], v[222:225], v[72:75]
	v_mfma_f32_16x16x32_bf16 v[124:127], v[170:173], v[202:205], v[124:127]
	v_mfma_f32_16x16x32_bf16 v[120:123], v[178:181], v[202:205], v[120:123]
	v_mfma_f32_16x16x32_bf16 v[112:115], v[170:173], v[210:213], v[112:115]
	v_mfma_f32_16x16x32_bf16 v[104:107], v[178:181], v[210:213], v[104:107]
	v_mfma_f32_16x16x32_bf16 v[96:99], v[170:173], v[218:221], v[96:99]
	v_mfma_f32_16x16x32_bf16 v[88:91], v[178:181], v[218:221], v[88:91]
	v_mfma_f32_16x16x32_bf16 v[80:83], v[170:173], v[226:229], v[80:83]
	v_mfma_f32_16x16x32_bf16 v[72:75], v[178:181], v[226:229], v[72:75]
	v_mfma_f32_16x16x32_bf16 v[116:119], v[182:185], v[198:201], v[116:119]
	v_mfma_f32_16x16x32_bf16 v[108:111], v[190:193], v[198:201], v[108:111]
	v_mfma_f32_16x16x32_bf16 v[100:103], v[182:185], v[206:209], v[100:103]
	v_mfma_f32_16x16x32_bf16 v[92:95], v[190:193], v[206:209], v[92:95]
	v_mfma_f32_16x16x32_bf16 v[84:87], v[182:185], v[214:217], v[84:87]
	v_mfma_f32_16x16x32_bf16 v[76:79], v[190:193], v[214:217], v[76:79]
	v_mfma_f32_16x16x32_bf16 v[68:71], v[182:185], v[222:225], v[68:71]
	v_mfma_f32_16x16x32_bf16 v[64:67], v[190:193], v[222:225], v[64:67]
	v_mfma_f32_16x16x32_bf16 v[116:119], v[186:189], v[202:205], v[116:119]
	v_mfma_f32_16x16x32_bf16 v[108:111], v[194:197], v[202:205], v[108:111]
	v_mfma_f32_16x16x32_bf16 v[100:103], v[186:189], v[210:213], v[100:103]
	v_mfma_f32_16x16x32_bf16 v[92:95], v[194:197], v[210:213], v[92:95]
	v_mfma_f32_16x16x32_bf16 v[84:87], v[186:189], v[218:221], v[84:87]
	v_mfma_f32_16x16x32_bf16 v[76:79], v[194:197], v[218:221], v[76:79]
	v_mfma_f32_16x16x32_bf16 v[68:71], v[186:189], v[226:229], v[68:71]
	v_mfma_f32_16x16x32_bf16 v[64:67], v[194:197], v[226:229], v[64:67]
	s_barrier
	s_setprio 0
	s_add_i32 s0, s24, s41
	v_lshl_add_u64 v[166:167], v[166:167], 0, s[8:9]
	s_mov_b32 m0, s0
	ds_read_b128 v[198:201], v159 offset:49152
	ds_read_b128 v[202:205], v159 offset:50176
	ds_read_b128 v[206:209], v159 offset:51200
	ds_read_b128 v[210:213], v159 offset:52224
	ds_read_b128 v[214:217], v159 offset:53248
	ds_read_b128 v[218:221], v159 offset:54272
	ds_read_b128 v[222:225], v159 offset:55296
	ds_read_b128 v[226:229], v159 offset:56320
	global_load_lds_dwordx4 v[166:167], off
	s_add_i32 m0, s0, 0x2000
	s_add_u32 s0, s28, 0x40080
	v_lshl_add_u64 v[166:167], v[230:231], 0, s[8:9]
	s_addc_u32 s1, s29, 0
	s_add_i32 s24, s25, s41
	global_load_lds_dwordx4 v[166:167], off
	s_mov_b32 m0, s24
	s_nop 0
	global_load_lds_dwordx4 v130, s[0:1]
	s_add_i32 m0, s24, 0x2000
	s_nop 0
	global_load_lds_dwordx4 v134, s[0:1]
	v_lshl_add_u64 v[166:167], v[232:233], 0, s[8:9]
	s_mov_b32 m0, s47
	s_nop 0
	global_load_lds_dwordx4 v[166:167], off
	v_lshl_add_u64 v[166:167], v[234:235], 0, s[8:9]
	s_mov_b32 m0, s48
	s_nop 0
	global_load_lds_dwordx4 v[166:167], off
	s_waitcnt vmcnt(6)
	s_waitcnt lgkmcnt(0)
	s_setprio 1
	s_barrier
	v_mfma_f32_16x16x32_bf16 v[60:63], v[162:165], v[198:201], v[60:63]
	v_mfma_f32_16x16x32_bf16 v[56:59], v[174:177], v[198:201], v[56:59]
	v_mfma_f32_16x16x32_bf16 v[48:51], v[162:165], v[206:209], v[48:51]
	v_mfma_f32_16x16x32_bf16 v[40:43], v[174:177], v[206:209], v[40:43]
	v_mfma_f32_16x16x32_bf16 v[32:35], v[162:165], v[214:217], v[32:35]
	v_mfma_f32_16x16x32_bf16 v[24:27], v[174:177], v[214:217], v[24:27]
	v_mfma_f32_16x16x32_bf16 v[16:19], v[162:165], v[222:225], v[16:19]
	v_mfma_f32_16x16x32_bf16 v[8:11], v[174:177], v[222:225], v[8:11]
	v_mfma_f32_16x16x32_bf16 v[60:63], v[170:173], v[202:205], v[60:63]
	v_mfma_f32_16x16x32_bf16 v[56:59], v[178:181], v[202:205], v[56:59]
	v_mfma_f32_16x16x32_bf16 v[48:51], v[170:173], v[210:213], v[48:51]
	v_mfma_f32_16x16x32_bf16 v[40:43], v[178:181], v[210:213], v[40:43]
	v_mfma_f32_16x16x32_bf16 v[32:35], v[170:173], v[218:221], v[32:35]
	v_mfma_f32_16x16x32_bf16 v[24:27], v[178:181], v[218:221], v[24:27]
	v_mfma_f32_16x16x32_bf16 v[16:19], v[170:173], v[226:229], v[16:19]
	v_mfma_f32_16x16x32_bf16 v[8:11], v[178:181], v[226:229], v[8:11]
	v_mfma_f32_16x16x32_bf16 v[52:55], v[182:185], v[198:201], v[52:55]
	v_mfma_f32_16x16x32_bf16 v[44:47], v[190:193], v[198:201], v[44:47]
	v_mfma_f32_16x16x32_bf16 v[36:39], v[182:185], v[206:209], v[36:39]
	v_mfma_f32_16x16x32_bf16 v[28:31], v[190:193], v[206:209], v[28:31]
	v_mfma_f32_16x16x32_bf16 v[20:23], v[182:185], v[214:217], v[20:23]
	v_mfma_f32_16x16x32_bf16 v[12:15], v[190:193], v[214:217], v[12:15]
	v_mfma_f32_16x16x32_bf16 v[4:7], v[182:185], v[222:225], v[4:7]
	v_mfma_f32_16x16x32_bf16 v[0:3], v[190:193], v[222:225], v[0:3]
	v_mfma_f32_16x16x32_bf16 v[52:55], v[186:189], v[202:205], v[52:55]
	v_mfma_f32_16x16x32_bf16 v[44:47], v[194:197], v[202:205], v[44:47]
	v_mfma_f32_16x16x32_bf16 v[36:39], v[186:189], v[210:213], v[36:39]
	v_mfma_f32_16x16x32_bf16 v[28:31], v[194:197], v[210:213], v[28:31]
	v_mfma_f32_16x16x32_bf16 v[20:23], v[186:189], v[218:221], v[20:23]
	v_mfma_f32_16x16x32_bf16 v[12:15], v[194:197], v[218:221], v[12:15]
	v_mfma_f32_16x16x32_bf16 v[4:7], v[186:189], v[226:229], v[4:7]
	v_mfma_f32_16x16x32_bf16 v[0:3], v[194:197], v[226:229], v[0:3]
	s_barrier
	s_setprio 0
	s_add_i32 s59, s59, 2
	s_add_u32 s57, s57, 0x100
	s_addc_u32 s58, s58, 0
	s_cmp_gt_u32 s59, 13
	s_mov_b64 s[24:25], s[26:27]

.LBB0_388:
	s_add_u32 s12, s4, 0x1e000000
	s_addc_u32 s13, s5, 0
	s_lshl_b32 s4, s14, 5
	s_mov_b64 s[14:15], 0x80
	s_and_b32 s18, s4, 0x60
	s_add_i32 m0, s35, 0x18000
	v_lshl_add_u64 v[10:11], v[10:11], 0, s[14:15]
	s_lshl_b32 s17, s1, 13
	s_lshl_b32 s19, s18, 7
	s_waitcnt vmcnt(2)
	s_barrier
	global_load_lds_dwordx4 v[10:11], off
	v_lshl_add_u64 v[8:9], v[8:9], 0, s[14:15]
	s_add_i32 m0, s35, 0x1a000
	s_add_i32 s42, s35, 0x8000
	s_add_i32 s43, s35, 0xa000
	global_load_lds_dwordx4 v[8:9], off
	v_lshl_add_u64 v[4:5], v[4:5], 0, s[14:15]
	s_mov_b32 m0, s42
	s_add_u32 s4, s22, 0x28080
	global_load_lds_dwordx4 v[4:5], off
	v_lshl_add_u64 v[4:5], v[6:7], 0, s[14:15]
	s_mov_b32 m0, s43
	s_addc_u32 s5, s23, 0
	global_load_lds_dwordx4 v[4:5], off
	s_add_i32 m0, s35, 0x1c000
	v_lshl_add_u64 v[4:5], s[4:5], 0, v[162:163]
	global_load_lds_dwordx4 v[4:5], off
	v_lshl_add_u64 v[4:5], s[4:5], 0, v[166:167]
	s_add_i32 m0, s35, 0x1e000
	s_ashr_i32 s44, s38, 31
	global_load_lds_dwordx4 v[4:5], off
	v_lshrrev_b32_e32 v5, 1, v1
	v_and_b32_e32 v6, 24, v5
	v_and_b32_e32 v4, 15, v1
	v_lshlrev_b32_e32 v5, 1, v6
	v_lshl_or_b32 v202, s1, 6, v4
	v_lshl_or_b32 v4, v4, 6, v5
	v_lshlrev_b32_e32 v5, 2, v1
	v_and_b32_e32 v5, 32, v5
	v_lshlrev_b32_e32 v1, 1, v1
	v_bitop3_b32 v7, v4, s17, v5 bitop3:0xde
	v_bitop3_b32 v203, v4, s19, v5 bitop3:0xde
	v_and_b32_e32 v4, 32, v1
	v_mov_b32_e32 v5, v163
	s_waitcnt lgkmcnt(0)
	v_lshl_add_u64 v[170:171], s[6:7], 0, v[4:5]
	v_lshrrev_b32_e32 v1, 1, v3
	v_mul_lo_u32 v4, v12, s33
	s_movk_i32 s6, 0x5000
	s_cmpk_lt_u32 s0, 0x100
	v_mad_u64_u32 v[4:5], s[0:1], v1, s6, v[4:5]
	s_mov_b64 s[4:5], 0x28080
	v_add3_u32 v0, v4, v0, v13
	v_mov_b32_e32 v1, v163
	v_lshl_add_u64 v[172:173], v[0:1], 0, s[4:5]
	v_lshrrev_b32_e32 v1, 1, v14
	v_mul_lo_u32 v0, v15, s33
	s_waitcnt vmcnt(6)
	s_mov_b32 s99, 1
	v_mad_u64_u32 v[0:1], s[0:1], v1, s6, v[0:1]
	s_sext_i32_i8 s51, s16
	s_cselect_b64 s[16:17], -1, 0
	v_add3_u32 v0, v0, v2, v16
	v_mov_b32_e32 v1, v163
	s_add_i32 s46, 0, 0x10000
	s_add_i32 s47, 0, 0x14000
	s_mov_b32 s45, s38
	v_or_b32_e32 v204, s18, v6
	v_lshl_add_u64 v[174:175], v[0:1], 0, s[4:5]
	v_mov_b64_e32 v[176:177], 0x400
	v_mov_b64_e32 v[178:179], 0x3ff
	v_add_u32_e32 v205, s46, v203
	v_add_u32_e32 v206, s47, v203
	v_add_u32_e32 v207, 0, v7
	s_barrier
	s_branch .LBB0_391

.Lrestag_402:
	ds_read_b128 v[120:123], v205
	ds_read_b128 v[124:127], v205 offset:1024
	ds_read_b128 v[132:135], v205 offset:2048
	ds_read_b128 v[140:143], v205 offset:3072
	ds_read_b128 v[144:147], v206
	ds_read_b128 v[148:151], v206 offset:1024
	ds_read_b128 v[152:155], v206 offset:2048
	ds_read_b128 v[156:159], v206 offset:3072
	s_add_u32 s22, s20, 0x100
	s_addc_u32 s23, s21, 0
	s_cmp_eq_u32 s54, 6
	s_cselect_b32 s27, s7, s23
	s_cselect_b32 s26, s6, s22
	s_cselect_b32 s25, s19, s53
	s_cselect_b32 s24, s18, s52
	s_add_i32 m0, s35, 0xc000
	ds_read_b128 v[180:183], v207
	ds_read_b128 v[184:187], v207 offset:1024
	ds_read_b128 v[188:191], v207 offset:2048
	ds_read_b128 v[192:195], v207 offset:3072
	ds_read_b128 v[196:199], v207 offset:4096
	ds_read_b128 v[208:211], v207 offset:5120
	ds_read_b128 v[212:215], v207 offset:6144
	ds_read_b128 v[216:219], v207 offset:7168
	global_load_lds_dwordx4 v172, s[20:21]
	s_add_i32 m0, s35, 0xe000
	s_nop 0
	global_load_lds_dwordx4 v174, s[20:21]
	s_nop 0
	s_waitcnt lgkmcnt(0)
	s_setprio 1
	s_barrier
	v_mfma_f32_16x16x32_bf16 v[136:139], v[120:123], v[180:183], 0
	v_mfma_f32_16x16x32_bf16 v[128:131], v[132:135], v[180:183], 0
	v_mfma_f32_16x16x32_bf16 v[116:119], v[120:123], v[188:191], 0
	v_mfma_f32_16x16x32_bf16 v[112:115], v[132:135], v[188:191], 0
	v_mfma_f32_16x16x32_bf16 v[108:111], v[120:123], v[196:199], 0
	v_mfma_f32_16x16x32_bf16 v[104:107], v[132:135], v[196:199], 0
	v_mfma_f32_16x16x32_bf16 v[100:103], v[120:123], v[212:215], 0
	v_mfma_f32_16x16x32_bf16 v[96:99], v[132:135], v[212:215], 0
	v_mfma_f32_16x16x32_bf16 v[136:139], v[124:127], v[184:187], v[136:139]
	v_mfma_f32_16x16x32_bf16 v[128:131], v[140:143], v[184:187], v[128:131]
	v_mfma_f32_16x16x32_bf16 v[116:119], v[124:127], v[192:195], v[116:119]
	v_mfma_f32_16x16x32_bf16 v[112:115], v[140:143], v[192:195], v[112:115]
	v_mfma_f32_16x16x32_bf16 v[108:111], v[124:127], v[208:211], v[108:111]
	v_mfma_f32_16x16x32_bf16 v[104:107], v[140:143], v[208:211], v[104:107]
	v_mfma_f32_16x16x32_bf16 v[100:103], v[124:127], v[216:219], v[100:103]
	v_mfma_f32_16x16x32_bf16 v[96:99], v[140:143], v[216:219], v[96:99]
	v_mfma_f32_16x16x32_bf16 v[60:63], v[144:147], v[180:183], 0
	v_mfma_f32_16x16x32_bf16 v[56:59], v[152:155], v[180:183], 0
	v_mfma_f32_16x16x32_bf16 v[52:55], v[144:147], v[188:191], 0
	v_mfma_f32_16x16x32_bf16 v[48:51], v[152:155], v[188:191], 0
	v_mfma_f32_16x16x32_bf16 v[44:47], v[144:147], v[196:199], 0
	v_mfma_f32_16x16x32_bf16 v[40:43], v[152:155], v[196:199], 0
	v_mfma_f32_16x16x32_bf16 v[36:39], v[144:147], v[212:215], 0
	v_mfma_f32_16x16x32_bf16 v[32:35], v[152:155], v[212:215], 0
	v_mfma_f32_16x16x32_bf16 v[60:63], v[148:151], v[184:187], v[60:63]
	v_mfma_f32_16x16x32_bf16 v[56:59], v[156:159], v[184:187], v[56:59]
	v_mfma_f32_16x16x32_bf16 v[52:55], v[148:151], v[192:195], v[52:55]
	v_mfma_f32_16x16x32_bf16 v[48:51], v[156:159], v[192:195], v[48:51]
	v_mfma_f32_16x16x32_bf16 v[44:47], v[148:151], v[208:211], v[44:47]
	v_mfma_f32_16x16x32_bf16 v[40:43], v[156:159], v[208:211], v[40:43]
	v_mfma_f32_16x16x32_bf16 v[36:39], v[148:151], v[216:219], v[36:39]
	v_mfma_f32_16x16x32_bf16 v[32:35], v[156:159], v[216:219], v[32:35]
	s_barrier
	s_setprio 0
	s_add_i32 s0, s46, s34
	v_lshl_add_u64 v[200:201], s[24:25], 0, v[162:163]
	s_mov_b32 m0, s0
	ds_read_b128 v[180:183], v207 offset:16384
	ds_read_b128 v[184:187], v207 offset:17408
	ds_read_b128 v[188:191], v207 offset:18432
	ds_read_b128 v[192:195], v207 offset:19456
	ds_read_b128 v[196:199], v207 offset:20480
	ds_read_b128 v[208:211], v207 offset:21504
	ds_read_b128 v[212:215], v207 offset:22528
	ds_read_b128 v[216:219], v207 offset:23552
	global_load_lds_dwordx4 v[200:201], off
	s_add_i32 m0, s0, 0x2000
	s_add_u32 s0, s24, 0x28000
	v_lshl_add_u64 v[220:221], s[24:25], 0, v[166:167]
	s_addc_u32 s1, s25, 0
	s_add_i32 s20, s47, s34
	global_load_lds_dwordx4 v[220:221], off
	s_mov_b32 m0, s20
	v_lshl_add_u64 v[224:225], s[26:27], 0, v[164:165]
	global_load_lds_dwordx4 v162, s[0:1]
	s_add_i32 m0, s20, 0x2000
	s_nop 0
	global_load_lds_dwordx4 v166, s[0:1]
	v_lshl_add_u64 v[222:223], s[26:27], 0, v[160:161]
	s_cmp_eq_u32 s99, 1
	s_cbranch_scc0 .Lft_402
	s_waitcnt vmcnt(6)
	s_mov_b32 s99, 0
.Lft_402:
	s_waitcnt lgkmcnt(0)
	s_setprio 1
	s_barrier
	v_mfma_f32_16x16x32_bf16 v[92:95], v[120:123], v[180:183], 0
	v_mfma_f32_16x16x32_bf16 v[88:91], v[132:135], v[180:183], 0
	v_mfma_f32_16x16x32_bf16 v[84:87], v[120:123], v[188:191], 0
	v_mfma_f32_16x16x32_bf16 v[80:83], v[132:135], v[188:191], 0
	v_mfma_f32_16x16x32_bf16 v[76:79], v[120:123], v[196:199], 0
	v_mfma_f32_16x16x32_bf16 v[72:75], v[132:135], v[196:199], 0
	v_mfma_f32_16x16x32_bf16 v[68:71], v[120:123], v[212:215], 0
	v_mfma_f32_16x16x32_bf16 v[64:67], v[132:135], v[212:215], 0
	v_mfma_f32_16x16x32_bf16 v[92:95], v[124:127], v[184:187], v[92:95]
	v_mfma_f32_16x16x32_bf16 v[88:91], v[140:143], v[184:187], v[88:91]
	v_mfma_f32_16x16x32_bf16 v[84:87], v[124:127], v[192:195], v[84:87]
	v_mfma_f32_16x16x32_bf16 v[80:83], v[140:143], v[192:195], v[80:83]
	v_mfma_f32_16x16x32_bf16 v[76:79], v[124:127], v[208:211], v[76:79]
	v_mfma_f32_16x16x32_bf16 v[72:75], v[140:143], v[208:211], v[72:75]
	v_mfma_f32_16x16x32_bf16 v[68:71], v[124:127], v[216:219], v[68:71]
	v_mfma_f32_16x16x32_bf16 v[64:67], v[140:143], v[216:219], v[64:67]
	v_mfma_f32_16x16x32_bf16 v[28:31], v[144:147], v[180:183], 0
	v_mfma_f32_16x16x32_bf16 v[24:27], v[152:155], v[180:183], 0
	v_mfma_f32_16x16x32_bf16 v[20:23], v[144:147], v[188:191], 0
	v_mfma_f32_16x16x32_bf16 v[16:19], v[152:155], v[188:191], 0
	v_mfma_f32_16x16x32_bf16 v[12:15], v[144:147], v[196:199], 0
	v_mfma_f32_16x16x32_bf16 v[8:11], v[152:155], v[196:199], 0
	v_mfma_f32_16x16x32_bf16 v[4:7], v[144:147], v[212:215], 0
	v_mfma_f32_16x16x32_bf16 v[0:3], v[152:155], v[212:215], 0
	v_mfma_f32_16x16x32_bf16 v[28:31], v[148:151], v[184:187], v[28:31]
	v_mfma_f32_16x16x32_bf16 v[24:27], v[156:159], v[184:187], v[24:27]
	v_mfma_f32_16x16x32_bf16 v[20:23], v[148:151], v[192:195], v[20:23]
	v_mfma_f32_16x16x32_bf16 v[16:19], v[156:159], v[192:195], v[16:19]
	v_mfma_f32_16x16x32_bf16 v[12:15], v[148:151], v[208:211], v[12:15]
	v_mfma_f32_16x16x32_bf16 v[8:11], v[156:159], v[208:211], v[8:11]
	v_mfma_f32_16x16x32_bf16 v[4:7], v[148:151], v[216:219], v[4:7]
	v_mfma_f32_16x16x32_bf16 v[0:3], v[156:159], v[216:219], v[0:3]
	s_barrier
	s_setprio 0
	s_add_i32 s20, 0, 0x18000
	s_add_i32 s21, 0, 0x1c000
	v_add_u32_e32 v140, s20, v203
	v_add_u32_e32 v156, s21, v203
	ds_read_b128 v[120:123], v140
	ds_read_b128 v[124:127], v140 offset:1024
	ds_read_b128 v[132:135], v140 offset:2048
	ds_read_b128 v[140:143], v140 offset:3072
	ds_read_b128 v[144:147], v156
	ds_read_b128 v[148:151], v156 offset:1024
	ds_read_b128 v[152:155], v156 offset:2048
	ds_read_b128 v[156:159], v156 offset:3072
	s_add_u32 s0, s26, 0x28000
	s_addc_u32 s1, s27, 0
	s_mov_b32 m0, s37
	ds_read_b128 v[180:183], v207 offset:32768
	ds_read_b128 v[184:187], v207 offset:33792
	ds_read_b128 v[188:191], v207 offset:34816
	ds_read_b128 v[192:195], v207 offset:35840
	ds_read_b128 v[196:199], v207 offset:36864
	ds_read_b128 v[208:211], v207 offset:37888
	ds_read_b128 v[212:215], v207 offset:38912
	ds_read_b128 v[216:219], v207 offset:39936
	global_load_lds_dwordx4 v160, s[0:1]
	s_mov_b32 m0, s40
	s_nop 0
	global_load_lds_dwordx4 v164, s[0:1]
	s_mov_b32 m0, s35
	s_nop 0
	global_load_lds_dwordx4 v[222:223], off
	s_mov_b32 m0, s36
	s_nop 0
	global_load_lds_dwordx4 v[224:225], off
	s_waitcnt vmcnt(8)
	s_waitcnt lgkmcnt(0)
	s_setprio 1
	s_barrier
	v_mfma_f32_16x16x32_bf16 v[136:139], v[120:123], v[180:183], v[136:139]
	v_mfma_f32_16x16x32_bf16 v[128:131], v[132:135], v[180:183], v[128:131]
	v_mfma_f32_16x16x32_bf16 v[116:119], v[120:123], v[188:191], v[116:119]
	v_mfma_f32_16x16x32_bf16 v[112:115], v[132:135], v[188:191], v[112:115]
	v_mfma_f32_16x16x32_bf16 v[108:111], v[120:123], v[196:199], v[108:111]
	v_mfma_f32_16x16x32_bf16 v[104:107], v[132:135], v[196:199], v[104:107]
	v_mfma_f32_16x16x32_bf16 v[100:103], v[120:123], v[212:215], v[100:103]
	v_mfma_f32_16x16x32_bf16 v[96:99], v[132:135], v[212:215], v[96:99]
	v_mfma_f32_16x16x32_bf16 v[136:139], v[124:127], v[184:187], v[136:139]
	v_mfma_f32_16x16x32_bf16 v[128:131], v[140:143], v[184:187], v[128:131]
	v_mfma_f32_16x16x32_bf16 v[116:119], v[124:127], v[192:195], v[116:119]
	v_mfma_f32_16x16x32_bf16 v[112:115], v[140:143], v[192:195], v[112:115]
	v_mfma_f32_16x16x32_bf16 v[108:111], v[124:127], v[208:211], v[108:111]
	v_mfma_f32_16x16x32_bf16 v[104:107], v[140:143], v[208:211], v[104:107]
	v_mfma_f32_16x16x32_bf16 v[100:103], v[124:127], v[216:219], v[100:103]
	v_mfma_f32_16x16x32_bf16 v[96:99], v[140:143], v[216:219], v[96:99]
	v_mfma_f32_16x16x32_bf16 v[60:63], v[144:147], v[180:183], v[60:63]
	v_mfma_f32_16x16x32_bf16 v[56:59], v[152:155], v[180:183], v[56:59]
	v_mfma_f32_16x16x32_bf16 v[52:55], v[144:147], v[188:191], v[52:55]
	v_mfma_f32_16x16x32_bf16 v[48:51], v[152:155], v[188:191], v[48:51]
	v_mfma_f32_16x16x32_bf16 v[44:47], v[144:147], v[196:199], v[44:47]
	v_mfma_f32_16x16x32_bf16 v[40:43], v[152:155], v[196:199], v[40:43]
	v_mfma_f32_16x16x32_bf16 v[36:39], v[144:147], v[212:215], v[36:39]
	v_mfma_f32_16x16x32_bf16 v[32:35], v[152:155], v[212:215], v[32:35]
	v_mfma_f32_16x16x32_bf16 v[60:63], v[148:151], v[184:187], v[60:63]
	v_mfma_f32_16x16x32_bf16 v[56:59], v[156:159], v[184:187], v[56:59]
	v_mfma_f32_16x16x32_bf16 v[52:55], v[148:151], v[192:195], v[52:55]
	v_mfma_f32_16x16x32_bf16 v[48:51], v[156:159], v[192:195], v[48:51]
	v_mfma_f32_16x16x32_bf16 v[44:47], v[148:151], v[208:211], v[44:47]
	v_mfma_f32_16x16x32_bf16 v[40:43], v[156:159], v[208:211], v[40:43]
	v_mfma_f32_16x16x32_bf16 v[36:39], v[148:151], v[216:219], v[36:39]
	v_mfma_f32_16x16x32_bf16 v[32:35], v[156:159], v[216:219], v[32:35]
	s_barrier
	s_setprio 0
	s_add_i32 s0, s20, s34
	v_lshl_add_u64 v[200:201], v[200:201], 0, s[14:15]
	s_mov_b32 m0, s0
	ds_read_b128 v[180:183], v207 offset:49152
	ds_read_b128 v[184:187], v207 offset:50176
	ds_read_b128 v[188:191], v207 offset:51200
	ds_read_b128 v[192:195], v207 offset:52224
	ds_read_b128 v[196:199], v207 offset:53248
	ds_read_b128 v[208:211], v207 offset:54272
	ds_read_b128 v[212:215], v207 offset:55296
	ds_read_b128 v[216:219], v207 offset:56320
	global_load_lds_dwordx4 v[200:201], off
	s_add_i32 m0, s0, 0x2000
	s_add_u32 s0, s24, 0x28080
	v_lshl_add_u64 v[200:201], v[220:221], 0, s[14:15]
	s_addc_u32 s1, s25, 0
	s_add_i32 s20, s21, s34
	global_load_lds_dwordx4 v[200:201], off
	s_mov_b32 m0, s20
	s_nop 0
	global_load_lds_dwordx4 v162, s[0:1]
	s_add_i32 m0, s20, 0x2000
	s_nop 0
	global_load_lds_dwordx4 v166, s[0:1]
	v_lshl_add_u64 v[200:201], v[222:223], 0, s[14:15]
	s_mov_b32 m0, s42
	s_nop 0
	global_load_lds_dwordx4 v[200:201], off
	v_lshl_add_u64 v[200:201], v[224:225], 0, s[14:15]
	s_mov_b32 m0, s43
	s_nop 0
	global_load_lds_dwordx4 v[200:201], off
	s_waitcnt vmcnt(6)
	s_waitcnt lgkmcnt(0)
	s_setprio 1
	s_barrier
	v_mfma_f32_16x16x32_bf16 v[92:95], v[120:123], v[180:183], v[92:95]
	v_mfma_f32_16x16x32_bf16 v[88:91], v[132:135], v[180:183], v[88:91]
	v_mfma_f32_16x16x32_bf16 v[84:87], v[120:123], v[188:191], v[84:87]
	v_mfma_f32_16x16x32_bf16 v[80:83], v[132:135], v[188:191], v[80:83]
	v_mfma_f32_16x16x32_bf16 v[76:79], v[120:123], v[196:199], v[76:79]
	v_mfma_f32_16x16x32_bf16 v[72:75], v[132:135], v[196:199], v[72:75]
	v_mfma_f32_16x16x32_bf16 v[68:71], v[120:123], v[212:215], v[68:71]
	v_mfma_f32_16x16x32_bf16 v[64:67], v[132:135], v[212:215], v[64:67]
	v_mfma_f32_16x16x32_bf16 v[92:95], v[124:127], v[184:187], v[92:95]
	v_mfma_f32_16x16x32_bf16 v[88:91], v[140:143], v[184:187], v[88:91]
	v_mfma_f32_16x16x32_bf16 v[84:87], v[124:127], v[192:195], v[84:87]
	v_mfma_f32_16x16x32_bf16 v[80:83], v[140:143], v[192:195], v[80:83]
	v_mfma_f32_16x16x32_bf16 v[76:79], v[124:127], v[208:211], v[76:79]
	v_mfma_f32_16x16x32_bf16 v[72:75], v[140:143], v[208:211], v[72:75]
	v_mfma_f32_16x16x32_bf16 v[68:71], v[124:127], v[216:219], v[68:71]
	v_mfma_f32_16x16x32_bf16 v[64:67], v[140:143], v[216:219], v[64:67]
	v_mfma_f32_16x16x32_bf16 v[28:31], v[144:147], v[180:183], v[28:31]
	v_mfma_f32_16x16x32_bf16 v[24:27], v[152:155], v[180:183], v[24:27]
	v_mfma_f32_16x16x32_bf16 v[20:23], v[144:147], v[188:191], v[20:23]
	v_mfma_f32_16x16x32_bf16 v[16:19], v[152:155], v[188:191], v[16:19]
	v_mfma_f32_16x16x32_bf16 v[12:15], v[144:147], v[196:199], v[12:15]
	v_mfma_f32_16x16x32_bf16 v[8:11], v[152:155], v[196:199], v[8:11]
	v_mfma_f32_16x16x32_bf16 v[4:7], v[144:147], v[212:215], v[4:7]
	v_mfma_f32_16x16x32_bf16 v[0:3], v[152:155], v[212:215], v[0:3]
	v_mfma_f32_16x16x32_bf16 v[28:31], v[148:151], v[184:187], v[28:31]
	v_mfma_f32_16x16x32_bf16 v[24:27], v[156:159], v[184:187], v[24:27]
	v_mfma_f32_16x16x32_bf16 v[20:23], v[148:151], v[192:195], v[20:23]
	v_mfma_f32_16x16x32_bf16 v[16:19], v[156:159], v[192:195], v[16:19]
	v_mfma_f32_16x16x32_bf16 v[12:15], v[148:151], v[208:211], v[12:15]
	v_mfma_f32_16x16x32_bf16 v[8:11], v[156:159], v[208:211], v[8:11]
	v_mfma_f32_16x16x32_bf16 v[4:7], v[148:151], v[216:219], v[4:7]
	v_mfma_f32_16x16x32_bf16 v[0:3], v[156:159], v[216:219], v[0:3]
	s_barrier
	s_setprio 0
	s_add_i32 s54, s54, 2
	s_add_u32 s52, s52, 0x100
	s_addc_u32 s53, s53, 0
	s_cmp_gt_u32 s54, 7
	s_mov_b64 s[20:21], s[22:23]

.LBB0_470:
	s_add_u32 s12, s4, 0x10000000
	s_addc_u32 s13, s5, 0
	s_add_u32 s14, s4, 0x140000
	s_addc_u32 s15, s5, 0
	s_lshl_b32 s2, s2, 5
	s_mov_b64 s[16:17], 0x80
	s_and_b32 s2, s2, 0x60
	s_add_i32 m0, s52, 0x18000
	v_lshl_add_u64 v[2:3], v[2:3], 0, s[16:17]
	s_lshl_b32 s18, s1, 13
	s_lshl_b32 s19, s2, 7
	s_waitcnt vmcnt(2)
	s_barrier
	global_load_lds_dwordx4 v[2:3], off
	s_add_i32 m0, s52, 0x1a000
	s_add_u32 s6, s34, 0x800000
	v_lshl_add_u64 v[0:1], v[0:1], 0, s[16:17]
	s_addc_u32 s7, s35, 0
	s_add_i32 s56, s52, 0x8000
	global_load_lds_dwordx4 v[0:1], off
	v_lshl_add_u64 v[0:1], s[6:7], 0, v[156:157]
	s_mov_b32 m0, s56
	s_add_i32 s57, s52, 0xa000
	global_load_lds_dwordx4 v[0:1], off
	v_lshl_add_u64 v[0:1], s[6:7], 0, v[160:161]
	s_add_u32 s6, s36, 0x40080
	s_mov_b32 m0, s57
	s_addc_u32 s7, s37, 0
	global_load_lds_dwordx4 v[0:1], off
	s_add_i32 m0, s52, 0x1c000
	v_lshl_add_u64 v[0:1], s[6:7], 0, v[158:159]
	global_load_lds_dwordx4 v[0:1], off
	v_lshl_add_u64 v[0:1], s[6:7], 0, v[162:163]
	s_add_i32 m0, s52, 0x1e000
	v_bfe_u32 v13, v4, 4, 2
	global_load_lds_dwordx4 v[0:1], off
	v_and_b32_e32 v1, 15, v4
	v_lshlrev_b32_e32 v164, 4, v13
	v_lshlrev_b32_e32 v2, 2, v4
	s_ashr_i32 s58, s38, 31
	v_lshl_or_b32 v208, s1, 6, v1
	v_lshl_or_b32 v1, v1, 6, v164
	v_and_b32_e32 v2, 32, v2
	s_cmpk_lt_u32 s0, 0x100
	v_bitop3_b32 v4, v1, s18, v2 bitop3:0xde
	v_bitop3_b32 v209, v1, s19, v2 bitop3:0xde
	s_cselect_b64 s[18:19], -1, 0
	s_lshl_b32 s0, s2, 1
	s_add_u32 s0, s4, s0
	s_addc_u32 s1, s5, 0
	v_lshlrev_b32_e32 v1, 8, v5
	v_lshl_add_u64 v[2:3], s[0:1], 0, v[164:165]
	s_mov_b64 s[0:1], 0x8000000
	v_and_b32_e32 v1, 0xfffffe00, v1
	v_lshl_add_u64 v[166:167], v[2:3], 0, s[0:1]
	v_add_u32_e32 v1, v7, v1
	v_lshlrev_b32_e32 v2, 5, v6
	v_add3_u32 v164, v1, v2, v8
	v_lshlrev_b32_e32 v1, 8, v9
	v_and_b32_e32 v1, 0xfffffe00, v1
	s_waitcnt vmcnt(6)
	s_mov_b32 s99, 1
	s_mov_b64 s[0:1], 0x801000
	v_add_u32_e32 v1, v11, v1
	v_lshlrev_b32_e32 v2, 5, v10
	v_lshlrev_b32_e32 v0, 3, v13
	v_lshl_add_u64 v[170:171], v[164:165], 0, s[0:1]
	v_add3_u32 v164, v1, v2, v12
	s_add_i32 s60, 0, 0x10000
	s_add_i32 s61, 0, 0x14000
	s_mov_b32 s59, s38
	v_cmp_eq_u32_e64 s[4:5], 0, v13
	v_lshl_add_u64 v[172:173], v[164:165], 0, s[0:1]
	v_mov_b64_e32 v[174:175], 0x800
	v_mov_b64_e32 v[176:177], 0x7ff
	v_add_u32_e32 v210, s60, v209
	v_add_u32_e32 v211, s61, v209
	v_add_u32_e32 v212, 0, v4
	s_lshl_b32 s2, s2, 1
	v_lshlrev_b32_e32 v164, 1, v0
	v_mbcnt_hi_u32_b32 v213, -1, v169
	s_mov_b32 s62, s3
	s_barrier
	s_branch .LBB0_473

.Lrestag_480:
	ds_read_b128 v[100:103], v210
	ds_read_b128 v[116:119], v210 offset:1024
	ds_read_b128 v[136:139], v210 offset:2048
	ds_read_b128 v[140:143], v210 offset:3072
	ds_read_b128 v[144:147], v211
	ds_read_b128 v[148:151], v211 offset:1024
	ds_read_b128 v[152:155], v211 offset:2048
	ds_read_b128 v[178:181], v211 offset:3072
	s_add_u32 s36, s34, 0x1000000
	s_addc_u32 s37, s35, 0
	s_cmp_eq_u32 s65, 12
	s_cselect_b32 s44, s29, s36
	s_cselect_b32 s45, s23, s37
	s_cselect_b32 s42, s31, s63
	s_cselect_b32 s43, s21, s64
	s_add_u32 s40, s44, 0x800000
	s_addc_u32 s41, s45, 0
	s_add_i32 m0, s52, 0xc000
	ds_read_b128 v[182:185], v212
	ds_read_b128 v[186:189], v212 offset:1024
	ds_read_b128 v[190:193], v212 offset:2048
	ds_read_b128 v[194:197], v212 offset:3072
	ds_read_b128 v[198:201], v212 offset:4096
	ds_read_b128 v[202:205], v212 offset:5120
	ds_read_b128 v[214:217], v212 offset:6144
	ds_read_b128 v[218:221], v212 offset:7168
	global_load_lds_dwordx4 v170, s[34:35]
	s_add_i32 m0, s52, 0xe000
	s_nop 0
	global_load_lds_dwordx4 v172, s[34:35]
	s_nop 0
	s_waitcnt lgkmcnt(0)
	s_setprio 1
	s_barrier
	v_mfma_f32_16x16x32_bf16 v[132:135], v[100:103], v[182:185], 0
	v_mfma_f32_16x16x32_bf16 v[124:127], v[136:139], v[182:185], 0
	v_mfma_f32_16x16x32_bf16 v[112:115], v[100:103], v[190:193], 0
	v_mfma_f32_16x16x32_bf16 v[104:107], v[136:139], v[190:193], 0
	v_mfma_f32_16x16x32_bf16 v[92:95], v[100:103], v[198:201], 0
	v_mfma_f32_16x16x32_bf16 v[84:87], v[136:139], v[198:201], 0
	v_mfma_f32_16x16x32_bf16 v[76:79], v[100:103], v[214:217], 0
	v_mfma_f32_16x16x32_bf16 v[68:71], v[136:139], v[214:217], 0
	v_mfma_f32_16x16x32_bf16 v[132:135], v[116:119], v[186:189], v[132:135]
	v_mfma_f32_16x16x32_bf16 v[124:127], v[140:143], v[186:189], v[124:127]
	v_mfma_f32_16x16x32_bf16 v[112:115], v[116:119], v[194:197], v[112:115]
	v_mfma_f32_16x16x32_bf16 v[104:107], v[140:143], v[194:197], v[104:107]
	v_mfma_f32_16x16x32_bf16 v[92:95], v[116:119], v[202:205], v[92:95]
	v_mfma_f32_16x16x32_bf16 v[84:87], v[140:143], v[202:205], v[84:87]
	v_mfma_f32_16x16x32_bf16 v[76:79], v[116:119], v[218:221], v[76:79]
	v_mfma_f32_16x16x32_bf16 v[68:71], v[140:143], v[218:221], v[68:71]
	v_mfma_f32_16x16x32_bf16 v[128:131], v[144:147], v[182:185], 0
	v_mfma_f32_16x16x32_bf16 v[120:123], v[152:155], v[182:185], 0
	v_mfma_f32_16x16x32_bf16 v[108:111], v[144:147], v[190:193], 0
	v_mfma_f32_16x16x32_bf16 v[96:99], v[152:155], v[190:193], 0
	v_mfma_f32_16x16x32_bf16 v[88:91], v[144:147], v[198:201], 0
	v_mfma_f32_16x16x32_bf16 v[80:83], v[152:155], v[198:201], 0
	v_mfma_f32_16x16x32_bf16 v[72:75], v[144:147], v[214:217], 0
	v_mfma_f32_16x16x32_bf16 v[64:67], v[152:155], v[214:217], 0
	v_mfma_f32_16x16x32_bf16 v[128:131], v[148:151], v[186:189], v[128:131]
	v_mfma_f32_16x16x32_bf16 v[120:123], v[178:181], v[186:189], v[120:123]
	v_mfma_f32_16x16x32_bf16 v[108:111], v[148:151], v[194:197], v[108:111]
	v_mfma_f32_16x16x32_bf16 v[96:99], v[178:181], v[194:197], v[96:99]
	v_mfma_f32_16x16x32_bf16 v[88:91], v[148:151], v[202:205], v[88:91]
	v_mfma_f32_16x16x32_bf16 v[80:83], v[178:181], v[202:205], v[80:83]
	v_mfma_f32_16x16x32_bf16 v[72:75], v[148:151], v[218:221], v[72:75]
	v_mfma_f32_16x16x32_bf16 v[64:67], v[178:181], v[218:221], v[64:67]
	s_barrier
	s_setprio 0
	s_add_i32 s0, s60, s51
	v_lshl_add_u64 v[206:207], s[42:43], 0, v[158:159]
	s_mov_b32 m0, s0
	ds_read_b128 v[182:185], v212 offset:16384
	ds_read_b128 v[186:189], v212 offset:17408
	ds_read_b128 v[190:193], v212 offset:18432
	ds_read_b128 v[194:197], v212 offset:19456
	ds_read_b128 v[198:201], v212 offset:20480
	ds_read_b128 v[202:205], v212 offset:21504
	ds_read_b128 v[214:217], v212 offset:22528
	ds_read_b128 v[218:221], v212 offset:23552
	global_load_lds_dwordx4 v[206:207], off
	s_add_i32 m0, s0, 0x2000
	s_add_u32 s0, s42, 0x40000
	v_lshl_add_u64 v[222:223], s[42:43], 0, v[162:163]
	s_addc_u32 s1, s43, 0
	s_add_i32 s34, s61, s51
	global_load_lds_dwordx4 v[222:223], off
	s_mov_b32 m0, s34
	s_nop 0
	global_load_lds_dwordx4 v158, s[0:1]
	s_add_i32 m0, s34, 0x2000
	s_nop 0
	global_load_lds_dwordx4 v162, s[0:1]
	s_cmp_eq_u32 s99, 1
	s_cbranch_scc0 .Lft_480
	s_waitcnt vmcnt(6)
	s_mov_b32 s99, 0
.Lft_480:
	s_waitcnt lgkmcnt(0)
	s_setprio 1
	s_barrier
	v_mfma_f32_16x16x32_bf16 v[60:63], v[100:103], v[182:185], 0
	v_mfma_f32_16x16x32_bf16 v[52:55], v[136:139], v[182:185], 0
	v_mfma_f32_16x16x32_bf16 v[44:47], v[100:103], v[190:193], 0
	v_mfma_f32_16x16x32_bf16 v[36:39], v[136:139], v[190:193], 0
	v_mfma_f32_16x16x32_bf16 v[28:31], v[100:103], v[198:201], 0
	v_mfma_f32_16x16x32_bf16 v[20:23], v[136:139], v[198:201], 0
	v_mfma_f32_16x16x32_bf16 v[12:15], v[100:103], v[214:217], 0
	v_mfma_f32_16x16x32_bf16 v[4:7], v[136:139], v[214:217], 0
	v_mfma_f32_16x16x32_bf16 v[60:63], v[116:119], v[186:189], v[60:63]
	v_mfma_f32_16x16x32_bf16 v[52:55], v[140:143], v[186:189], v[52:55]
	v_mfma_f32_16x16x32_bf16 v[44:47], v[116:119], v[194:197], v[44:47]
	v_mfma_f32_16x16x32_bf16 v[36:39], v[140:143], v[194:197], v[36:39]
	v_mfma_f32_16x16x32_bf16 v[28:31], v[116:119], v[202:205], v[28:31]
	v_mfma_f32_16x16x32_bf16 v[20:23], v[140:143], v[202:205], v[20:23]
	v_mfma_f32_16x16x32_bf16 v[12:15], v[116:119], v[218:221], v[12:15]
	v_mfma_f32_16x16x32_bf16 v[4:7], v[140:143], v[218:221], v[4:7]
	v_mfma_f32_16x16x32_bf16 v[56:59], v[144:147], v[182:185], 0
	v_mfma_f32_16x16x32_bf16 v[48:51], v[152:155], v[182:185], 0
	v_mfma_f32_16x16x32_bf16 v[40:43], v[144:147], v[190:193], 0
	v_mfma_f32_16x16x32_bf16 v[32:35], v[152:155], v[190:193], 0
	v_mfma_f32_16x16x32_bf16 v[24:27], v[144:147], v[198:201], 0
	v_mfma_f32_16x16x32_bf16 v[16:19], v[152:155], v[198:201], 0
	v_mfma_f32_16x16x32_bf16 v[8:11], v[144:147], v[214:217], 0
	v_mfma_f32_16x16x32_bf16 v[0:3], v[152:155], v[214:217], 0
	v_mfma_f32_16x16x32_bf16 v[56:59], v[148:151], v[186:189], v[56:59]
	v_mfma_f32_16x16x32_bf16 v[48:51], v[178:181], v[186:189], v[48:51]
	v_mfma_f32_16x16x32_bf16 v[40:43], v[148:151], v[194:197], v[40:43]
	v_mfma_f32_16x16x32_bf16 v[32:35], v[178:181], v[194:197], v[32:35]
	v_mfma_f32_16x16x32_bf16 v[24:27], v[148:151], v[202:205], v[24:27]
	v_mfma_f32_16x16x32_bf16 v[16:19], v[178:181], v[202:205], v[16:19]
	v_mfma_f32_16x16x32_bf16 v[8:11], v[148:151], v[218:221], v[8:11]
	v_mfma_f32_16x16x32_bf16 v[0:3], v[178:181], v[218:221], v[0:3]
	s_barrier
	s_setprio 0
	s_add_i32 s34, 0, 0x18000
	s_add_i32 s35, 0, 0x1c000
	v_add_u32_e32 v140, s34, v209
	v_add_u32_e32 v178, s35, v209
	ds_read_b128 v[100:103], v140
	ds_read_b128 v[116:119], v140 offset:1024
	ds_read_b128 v[136:139], v140 offset:2048
	ds_read_b128 v[140:143], v140 offset:3072
	ds_read_b128 v[144:147], v178
	ds_read_b128 v[148:151], v178 offset:1024
	ds_read_b128 v[152:155], v178 offset:2048
	ds_read_b128 v[178:181], v178 offset:3072
	s_add_u32 s0, s44, 0x1000
	s_addc_u32 s1, s45, 0
	s_mov_b32 m0, s54
	ds_read_b128 v[182:185], v212 offset:32768
	ds_read_b128 v[186:189], v212 offset:33792
	ds_read_b128 v[190:193], v212 offset:34816
	ds_read_b128 v[194:197], v212 offset:35840
	ds_read_b128 v[198:201], v212 offset:36864
	ds_read_b128 v[202:205], v212 offset:37888
	ds_read_b128 v[214:217], v212 offset:38912
	ds_read_b128 v[218:221], v212 offset:39936
	global_load_lds_dwordx4 v156, s[0:1]
	s_mov_b32 m0, s55
	s_nop 0
	global_load_lds_dwordx4 v160, s[0:1]
	s_mov_b32 m0, s52
	s_nop 0
	global_load_lds_dwordx4 v156, s[44:45]
	s_mov_b32 m0, s53
	s_nop 0
	global_load_lds_dwordx4 v160, s[44:45]
	s_waitcnt vmcnt(8)
	s_waitcnt lgkmcnt(0)
	s_setprio 1
	s_barrier
	v_mfma_f32_16x16x32_bf16 v[132:135], v[100:103], v[182:185], v[132:135]
	v_mfma_f32_16x16x32_bf16 v[124:127], v[136:139], v[182:185], v[124:127]
	v_mfma_f32_16x16x32_bf16 v[112:115], v[100:103], v[190:193], v[112:115]
	v_mfma_f32_16x16x32_bf16 v[104:107], v[136:139], v[190:193], v[104:107]
	v_mfma_f32_16x16x32_bf16 v[92:95], v[100:103], v[198:201], v[92:95]
	v_mfma_f32_16x16x32_bf16 v[84:87], v[136:139], v[198:201], v[84:87]
	v_mfma_f32_16x16x32_bf16 v[76:79], v[100:103], v[214:217], v[76:79]
	v_mfma_f32_16x16x32_bf16 v[68:71], v[136:139], v[214:217], v[68:71]
	v_mfma_f32_16x16x32_bf16 v[132:135], v[116:119], v[186:189], v[132:135]
	v_mfma_f32_16x16x32_bf16 v[124:127], v[140:143], v[186:189], v[124:127]
	v_mfma_f32_16x16x32_bf16 v[112:115], v[116:119], v[194:197], v[112:115]
	v_mfma_f32_16x16x32_bf16 v[104:107], v[140:143], v[194:197], v[104:107]
	v_mfma_f32_16x16x32_bf16 v[92:95], v[116:119], v[202:205], v[92:95]
	v_mfma_f32_16x16x32_bf16 v[84:87], v[140:143], v[202:205], v[84:87]
	v_mfma_f32_16x16x32_bf16 v[76:79], v[116:119], v[218:221], v[76:79]
	v_mfma_f32_16x16x32_bf16 v[68:71], v[140:143], v[218:221], v[68:71]
	v_mfma_f32_16x16x32_bf16 v[128:131], v[144:147], v[182:185], v[128:131]
	v_mfma_f32_16x16x32_bf16 v[120:123], v[152:155], v[182:185], v[120:123]
	v_mfma_f32_16x16x32_bf16 v[108:111], v[144:147], v[190:193], v[108:111]
	v_mfma_f32_16x16x32_bf16 v[96:99], v[152:155], v[190:193], v[96:99]
	v_mfma_f32_16x16x32_bf16 v[88:91], v[144:147], v[198:201], v[88:91]
	v_mfma_f32_16x16x32_bf16 v[80:83], v[152:155], v[198:201], v[80:83]
	v_mfma_f32_16x16x32_bf16 v[72:75], v[144:147], v[214:217], v[72:75]
	v_mfma_f32_16x16x32_bf16 v[64:67], v[152:155], v[214:217], v[64:67]
	v_mfma_f32_16x16x32_bf16 v[128:131], v[148:151], v[186:189], v[128:131]
	v_mfma_f32_16x16x32_bf16 v[120:123], v[178:181], v[186:189], v[120:123]
	v_mfma_f32_16x16x32_bf16 v[108:111], v[148:151], v[194:197], v[108:111]
	v_mfma_f32_16x16x32_bf16 v[96:99], v[178:181], v[194:197], v[96:99]
	v_mfma_f32_16x16x32_bf16 v[88:91], v[148:151], v[202:205], v[88:91]
	v_mfma_f32_16x16x32_bf16 v[80:83], v[178:181], v[202:205], v[80:83]
	v_mfma_f32_16x16x32_bf16 v[72:75], v[148:151], v[218:221], v[72:75]
	v_mfma_f32_16x16x32_bf16 v[64:67], v[178:181], v[218:221], v[64:67]
	s_barrier
	s_setprio 0
	s_add_i32 s0, s34, s51
	v_lshl_add_u64 v[206:207], v[206:207], 0, s[16:17]
	s_mov_b32 m0, s0
	ds_read_b128 v[182:185], v212 offset:49152
	ds_read_b128 v[186:189], v212 offset:50176
	ds_read_b128 v[190:193], v212 offset:51200
	ds_read_b128 v[194:197], v212 offset:52224
	ds_read_b128 v[198:201], v212 offset:53248
	ds_read_b128 v[202:205], v212 offset:54272
	ds_read_b128 v[214:217], v212 offset:55296
	ds_read_b128 v[218:221], v212 offset:56320
	global_load_lds_dwordx4 v[206:207], off
	s_add_i32 m0, s0, 0x2000
	s_add_u32 s0, s42, 0x40080
	v_lshl_add_u64 v[206:207], v[222:223], 0, s[16:17]
	s_addc_u32 s1, s43, 0
	s_add_i32 s34, s35, s51
	global_load_lds_dwordx4 v[206:207], off
	s_mov_b32 m0, s34
	s_nop 0
	global_load_lds_dwordx4 v158, s[0:1]
	s_add_i32 m0, s34, 0x2000
	s_nop 0
	global_load_lds_dwordx4 v162, s[0:1]
	s_mov_b32 m0, s56
	s_nop 0
	global_load_lds_dwordx4 v156, s[40:41]
	s_mov_b32 m0, s57
	s_nop 0
	global_load_lds_dwordx4 v160, s[40:41]
	s_waitcnt vmcnt(6)
	s_waitcnt lgkmcnt(0)
	s_setprio 1
	s_barrier
	v_mfma_f32_16x16x32_bf16 v[60:63], v[100:103], v[182:185], v[60:63]
	v_mfma_f32_16x16x32_bf16 v[52:55], v[136:139], v[182:185], v[52:55]
	v_mfma_f32_16x16x32_bf16 v[44:47], v[100:103], v[190:193], v[44:47]
	v_mfma_f32_16x16x32_bf16 v[36:39], v[136:139], v[190:193], v[36:39]
	v_mfma_f32_16x16x32_bf16 v[28:31], v[100:103], v[198:201], v[28:31]
	v_mfma_f32_16x16x32_bf16 v[20:23], v[136:139], v[198:201], v[20:23]
	v_mfma_f32_16x16x32_bf16 v[12:15], v[100:103], v[214:217], v[12:15]
	v_mfma_f32_16x16x32_bf16 v[4:7], v[136:139], v[214:217], v[4:7]
	v_mfma_f32_16x16x32_bf16 v[60:63], v[116:119], v[186:189], v[60:63]
	v_mfma_f32_16x16x32_bf16 v[52:55], v[140:143], v[186:189], v[52:55]
	v_mfma_f32_16x16x32_bf16 v[44:47], v[116:119], v[194:197], v[44:47]
	v_mfma_f32_16x16x32_bf16 v[36:39], v[140:143], v[194:197], v[36:39]
	v_mfma_f32_16x16x32_bf16 v[28:31], v[116:119], v[202:205], v[28:31]
	v_mfma_f32_16x16x32_bf16 v[20:23], v[140:143], v[202:205], v[20:23]
	v_mfma_f32_16x16x32_bf16 v[12:15], v[116:119], v[218:221], v[12:15]
	v_mfma_f32_16x16x32_bf16 v[4:7], v[140:143], v[218:221], v[4:7]
	v_mfma_f32_16x16x32_bf16 v[56:59], v[144:147], v[182:185], v[56:59]
	v_mfma_f32_16x16x32_bf16 v[48:51], v[152:155], v[182:185], v[48:51]
	v_mfma_f32_16x16x32_bf16 v[40:43], v[144:147], v[190:193], v[40:43]
	v_mfma_f32_16x16x32_bf16 v[32:35], v[152:155], v[190:193], v[32:35]
	v_mfma_f32_16x16x32_bf16 v[24:27], v[144:147], v[198:201], v[24:27]
	v_mfma_f32_16x16x32_bf16 v[16:19], v[152:155], v[198:201], v[16:19]
	v_mfma_f32_16x16x32_bf16 v[8:11], v[144:147], v[214:217], v[8:11]
	v_mfma_f32_16x16x32_bf16 v[0:3], v[152:155], v[214:217], v[0:3]
	v_mfma_f32_16x16x32_bf16 v[56:59], v[148:151], v[186:189], v[56:59]
	v_mfma_f32_16x16x32_bf16 v[48:51], v[178:181], v[186:189], v[48:51]
	v_mfma_f32_16x16x32_bf16 v[40:43], v[148:151], v[194:197], v[40:43]
	v_mfma_f32_16x16x32_bf16 v[32:35], v[178:181], v[194:197], v[32:35]
	v_mfma_f32_16x16x32_bf16 v[24:27], v[148:151], v[202:205], v[24:27]
	v_mfma_f32_16x16x32_bf16 v[16:19], v[178:181], v[202:205], v[16:19]
	v_mfma_f32_16x16x32_bf16 v[8:11], v[148:151], v[218:221], v[8:11]
	v_mfma_f32_16x16x32_bf16 v[0:3], v[178:181], v[218:221], v[0:3]
	s_barrier
	s_setprio 0
	s_add_i32 s65, s65, 2
	s_add_u32 s63, s63, 0x100
	s_addc_u32 s64, s64, 0
	s_cmp_gt_u32 s65, 13
	s_mov_b64 s[34:35], s[36:37]

.LBB0_567:
	s_add_u32 s34, s6, 0x180000
	s_addc_u32 s35, s7, 0
	s_and_b32 s63, s1, 3
	s_add_i32 m0, s49, 0x18000
	v_lshl_add_u64 v[6:7], v[6:7], 0, s[16:17]
	s_lshl_b32 s1, s12, 13
	s_lshl_b32 s13, s63, 12
	s_waitcnt vmcnt(2)
	s_barrier
	global_load_lds_dwordx4 v[6:7], off
	v_lshl_add_u64 v[4:5], v[4:5], 0, s[16:17]
	s_add_i32 m0, s49, 0x1a000
	s_add_i32 s64, s49, 0x8000
	s_add_i32 s65, s49, 0xa000
	global_load_lds_dwordx4 v[4:5], off
	v_lshl_add_u64 v[0:1], v[0:1], 0, s[16:17]
	s_mov_b32 m0, s64
	s_add_u32 s4, s52, 0x40080
	global_load_lds_dwordx4 v[0:1], off
	v_lshl_add_u64 v[0:1], v[2:3], 0, s[16:17]
	s_mov_b32 m0, s65
	s_addc_u32 s5, s53, 0
	global_load_lds_dwordx4 v[0:1], off
	s_add_i32 m0, s49, 0x1c000
	v_lshl_add_u64 v[0:1], s[4:5], 0, v[130:131]
	global_load_lds_dwordx4 v[0:1], off
	v_lshl_add_u64 v[0:1], s[4:5], 0, v[134:135]
	s_add_i32 m0, s49, 0x1e000
	s_cmpk_lt_u32 s0, 0x100
	global_load_lds_dwordx4 v[0:1], off
	v_lshrrev_b32_e32 v1, 1, v8
	v_and_b32_e32 v136, 24, v1
	v_and_b32_e32 v0, 15, v8
	v_lshlrev_b32_e32 v1, 1, v136
	v_lshl_or_b32 v137, s12, 6, v0
	v_lshl_or_b32 v0, v0, 6, v1
	v_lshlrev_b32_e32 v1, 2, v8
	v_and_b32_e32 v1, 32, v1
	v_bitop3_b32 v2, v0, s1, v1 bitop3:0xde
	v_bitop3_b32 v188, v0, s13, v1 bitop3:0xde
	v_lshlrev_b32_e32 v0, 14, v9
	v_and_b32_e32 v0, 0xffff8000, v0
	v_lshl_add_u32 v0, v10, 11, v0
	v_add3_u32 v170, v0, v11, v12
	v_lshlrev_b32_e32 v0, 14, v13
	v_and_b32_e32 v0, 0xffff8000, v0
	s_waitcnt vmcnt(6)
	s_mov_b32 s99, 1
	v_lshl_add_u32 v0, v14, 11, v0
	v_lshl_add_u64 v[138:139], v[170:171], 0, s[18:19]
	v_add3_u32 v170, v0, v15, v16
	s_sext_i32_i8 s66, s2
	s_cselect_b64 s[36:37], -1, 0
	v_lshl_add_u64 v[140:141], v[170:171], 0, s[18:19]
	s_mov_b32 s2, 0
	v_add_u32_e32 v189, 0, v2
	s_barrier
	s_branch .LBB0_570

.Lrestag_577:
	s_add_u32 s52, s50, 0x100
	s_addc_u32 s53, s51, 0
	s_add_i32 s0, 0, 0x10000
	s_cmp_eq_u32 s76, 12
	s_cselect_b32 s57, s43, s53
	s_cselect_b32 s56, s67, s52
	s_cselect_b32 s55, s41, s75
	s_cselect_b32 s54, s68, s69
	s_add_i32 s12, 0, 0x14000
	v_add_u32_e32 v154, s0, v188
	v_add_u32_e32 v166, s12, v188
	ds_read_b128 v[142:145], v154
	ds_read_b128 v[146:149], v154 offset:1024
	ds_read_b128 v[150:153], v154 offset:2048
	ds_read_b128 v[154:157], v154 offset:3072
	ds_read_b128 v[158:161], v166
	ds_read_b128 v[162:165], v166 offset:1024
	ds_read_b128 v[184:187], v166 offset:2048
	ds_read_b128 v[190:193], v166 offset:3072
	s_add_i32 m0, s49, 0xc000
	ds_read_b128 v[194:197], v189
	ds_read_b128 v[198:201], v189 offset:1024
	ds_read_b128 v[202:205], v189 offset:2048
	ds_read_b128 v[206:209], v189 offset:3072
	ds_read_b128 v[210:213], v189 offset:4096
	ds_read_b128 v[214:217], v189 offset:5120
	ds_read_b128 v[228:231], v189 offset:6144
	ds_read_b128 v[232:235], v189 offset:7168
	global_load_lds_dwordx4 v138, s[50:51]
	s_add_i32 m0, s49, 0xe000
	s_nop 0
	global_load_lds_dwordx4 v140, s[50:51]
	s_nop 0
	s_waitcnt lgkmcnt(0)
	s_setprio 1
	s_barrier
	v_mfma_f32_16x16x32_bf16 v[124:127], v[142:145], v[194:197], 0
	v_mfma_f32_16x16x32_bf16 v[120:123], v[150:153], v[194:197], 0
	v_mfma_f32_16x16x32_bf16 v[108:111], v[142:145], v[202:205], 0
	v_mfma_f32_16x16x32_bf16 v[104:107], v[150:153], v[202:205], 0
	v_mfma_f32_16x16x32_bf16 v[92:95], v[142:145], v[210:213], 0
	v_mfma_f32_16x16x32_bf16 v[88:91], v[150:153], v[210:213], 0
	v_mfma_f32_16x16x32_bf16 v[76:79], v[142:145], v[228:231], 0
	v_mfma_f32_16x16x32_bf16 v[72:75], v[150:153], v[228:231], 0
	v_mfma_f32_16x16x32_bf16 v[124:127], v[146:149], v[198:201], v[124:127]
	v_mfma_f32_16x16x32_bf16 v[120:123], v[154:157], v[198:201], v[120:123]
	v_mfma_f32_16x16x32_bf16 v[108:111], v[146:149], v[206:209], v[108:111]
	v_mfma_f32_16x16x32_bf16 v[104:107], v[154:157], v[206:209], v[104:107]
	v_mfma_f32_16x16x32_bf16 v[92:95], v[146:149], v[214:217], v[92:95]
	v_mfma_f32_16x16x32_bf16 v[88:91], v[154:157], v[214:217], v[88:91]
	v_mfma_f32_16x16x32_bf16 v[76:79], v[146:149], v[232:235], v[76:79]
	v_mfma_f32_16x16x32_bf16 v[72:75], v[154:157], v[232:235], v[72:75]
	v_mfma_f32_16x16x32_bf16 v[116:119], v[158:161], v[194:197], 0
	v_mfma_f32_16x16x32_bf16 v[112:115], v[184:187], v[194:197], 0
	v_mfma_f32_16x16x32_bf16 v[100:103], v[158:161], v[202:205], 0
	v_mfma_f32_16x16x32_bf16 v[96:99], v[184:187], v[202:205], 0
	v_mfma_f32_16x16x32_bf16 v[84:87], v[158:161], v[210:213], 0
	v_mfma_f32_16x16x32_bf16 v[80:83], v[184:187], v[210:213], 0
	v_mfma_f32_16x16x32_bf16 v[68:71], v[158:161], v[228:231], 0
	v_mfma_f32_16x16x32_bf16 v[64:67], v[184:187], v[228:231], 0
	v_mfma_f32_16x16x32_bf16 v[116:119], v[162:165], v[198:201], v[116:119]
	v_mfma_f32_16x16x32_bf16 v[112:115], v[190:193], v[198:201], v[112:115]
	v_mfma_f32_16x16x32_bf16 v[100:103], v[162:165], v[206:209], v[100:103]
	v_mfma_f32_16x16x32_bf16 v[96:99], v[190:193], v[206:209], v[96:99]
	v_mfma_f32_16x16x32_bf16 v[84:87], v[162:165], v[214:217], v[84:87]
	v_mfma_f32_16x16x32_bf16 v[80:83], v[190:193], v[214:217], v[80:83]
	v_mfma_f32_16x16x32_bf16 v[68:71], v[162:165], v[232:235], v[68:71]
	v_mfma_f32_16x16x32_bf16 v[64:67], v[190:193], v[232:235], v[64:67]
	s_barrier
	s_setprio 0
	s_add_i32 s0, s0, s59
	v_lshl_add_u64 v[166:167], s[54:55], 0, v[130:131]
	s_mov_b32 m0, s0
	ds_read_b128 v[194:197], v189 offset:16384
	ds_read_b128 v[198:201], v189 offset:17408
	ds_read_b128 v[202:205], v189 offset:18432
	ds_read_b128 v[206:209], v189 offset:19456
	ds_read_b128 v[210:213], v189 offset:20480
	ds_read_b128 v[214:217], v189 offset:21504
	ds_read_b128 v[228:231], v189 offset:22528
	ds_read_b128 v[232:235], v189 offset:23552
	global_load_lds_dwordx4 v[166:167], off
	s_add_i32 m0, s0, 0x2000
	s_add_u32 s0, s54, 0x40000
	v_lshl_add_u64 v[218:219], s[54:55], 0, v[134:135]
	s_addc_u32 s1, s55, 0
	s_add_i32 s12, s12, s59
	global_load_lds_dwordx4 v[218:219], off
	s_mov_b32 m0, s12
	v_lshl_add_u64 v[238:239], s[56:57], 0, v[132:133]
	global_load_lds_dwordx4 v130, s[0:1]
	s_add_i32 m0, s12, 0x2000
	s_nop 0
	global_load_lds_dwordx4 v134, s[0:1]
	v_lshl_add_u64 v[236:237], s[56:57], 0, v[128:129]
	s_cmp_eq_u32 s99, 1
	s_cbranch_scc0 .Lft_577
	s_waitcnt vmcnt(6)
	s_mov_b32 s99, 0
.Lft_577:
	s_waitcnt lgkmcnt(0)
	s_setprio 1
	s_barrier
	v_mfma_f32_16x16x32_bf16 v[60:63], v[142:145], v[194:197], 0
	v_mfma_f32_16x16x32_bf16 v[56:59], v[150:153], v[194:197], 0
	v_mfma_f32_16x16x32_bf16 v[44:47], v[142:145], v[202:205], 0
	v_mfma_f32_16x16x32_bf16 v[40:43], v[150:153], v[202:205], 0
	v_mfma_f32_16x16x32_bf16 v[28:31], v[142:145], v[210:213], 0
	v_mfma_f32_16x16x32_bf16 v[24:27], v[150:153], v[210:213], 0
	v_mfma_f32_16x16x32_bf16 v[12:15], v[142:145], v[228:231], 0
	v_mfma_f32_16x16x32_bf16 v[8:11], v[150:153], v[228:231], 0
	v_mfma_f32_16x16x32_bf16 v[60:63], v[146:149], v[198:201], v[60:63]
	v_mfma_f32_16x16x32_bf16 v[56:59], v[154:157], v[198:201], v[56:59]
	v_mfma_f32_16x16x32_bf16 v[44:47], v[146:149], v[206:209], v[44:47]
	v_mfma_f32_16x16x32_bf16 v[40:43], v[154:157], v[206:209], v[40:43]
	v_mfma_f32_16x16x32_bf16 v[28:31], v[146:149], v[214:217], v[28:31]
	v_mfma_f32_16x16x32_bf16 v[24:27], v[154:157], v[214:217], v[24:27]
	v_mfma_f32_16x16x32_bf16 v[12:15], v[146:149], v[232:235], v[12:15]
	v_mfma_f32_16x16x32_bf16 v[8:11], v[154:157], v[232:235], v[8:11]
	v_mfma_f32_16x16x32_bf16 v[52:55], v[158:161], v[194:197], 0
	v_mfma_f32_16x16x32_bf16 v[48:51], v[184:187], v[194:197], 0
	v_mfma_f32_16x16x32_bf16 v[36:39], v[158:161], v[202:205], 0
	v_mfma_f32_16x16x32_bf16 v[32:35], v[184:187], v[202:205], 0
	v_mfma_f32_16x16x32_bf16 v[20:23], v[158:161], v[210:213], 0
	v_mfma_f32_16x16x32_bf16 v[16:19], v[184:187], v[210:213], 0
	v_mfma_f32_16x16x32_bf16 v[4:7], v[158:161], v[228:231], 0
	v_mfma_f32_16x16x32_bf16 v[0:3], v[184:187], v[228:231], 0
	v_mfma_f32_16x16x32_bf16 v[52:55], v[162:165], v[198:201], v[52:55]
	v_mfma_f32_16x16x32_bf16 v[48:51], v[190:193], v[198:201], v[48:51]
	v_mfma_f32_16x16x32_bf16 v[36:39], v[162:165], v[206:209], v[36:39]
	v_mfma_f32_16x16x32_bf16 v[32:35], v[190:193], v[206:209], v[32:35]
	v_mfma_f32_16x16x32_bf16 v[20:23], v[162:165], v[214:217], v[20:23]
	v_mfma_f32_16x16x32_bf16 v[16:19], v[190:193], v[214:217], v[16:19]
	v_mfma_f32_16x16x32_bf16 v[4:7], v[162:165], v[232:235], v[4:7]
	v_mfma_f32_16x16x32_bf16 v[0:3], v[190:193], v[232:235], v[0:3]
	s_barrier
	s_setprio 0
	s_add_i32 s12, 0, 0x18000
	s_add_i32 s13, 0, 0x1c000
	v_add_u32_e32 v154, s12, v188
	v_add_u32_e32 v170, s13, v188
	ds_read_b128 v[142:145], v154
	ds_read_b128 v[146:149], v154 offset:1024
	ds_read_b128 v[150:153], v154 offset:2048
	ds_read_b128 v[154:157], v154 offset:3072
	ds_read_b128 v[158:161], v170
	ds_read_b128 v[162:165], v170 offset:1024
	ds_read_b128 v[184:187], v170 offset:2048
	ds_read_b128 v[190:193], v170 offset:3072
	s_add_u32 s0, s56, 0x40000
	s_addc_u32 s1, s57, 0
	s_mov_b32 m0, s61
	ds_read_b128 v[194:197], v189 offset:32768
	ds_read_b128 v[198:201], v189 offset:33792
	ds_read_b128 v[202:205], v189 offset:34816
	ds_read_b128 v[206:209], v189 offset:35840
	ds_read_b128 v[210:213], v189 offset:36864
	ds_read_b128 v[214:217], v189 offset:37888
	ds_read_b128 v[228:231], v189 offset:38912
	ds_read_b128 v[232:235], v189 offset:39936
	global_load_lds_dwordx4 v128, s[0:1]
	s_mov_b32 m0, s62
	s_nop 0
	global_load_lds_dwordx4 v132, s[0:1]
	s_mov_b32 m0, s49
	s_nop 0
	global_load_lds_dwordx4 v[236:237], off
	s_mov_b32 m0, s60
	s_nop 0
	global_load_lds_dwordx4 v[238:239], off
	s_waitcnt vmcnt(8)
	s_waitcnt lgkmcnt(0)
	s_setprio 1
	s_barrier
	v_mfma_f32_16x16x32_bf16 v[124:127], v[142:145], v[194:197], v[124:127]
	v_mfma_f32_16x16x32_bf16 v[120:123], v[150:153], v[194:197], v[120:123]
	v_mfma_f32_16x16x32_bf16 v[108:111], v[142:145], v[202:205], v[108:111]
	v_mfma_f32_16x16x32_bf16 v[104:107], v[150:153], v[202:205], v[104:107]
	v_mfma_f32_16x16x32_bf16 v[92:95], v[142:145], v[210:213], v[92:95]
	v_mfma_f32_16x16x32_bf16 v[88:91], v[150:153], v[210:213], v[88:91]
	v_mfma_f32_16x16x32_bf16 v[76:79], v[142:145], v[228:231], v[76:79]
	v_mfma_f32_16x16x32_bf16 v[72:75], v[150:153], v[228:231], v[72:75]
	v_mfma_f32_16x16x32_bf16 v[124:127], v[146:149], v[198:201], v[124:127]
	v_mfma_f32_16x16x32_bf16 v[120:123], v[154:157], v[198:201], v[120:123]
	v_mfma_f32_16x16x32_bf16 v[108:111], v[146:149], v[206:209], v[108:111]
	v_mfma_f32_16x16x32_bf16 v[104:107], v[154:157], v[206:209], v[104:107]
	v_mfma_f32_16x16x32_bf16 v[92:95], v[146:149], v[214:217], v[92:95]
	v_mfma_f32_16x16x32_bf16 v[88:91], v[154:157], v[214:217], v[88:91]
	v_mfma_f32_16x16x32_bf16 v[76:79], v[146:149], v[232:235], v[76:79]
	v_mfma_f32_16x16x32_bf16 v[72:75], v[154:157], v[232:235], v[72:75]
	v_mfma_f32_16x16x32_bf16 v[116:119], v[158:161], v[194:197], v[116:119]
	v_mfma_f32_16x16x32_bf16 v[112:115], v[184:187], v[194:197], v[112:115]
	v_mfma_f32_16x16x32_bf16 v[100:103], v[158:161], v[202:205], v[100:103]
	v_mfma_f32_16x16x32_bf16 v[96:99], v[184:187], v[202:205], v[96:99]
	v_mfma_f32_16x16x32_bf16 v[84:87], v[158:161], v[210:213], v[84:87]
	v_mfma_f32_16x16x32_bf16 v[80:83], v[184:187], v[210:213], v[80:83]
	v_mfma_f32_16x16x32_bf16 v[68:71], v[158:161], v[228:231], v[68:71]
	v_mfma_f32_16x16x32_bf16 v[64:67], v[184:187], v[228:231], v[64:67]
	v_mfma_f32_16x16x32_bf16 v[116:119], v[162:165], v[198:201], v[116:119]
	v_mfma_f32_16x16x32_bf16 v[112:115], v[190:193], v[198:201], v[112:115]
	v_mfma_f32_16x16x32_bf16 v[100:103], v[162:165], v[206:209], v[100:103]
	v_mfma_f32_16x16x32_bf16 v[96:99], v[190:193], v[206:209], v[96:99]
	v_mfma_f32_16x16x32_bf16 v[84:87], v[162:165], v[214:217], v[84:87]
	v_mfma_f32_16x16x32_bf16 v[80:83], v[190:193], v[214:217], v[80:83]
	v_mfma_f32_16x16x32_bf16 v[68:71], v[162:165], v[232:235], v[68:71]
	v_mfma_f32_16x16x32_bf16 v[64:67], v[190:193], v[232:235], v[64:67]
	s_barrier
	s_setprio 0
	s_add_i32 s0, s12, s59
	v_lshl_add_u64 v[166:167], v[166:167], 0, s[16:17]
	s_mov_b32 m0, s0
	ds_read_b128 v[194:197], v189 offset:49152
	ds_read_b128 v[198:201], v189 offset:50176
	ds_read_b128 v[202:205], v189 offset:51200
	ds_read_b128 v[206:209], v189 offset:52224
	ds_read_b128 v[210:213], v189 offset:53248
	ds_read_b128 v[214:217], v189 offset:54272
	ds_read_b128 v[228:231], v189 offset:55296
	ds_read_b128 v[232:235], v189 offset:56320
	global_load_lds_dwordx4 v[166:167], off
	s_add_i32 m0, s0, 0x2000
	s_add_u32 s0, s54, 0x40080
	v_lshl_add_u64 v[166:167], v[218:219], 0, s[16:17]
	s_addc_u32 s1, s55, 0
	s_add_i32 s12, s13, s59
	global_load_lds_dwordx4 v[166:167], off
	s_mov_b32 m0, s12
	s_nop 0
	global_load_lds_dwordx4 v130, s[0:1]
	s_add_i32 m0, s12, 0x2000
	s_nop 0
	global_load_lds_dwordx4 v134, s[0:1]
	v_lshl_add_u64 v[166:167], v[236:237], 0, s[16:17]
	s_mov_b32 m0, s64
	s_nop 0
	global_load_lds_dwordx4 v[166:167], off
	v_lshl_add_u64 v[166:167], v[238:239], 0, s[16:17]
	s_mov_b32 m0, s65
	s_nop 0
	global_load_lds_dwordx4 v[166:167], off
	s_waitcnt vmcnt(6)
	s_waitcnt lgkmcnt(0)
	s_setprio 1
	s_barrier
	v_mfma_f32_16x16x32_bf16 v[60:63], v[142:145], v[194:197], v[60:63]
	v_mfma_f32_16x16x32_bf16 v[56:59], v[150:153], v[194:197], v[56:59]
	v_mfma_f32_16x16x32_bf16 v[44:47], v[142:145], v[202:205], v[44:47]
	v_mfma_f32_16x16x32_bf16 v[40:43], v[150:153], v[202:205], v[40:43]
	v_mfma_f32_16x16x32_bf16 v[28:31], v[142:145], v[210:213], v[28:31]
	v_mfma_f32_16x16x32_bf16 v[24:27], v[150:153], v[210:213], v[24:27]
	v_mfma_f32_16x16x32_bf16 v[12:15], v[142:145], v[228:231], v[12:15]
	v_mfma_f32_16x16x32_bf16 v[8:11], v[150:153], v[228:231], v[8:11]
	v_mfma_f32_16x16x32_bf16 v[60:63], v[146:149], v[198:201], v[60:63]
	v_mfma_f32_16x16x32_bf16 v[56:59], v[154:157], v[198:201], v[56:59]
	v_mfma_f32_16x16x32_bf16 v[44:47], v[146:149], v[206:209], v[44:47]
	v_mfma_f32_16x16x32_bf16 v[40:43], v[154:157], v[206:209], v[40:43]
	v_mfma_f32_16x16x32_bf16 v[28:31], v[146:149], v[214:217], v[28:31]
	v_mfma_f32_16x16x32_bf16 v[24:27], v[154:157], v[214:217], v[24:27]
	v_mfma_f32_16x16x32_bf16 v[12:15], v[146:149], v[232:235], v[12:15]
	v_mfma_f32_16x16x32_bf16 v[8:11], v[154:157], v[232:235], v[8:11]
	v_mfma_f32_16x16x32_bf16 v[52:55], v[158:161], v[194:197], v[52:55]
	v_mfma_f32_16x16x32_bf16 v[48:51], v[184:187], v[194:197], v[48:51]
	v_mfma_f32_16x16x32_bf16 v[36:39], v[158:161], v[202:205], v[36:39]
	v_mfma_f32_16x16x32_bf16 v[32:35], v[184:187], v[202:205], v[32:35]
	v_mfma_f32_16x16x32_bf16 v[20:23], v[158:161], v[210:213], v[20:23]
	v_mfma_f32_16x16x32_bf16 v[16:19], v[184:187], v[210:213], v[16:19]
	v_mfma_f32_16x16x32_bf16 v[4:7], v[158:161], v[228:231], v[4:7]
	v_mfma_f32_16x16x32_bf16 v[0:3], v[184:187], v[228:231], v[0:3]
	v_mfma_f32_16x16x32_bf16 v[52:55], v[162:165], v[198:201], v[52:55]
	v_mfma_f32_16x16x32_bf16 v[48:51], v[190:193], v[198:201], v[48:51]
	v_mfma_f32_16x16x32_bf16 v[36:39], v[162:165], v[206:209], v[36:39]
	v_mfma_f32_16x16x32_bf16 v[32:35], v[190:193], v[206:209], v[32:35]
	v_mfma_f32_16x16x32_bf16 v[20:23], v[162:165], v[214:217], v[20:23]
	v_mfma_f32_16x16x32_bf16 v[16:19], v[190:193], v[214:217], v[16:19]
	v_mfma_f32_16x16x32_bf16 v[4:7], v[162:165], v[232:235], v[4:7]
	v_mfma_f32_16x16x32_bf16 v[0:3], v[190:193], v[232:235], v[0:3]
	s_barrier
	s_setprio 0
	s_add_i32 s76, s76, 2
	s_add_u32 s69, s69, 0x100
	s_addc_u32 s75, s75, 0
	s_cmp_gt_u32 s76, 13
	s_mov_b64 s[50:51], s[52:53]

.LBB0_591:
	s_add_u32 s8, s4, 0x180000
	s_addc_u32 s9, s5, 0
	s_add_u32 s28, s4, 0x26000000
	s_addc_u32 s29, s5, 0
	s_lshl_b32 s4, s12, 5
	s_and_b32 s12, s4, 0x60
	s_add_i32 m0, s45, 0x18000
	v_lshl_add_u64 v[6:7], v[6:7], 0, s[16:17]
	s_lshl_b32 s13, s1, 13
	s_lshl_b32 s30, s12, 7
	s_waitcnt vmcnt(2)
	s_barrier
	global_load_lds_dwordx4 v[6:7], off
	v_lshl_add_u64 v[4:5], v[4:5], 0, s[16:17]
	s_add_i32 m0, s45, 0x1a000
	s_add_i32 s59, s45, 0x8000
	s_add_i32 s60, s45, 0xa000
	global_load_lds_dwordx4 v[4:5], off
	v_lshl_add_u64 v[0:1], v[0:1], 0, s[16:17]
	s_mov_b32 m0, s59
	s_add_u32 s4, s48, 0x40080
	global_load_lds_dwordx4 v[0:1], off
	v_lshl_add_u64 v[0:1], v[2:3], 0, s[16:17]
	s_mov_b32 m0, s60
	s_addc_u32 s5, s49, 0
	global_load_lds_dwordx4 v[0:1], off
	s_add_i32 m0, s45, 0x1c000
	v_lshl_add_u64 v[0:1], s[4:5], 0, v[170:171]
	global_load_lds_dwordx4 v[0:1], off
	v_lshl_add_u64 v[0:1], s[4:5], 0, v[140:141]
	s_add_i32 m0, s45, 0x1e000
	s_cmpk_lt_u32 s0, 0x100
	global_load_lds_dwordx4 v[0:1], off
	v_lshrrev_b32_e32 v1, 1, v8
	v_and_b32_e32 v1, 24, v1
	v_and_b32_e32 v0, 15, v8
	v_lshlrev_b32_e32 v2, 1, v1
	v_lshl_or_b32 v148, s1, 6, v0
	v_lshl_or_b32 v0, v0, 6, v2
	v_lshlrev_b32_e32 v2, 2, v8
	v_and_b32_e32 v2, 32, v2
	v_bitop3_b32 v3, v0, s13, v2 bitop3:0xde
	v_bitop3_b32 v149, v0, s30, v2 bitop3:0xde
	v_lshlrev_b32_e32 v0, 14, v9
	v_and_b32_e32 v0, 0xffff8000, v0
	v_lshl_add_u32 v0, v10, 11, v0
	v_or_b32_e32 v150, s12, v1
	v_add3_u32 v0, v0, v11, v12
	v_mov_b32_e32 v1, v171
	v_lshl_add_u64 v[142:143], v[0:1], 0, s[18:19]
	v_lshlrev_b32_e32 v0, 14, v13
	v_and_b32_e32 v0, 0xffff8000, v0
	s_waitcnt vmcnt(6)
	s_mov_b32 s99, 1
	v_lshl_add_u32 v0, v14, 11, v0
	v_add3_u32 v0, v0, v15, v16
	s_sext_i32_i16 s61, s2
	s_cselect_b64 s[30:31], -1, 0
	v_lshl_add_u64 v[144:145], v[0:1], 0, s[18:19]
	s_mov_b32 s2, 0
	v_add_u32_e32 v151, 0, v3
	s_barrier
	s_branch .LBB0_594

.Lrestag_601:
	s_add_u32 s48, s46, 0x100
	s_addc_u32 s49, s47, 0
	s_add_i32 s0, 0, 0x10000
	s_cmp_eq_u32 s66, 12
	s_cselect_b32 s53, s37, s49
	s_cselect_b32 s52, s62, s48
	v_add_u32_e32 v146, s0, v149
	s_cselect_b32 s51, s35, s65
	s_cselect_b32 s50, s63, s64
	s_add_i32 s12, 0, 0x14000
	ds_read_b128 v[128:131], v146
	ds_read_b128 v[132:135], v146 offset:1024
	ds_read_b128 v[152:155], v146 offset:2048
	ds_read_b128 v[156:159], v146 offset:3072
	v_add_u32_e32 v146, s12, v149
	ds_read_b128 v[160:163], v146
	ds_read_b128 v[164:167], v146 offset:1024
	ds_read_b128 v[184:187], v146 offset:2048
	ds_read_b128 v[188:191], v146 offset:3072
	s_add_i32 m0, s45, 0xc000
	ds_read_b128 v[192:195], v151
	ds_read_b128 v[196:199], v151 offset:1024
	ds_read_b128 v[200:203], v151 offset:2048
	ds_read_b128 v[204:207], v151 offset:3072
	ds_read_b128 v[208:211], v151 offset:4096
	ds_read_b128 v[212:215], v151 offset:5120
	ds_read_b128 v[216:219], v151 offset:6144
	ds_read_b128 v[228:231], v151 offset:7168
	global_load_lds_dwordx4 v142, s[46:47]
	s_add_i32 m0, s45, 0xe000
	s_nop 0
	global_load_lds_dwordx4 v144, s[46:47]
	s_nop 0
	s_waitcnt lgkmcnt(0)
	s_setprio 1
	s_barrier
	v_mfma_f32_16x16x32_bf16 v[124:127], v[128:131], v[192:195], 0
	v_mfma_f32_16x16x32_bf16 v[120:123], v[152:155], v[192:195], 0
	v_mfma_f32_16x16x32_bf16 v[116:119], v[128:131], v[200:203], 0
	v_mfma_f32_16x16x32_bf16 v[112:115], v[152:155], v[200:203], 0
	v_mfma_f32_16x16x32_bf16 v[108:111], v[128:131], v[208:211], 0
	v_mfma_f32_16x16x32_bf16 v[104:107], v[152:155], v[208:211], 0
	v_mfma_f32_16x16x32_bf16 v[100:103], v[128:131], v[216:219], 0
	v_mfma_f32_16x16x32_bf16 v[96:99], v[152:155], v[216:219], 0
	v_mfma_f32_16x16x32_bf16 v[124:127], v[132:135], v[196:199], v[124:127]
	v_mfma_f32_16x16x32_bf16 v[120:123], v[156:159], v[196:199], v[120:123]
	v_mfma_f32_16x16x32_bf16 v[116:119], v[132:135], v[204:207], v[116:119]
	v_mfma_f32_16x16x32_bf16 v[112:115], v[156:159], v[204:207], v[112:115]
	v_mfma_f32_16x16x32_bf16 v[108:111], v[132:135], v[212:215], v[108:111]
	v_mfma_f32_16x16x32_bf16 v[104:107], v[156:159], v[212:215], v[104:107]
	v_mfma_f32_16x16x32_bf16 v[100:103], v[132:135], v[228:231], v[100:103]
	v_mfma_f32_16x16x32_bf16 v[96:99], v[156:159], v[228:231], v[96:99]
	v_mfma_f32_16x16x32_bf16 v[68:71], v[160:163], v[192:195], 0
	v_mfma_f32_16x16x32_bf16 v[60:63], v[184:187], v[192:195], 0
	v_mfma_f32_16x16x32_bf16 v[52:55], v[160:163], v[200:203], 0
	v_mfma_f32_16x16x32_bf16 v[48:51], v[184:187], v[200:203], 0
	v_mfma_f32_16x16x32_bf16 v[44:47], v[160:163], v[208:211], 0
	v_mfma_f32_16x16x32_bf16 v[40:43], v[184:187], v[208:211], 0
	v_mfma_f32_16x16x32_bf16 v[36:39], v[160:163], v[216:219], 0
	v_mfma_f32_16x16x32_bf16 v[32:35], v[184:187], v[216:219], 0
	v_mfma_f32_16x16x32_bf16 v[68:71], v[164:167], v[196:199], v[68:71]
	v_mfma_f32_16x16x32_bf16 v[60:63], v[188:191], v[196:199], v[60:63]
	v_mfma_f32_16x16x32_bf16 v[52:55], v[164:167], v[204:207], v[52:55]
	v_mfma_f32_16x16x32_bf16 v[48:51], v[188:191], v[204:207], v[48:51]
	v_mfma_f32_16x16x32_bf16 v[44:47], v[164:167], v[212:215], v[44:47]
	v_mfma_f32_16x16x32_bf16 v[40:43], v[188:191], v[212:215], v[40:43]
	v_mfma_f32_16x16x32_bf16 v[36:39], v[164:167], v[228:231], v[36:39]
	v_mfma_f32_16x16x32_bf16 v[32:35], v[188:191], v[228:231], v[32:35]
	s_barrier
	s_setprio 0
	s_add_i32 s0, s0, s55
	v_lshl_add_u64 v[146:147], s[50:51], 0, v[170:171]
	s_mov_b32 m0, s0
	ds_read_b128 v[192:195], v151 offset:16384
	ds_read_b128 v[196:199], v151 offset:17408
	ds_read_b128 v[200:203], v151 offset:18432
	ds_read_b128 v[204:207], v151 offset:19456
	ds_read_b128 v[208:211], v151 offset:20480
	ds_read_b128 v[212:215], v151 offset:21504
	ds_read_b128 v[216:219], v151 offset:22528
	ds_read_b128 v[228:231], v151 offset:23552
	global_load_lds_dwordx4 v[146:147], off
	s_add_i32 m0, s0, 0x2000
	s_add_u32 s0, s50, 0x40000
	v_lshl_add_u64 v[232:233], s[50:51], 0, v[140:141]
	s_addc_u32 s1, s51, 0
	s_add_i32 s12, s12, s55
	global_load_lds_dwordx4 v[232:233], off
	s_mov_b32 m0, s12
	v_lshl_add_u64 v[236:237], s[52:53], 0, v[138:139]
	global_load_lds_dwordx4 v170, s[0:1]
	s_add_i32 m0, s12, 0x2000
	s_nop 0
	global_load_lds_dwordx4 v140, s[0:1]
	v_lshl_add_u64 v[234:235], s[52:53], 0, v[136:137]
	s_cmp_eq_u32 s99, 1
	s_cbranch_scc0 .Lft_601
	s_waitcnt vmcnt(6)
	s_mov_b32 s99, 0
.Lft_601:
	s_waitcnt lgkmcnt(0)
	s_setprio 1
	s_barrier
	v_mfma_f32_16x16x32_bf16 v[92:95], v[128:131], v[192:195], 0
	v_mfma_f32_16x16x32_bf16 v[88:91], v[152:155], v[192:195], 0
	v_mfma_f32_16x16x32_bf16 v[84:87], v[128:131], v[200:203], 0
	v_mfma_f32_16x16x32_bf16 v[80:83], v[152:155], v[200:203], 0
	v_mfma_f32_16x16x32_bf16 v[76:79], v[128:131], v[208:211], 0
	v_mfma_f32_16x16x32_bf16 v[72:75], v[152:155], v[208:211], 0
	v_mfma_f32_16x16x32_bf16 v[64:67], v[128:131], v[216:219], 0
	v_mfma_f32_16x16x32_bf16 v[56:59], v[152:155], v[216:219], 0
	v_mfma_f32_16x16x32_bf16 v[92:95], v[132:135], v[196:199], v[92:95]
	v_mfma_f32_16x16x32_bf16 v[88:91], v[156:159], v[196:199], v[88:91]
	v_mfma_f32_16x16x32_bf16 v[84:87], v[132:135], v[204:207], v[84:87]
	v_mfma_f32_16x16x32_bf16 v[80:83], v[156:159], v[204:207], v[80:83]
	v_mfma_f32_16x16x32_bf16 v[76:79], v[132:135], v[212:215], v[76:79]
	v_mfma_f32_16x16x32_bf16 v[72:75], v[156:159], v[212:215], v[72:75]
	v_mfma_f32_16x16x32_bf16 v[64:67], v[132:135], v[228:231], v[64:67]
	v_mfma_f32_16x16x32_bf16 v[56:59], v[156:159], v[228:231], v[56:59]
	v_mfma_f32_16x16x32_bf16 v[28:31], v[160:163], v[192:195], 0
	v_mfma_f32_16x16x32_bf16 v[24:27], v[184:187], v[192:195], 0
	v_mfma_f32_16x16x32_bf16 v[20:23], v[160:163], v[200:203], 0
	v_mfma_f32_16x16x32_bf16 v[16:19], v[184:187], v[200:203], 0
	v_mfma_f32_16x16x32_bf16 v[12:15], v[160:163], v[208:211], 0
	v_mfma_f32_16x16x32_bf16 v[8:11], v[184:187], v[208:211], 0
	v_mfma_f32_16x16x32_bf16 v[4:7], v[160:163], v[216:219], 0
	v_mfma_f32_16x16x32_bf16 v[0:3], v[184:187], v[216:219], 0
	v_mfma_f32_16x16x32_bf16 v[28:31], v[164:167], v[196:199], v[28:31]
	v_mfma_f32_16x16x32_bf16 v[24:27], v[188:191], v[196:199], v[24:27]
	v_mfma_f32_16x16x32_bf16 v[20:23], v[164:167], v[204:207], v[20:23]
	v_mfma_f32_16x16x32_bf16 v[16:19], v[188:191], v[204:207], v[16:19]
	v_mfma_f32_16x16x32_bf16 v[12:15], v[164:167], v[212:215], v[12:15]
	v_mfma_f32_16x16x32_bf16 v[8:11], v[188:191], v[212:215], v[8:11]
	v_mfma_f32_16x16x32_bf16 v[4:7], v[164:167], v[228:231], v[4:7]
	v_mfma_f32_16x16x32_bf16 v[0:3], v[188:191], v[228:231], v[0:3]
	s_barrier
	s_setprio 0
	s_add_i32 s12, 0, 0x18000
	s_add_i32 s13, 0, 0x1c000
	v_add_u32_e32 v156, s12, v149
	v_add_u32_e32 v188, s13, v149
	ds_read_b128 v[128:131], v156
	ds_read_b128 v[132:135], v156 offset:1024
	ds_read_b128 v[152:155], v156 offset:2048
	ds_read_b128 v[156:159], v156 offset:3072
	ds_read_b128 v[160:163], v188
	ds_read_b128 v[164:167], v188 offset:1024
	ds_read_b128 v[184:187], v188 offset:2048
	ds_read_b128 v[188:191], v188 offset:3072
	s_add_u32 s0, s52, 0x40000
	s_addc_u32 s1, s53, 0
	s_mov_b32 m0, s57
	ds_read_b128 v[192:195], v151 offset:32768
	ds_read_b128 v[196:199], v151 offset:33792
	ds_read_b128 v[200:203], v151 offset:34816
	ds_read_b128 v[204:207], v151 offset:35840
	ds_read_b128 v[208:211], v151 offset:36864
	ds_read_b128 v[212:215], v151 offset:37888
	ds_read_b128 v[216:219], v151 offset:38912
	ds_read_b128 v[228:231], v151 offset:39936
	global_load_lds_dwordx4 v136, s[0:1]
	s_mov_b32 m0, s58
	s_nop 0
	global_load_lds_dwordx4 v138, s[0:1]
	s_mov_b32 m0, s45
	s_nop 0
	global_load_lds_dwordx4 v[234:235], off
	s_mov_b32 m0, s56
	s_nop 0
	global_load_lds_dwordx4 v[236:237], off
	s_waitcnt vmcnt(8)
	s_waitcnt lgkmcnt(0)
	s_setprio 1
	s_barrier
	v_mfma_f32_16x16x32_bf16 v[124:127], v[128:131], v[192:195], v[124:127]
	v_mfma_f32_16x16x32_bf16 v[120:123], v[152:155], v[192:195], v[120:123]
	v_mfma_f32_16x16x32_bf16 v[116:119], v[128:131], v[200:203], v[116:119]
	v_mfma_f32_16x16x32_bf16 v[112:115], v[152:155], v[200:203], v[112:115]
	v_mfma_f32_16x16x32_bf16 v[108:111], v[128:131], v[208:211], v[108:111]
	v_mfma_f32_16x16x32_bf16 v[104:107], v[152:155], v[208:211], v[104:107]
	v_mfma_f32_16x16x32_bf16 v[100:103], v[128:131], v[216:219], v[100:103]
	v_mfma_f32_16x16x32_bf16 v[96:99], v[152:155], v[216:219], v[96:99]
	v_mfma_f32_16x16x32_bf16 v[124:127], v[132:135], v[196:199], v[124:127]
	v_mfma_f32_16x16x32_bf16 v[120:123], v[156:159], v[196:199], v[120:123]
	v_mfma_f32_16x16x32_bf16 v[116:119], v[132:135], v[204:207], v[116:119]
	v_mfma_f32_16x16x32_bf16 v[112:115], v[156:159], v[204:207], v[112:115]
	v_mfma_f32_16x16x32_bf16 v[108:111], v[132:135], v[212:215], v[108:111]
	v_mfma_f32_16x16x32_bf16 v[104:107], v[156:159], v[212:215], v[104:107]
	v_mfma_f32_16x16x32_bf16 v[100:103], v[132:135], v[228:231], v[100:103]
	v_mfma_f32_16x16x32_bf16 v[96:99], v[156:159], v[228:231], v[96:99]
	v_mfma_f32_16x16x32_bf16 v[68:71], v[160:163], v[192:195], v[68:71]
	v_mfma_f32_16x16x32_bf16 v[60:63], v[184:187], v[192:195], v[60:63]
	v_mfma_f32_16x16x32_bf16 v[52:55], v[160:163], v[200:203], v[52:55]
	v_mfma_f32_16x16x32_bf16 v[48:51], v[184:187], v[200:203], v[48:51]
	v_mfma_f32_16x16x32_bf16 v[44:47], v[160:163], v[208:211], v[44:47]
	v_mfma_f32_16x16x32_bf16 v[40:43], v[184:187], v[208:211], v[40:43]
	v_mfma_f32_16x16x32_bf16 v[36:39], v[160:163], v[216:219], v[36:39]
	v_mfma_f32_16x16x32_bf16 v[32:35], v[184:187], v[216:219], v[32:35]
	v_mfma_f32_16x16x32_bf16 v[68:71], v[164:167], v[196:199], v[68:71]
	v_mfma_f32_16x16x32_bf16 v[60:63], v[188:191], v[196:199], v[60:63]
	v_mfma_f32_16x16x32_bf16 v[52:55], v[164:167], v[204:207], v[52:55]
	v_mfma_f32_16x16x32_bf16 v[48:51], v[188:191], v[204:207], v[48:51]
	v_mfma_f32_16x16x32_bf16 v[44:47], v[164:167], v[212:215], v[44:47]
	v_mfma_f32_16x16x32_bf16 v[40:43], v[188:191], v[212:215], v[40:43]
	v_mfma_f32_16x16x32_bf16 v[36:39], v[164:167], v[228:231], v[36:39]
	v_mfma_f32_16x16x32_bf16 v[32:35], v[188:191], v[228:231], v[32:35]
	s_barrier
	s_setprio 0
	s_add_i32 s0, s12, s55
	v_lshl_add_u64 v[146:147], v[146:147], 0, s[16:17]
	s_mov_b32 m0, s0
	ds_read_b128 v[192:195], v151 offset:49152
	ds_read_b128 v[196:199], v151 offset:50176
	ds_read_b128 v[200:203], v151 offset:51200
	ds_read_b128 v[204:207], v151 offset:52224
	ds_read_b128 v[208:211], v151 offset:53248
	ds_read_b128 v[212:215], v151 offset:54272
	ds_read_b128 v[216:219], v151 offset:55296
	ds_read_b128 v[228:231], v151 offset:56320
	global_load_lds_dwordx4 v[146:147], off
	s_add_i32 m0, s0, 0x2000
	s_add_u32 s0, s50, 0x40080
	v_lshl_add_u64 v[146:147], v[232:233], 0, s[16:17]
	s_addc_u32 s1, s51, 0
	s_add_i32 s12, s13, s55
	global_load_lds_dwordx4 v[146:147], off
	s_mov_b32 m0, s12
	s_nop 0
	global_load_lds_dwordx4 v170, s[0:1]
	s_add_i32 m0, s12, 0x2000
	s_nop 0
	global_load_lds_dwordx4 v140, s[0:1]
	v_lshl_add_u64 v[146:147], v[234:235], 0, s[16:17]
	s_mov_b32 m0, s59
	s_nop 0
	global_load_lds_dwordx4 v[146:147], off
	v_lshl_add_u64 v[146:147], v[236:237], 0, s[16:17]
	s_mov_b32 m0, s60
	s_nop 0
	global_load_lds_dwordx4 v[146:147], off
	s_waitcnt vmcnt(6)
	s_waitcnt lgkmcnt(0)
	s_setprio 1
	s_barrier
	v_mfma_f32_16x16x32_bf16 v[92:95], v[128:131], v[192:195], v[92:95]
	v_mfma_f32_16x16x32_bf16 v[88:91], v[152:155], v[192:195], v[88:91]
	v_mfma_f32_16x16x32_bf16 v[84:87], v[128:131], v[200:203], v[84:87]
	v_mfma_f32_16x16x32_bf16 v[80:83], v[152:155], v[200:203], v[80:83]
	v_mfma_f32_16x16x32_bf16 v[76:79], v[128:131], v[208:211], v[76:79]
	v_mfma_f32_16x16x32_bf16 v[72:75], v[152:155], v[208:211], v[72:75]
	v_mfma_f32_16x16x32_bf16 v[64:67], v[128:131], v[216:219], v[64:67]
	v_mfma_f32_16x16x32_bf16 v[56:59], v[152:155], v[216:219], v[56:59]
	v_mfma_f32_16x16x32_bf16 v[92:95], v[132:135], v[196:199], v[92:95]
	v_mfma_f32_16x16x32_bf16 v[88:91], v[156:159], v[196:199], v[88:91]
	v_mfma_f32_16x16x32_bf16 v[84:87], v[132:135], v[204:207], v[84:87]
	v_mfma_f32_16x16x32_bf16 v[80:83], v[156:159], v[204:207], v[80:83]
	v_mfma_f32_16x16x32_bf16 v[76:79], v[132:135], v[212:215], v[76:79]
	v_mfma_f32_16x16x32_bf16 v[72:75], v[156:159], v[212:215], v[72:75]
	v_mfma_f32_16x16x32_bf16 v[64:67], v[132:135], v[228:231], v[64:67]
	v_mfma_f32_16x16x32_bf16 v[56:59], v[156:159], v[228:231], v[56:59]
	v_mfma_f32_16x16x32_bf16 v[28:31], v[160:163], v[192:195], v[28:31]
	v_mfma_f32_16x16x32_bf16 v[24:27], v[184:187], v[192:195], v[24:27]
	v_mfma_f32_16x16x32_bf16 v[20:23], v[160:163], v[200:203], v[20:23]
	v_mfma_f32_16x16x32_bf16 v[16:19], v[184:187], v[200:203], v[16:19]
	v_mfma_f32_16x16x32_bf16 v[12:15], v[160:163], v[208:211], v[12:15]
	v_mfma_f32_16x16x32_bf16 v[8:11], v[184:187], v[208:211], v[8:11]
	v_mfma_f32_16x16x32_bf16 v[4:7], v[160:163], v[216:219], v[4:7]
	v_mfma_f32_16x16x32_bf16 v[0:3], v[184:187], v[216:219], v[0:3]
	v_mfma_f32_16x16x32_bf16 v[28:31], v[164:167], v[196:199], v[28:31]
	v_mfma_f32_16x16x32_bf16 v[24:27], v[188:191], v[196:199], v[24:27]
	v_mfma_f32_16x16x32_bf16 v[20:23], v[164:167], v[204:207], v[20:23]
	v_mfma_f32_16x16x32_bf16 v[16:19], v[188:191], v[204:207], v[16:19]
	v_mfma_f32_16x16x32_bf16 v[12:15], v[164:167], v[212:215], v[12:15]
	v_mfma_f32_16x16x32_bf16 v[8:11], v[188:191], v[212:215], v[8:11]
	v_mfma_f32_16x16x32_bf16 v[4:7], v[164:167], v[228:231], v[4:7]
	v_mfma_f32_16x16x32_bf16 v[0:3], v[188:191], v[228:231], v[0:3]
	s_barrier
	s_setprio 0
	s_add_i32 s66, s66, 2
	s_add_u32 s64, s64, 0x100
	s_addc_u32 s65, s65, 0
	s_cmp_gt_u32 s66, 13
	s_mov_b64 s[46:47], s[48:49]

.LBB0_766:
	s_add_u32 s28, s4, 0x1c0000
	s_addc_u32 s29, s5, 0
	s_lshl_b32 s6, s6, 5
	s_and_b32 s13, s6, 0x60
	s_add_i32 m0, s47, 0x18000
	v_lshl_add_u64 v[6:7], v[6:7], 0, s[16:17]
	s_lshl_b32 s12, s1, 13
	s_lshl_b32 s30, s13, 7
	s_waitcnt vmcnt(2)
	s_barrier
	global_load_lds_dwordx4 v[6:7], off
	v_lshl_add_u64 v[4:5], v[4:5], 0, s[16:17]
	s_add_i32 m0, s47, 0x1a000
	s_add_i32 s60, s47, 0x8000
	s_add_i32 s61, s47, 0xa000
	global_load_lds_dwordx4 v[4:5], off
	v_lshl_add_u64 v[0:1], v[0:1], 0, s[16:17]
	s_mov_b32 m0, s60
	s_add_u32 s6, s50, 0x40080
	global_load_lds_dwordx4 v[0:1], off
	v_lshl_add_u64 v[0:1], v[2:3], 0, s[16:17]
	s_mov_b32 m0, s61
	s_addc_u32 s7, s51, 0
	global_load_lds_dwordx4 v[0:1], off
	s_add_i32 m0, s47, 0x1c000
	v_lshl_add_u64 v[0:1], s[6:7], 0, v[170:171]
	global_load_lds_dwordx4 v[0:1], off
	v_lshl_add_u64 v[0:1], s[6:7], 0, v[156:157]
	s_add_i32 m0, s47, 0x1e000
	v_bfe_u32 v2, v8, 4, 2
	global_load_lds_dwordx4 v[0:1], off
	v_and_b32_e32 v1, 15, v8
	v_lshlrev_b32_e32 v0, 4, v2
	v_lshlrev_b32_e32 v3, 2, v8
	v_lshl_or_b32 v196, s1, 6, v1
	v_lshl_or_b32 v1, v1, 6, v0
	v_and_b32_e32 v3, 32, v3
	s_cmpk_lt_u32 s0, 0x100
	v_bitop3_b32 v197, v1, s30, v3 bitop3:0xde
	s_cselect_b64 s[30:31], -1, 0
	s_lshl_b32 s0, s13, 1
	s_add_u32 s0, s4, s0
	v_bitop3_b32 v4, v1, s12, v3 bitop3:0xde
	s_addc_u32 s1, s5, 0
	v_mov_b32_e32 v1, v171
	v_lshl_add_u64 v[0:1], s[0:1], 0, v[0:1]
	s_mov_b64 s[0:1], 0x10000000
	v_lshl_add_u64 v[158:159], v[0:1], 0, s[0:1]
	v_lshlrev_b32_e32 v0, 14, v9
	v_and_b32_e32 v0, 0xffff8000, v0
	v_lshl_add_u32 v0, v10, 11, v0
	v_add3_u32 v0, v0, v11, v12
	v_mov_b32_e32 v1, v171
	v_lshl_add_u64 v[160:161], v[0:1], 0, s[18:19]
	v_lshlrev_b32_e32 v0, 14, v13
	v_and_b32_e32 v0, 0xffff8000, v0
	s_waitcnt vmcnt(6)
	s_mov_b32 s99, 1
	v_lshl_add_u32 v0, v14, 11, v0
	v_add3_u32 v0, v0, v15, v16
	s_mov_b32 s62, 0
	v_cmp_eq_u32_e64 s[4:5], 0, v2
	v_lshl_add_u64 v[162:163], v[0:1], 0, s[18:19]
	v_add_u32_e32 v198, 0, v4
	s_barrier
	s_branch .LBB0_769

.Lrestag_776:
	s_add_u32 s50, s48, 0x100
	s_addc_u32 s51, s49, 0
	s_add_i32 s0, 0, 0x10000
	s_cmp_eq_u32 s66, 12
	s_cselect_b32 s55, s37, s51
	s_cselect_b32 s54, s45, s50
	s_cselect_b32 s53, s35, s65
	s_cselect_b32 s52, s63, s64
	s_add_i32 s12, 0, 0x14000
	v_add_u32_e32 v140, s0, v197
	v_add_u32_e32 v184, s12, v197
	ds_read_b128 v[128:131], v140
	ds_read_b128 v[132:135], v140 offset:1024
	ds_read_b128 v[136:139], v140 offset:2048
	ds_read_b128 v[140:143], v140 offset:3072
	ds_read_b128 v[144:147], v184
	ds_read_b128 v[148:151], v184 offset:1024
	ds_read_b128 v[164:167], v184 offset:2048
	ds_read_b128 v[184:187], v184 offset:3072
	s_add_i32 m0, s47, 0xc000
	ds_read_b128 v[188:191], v198
	ds_read_b128 v[192:195], v198 offset:1024
	ds_read_b128 v[200:203], v198 offset:2048
	ds_read_b128 v[204:207], v198 offset:3072
	ds_read_b128 v[208:211], v198 offset:4096
	ds_read_b128 v[212:215], v198 offset:5120
	ds_read_b128 v[216:219], v198 offset:6144
	ds_read_b128 v[228:231], v198 offset:7168
	global_load_lds_dwordx4 v160, s[48:49]
	s_add_i32 m0, s47, 0xe000
	s_nop 0
	global_load_lds_dwordx4 v162, s[48:49]
	s_nop 0
	s_waitcnt lgkmcnt(0)
	s_setprio 1
	s_barrier
	v_mfma_f32_16x16x32_bf16 v[124:127], v[128:131], v[188:191], 0
	v_mfma_f32_16x16x32_bf16 v[120:123], v[136:139], v[188:191], 0
	v_mfma_f32_16x16x32_bf16 v[108:111], v[128:131], v[200:203], 0
	v_mfma_f32_16x16x32_bf16 v[104:107], v[136:139], v[200:203], 0
	v_mfma_f32_16x16x32_bf16 v[92:95], v[128:131], v[208:211], 0
	v_mfma_f32_16x16x32_bf16 v[88:91], v[136:139], v[208:211], 0
	v_mfma_f32_16x16x32_bf16 v[76:79], v[128:131], v[216:219], 0
	v_mfma_f32_16x16x32_bf16 v[72:75], v[136:139], v[216:219], 0
	v_mfma_f32_16x16x32_bf16 v[124:127], v[132:135], v[192:195], v[124:127]
	v_mfma_f32_16x16x32_bf16 v[120:123], v[140:143], v[192:195], v[120:123]
	v_mfma_f32_16x16x32_bf16 v[108:111], v[132:135], v[204:207], v[108:111]
	v_mfma_f32_16x16x32_bf16 v[104:107], v[140:143], v[204:207], v[104:107]
	v_mfma_f32_16x16x32_bf16 v[92:95], v[132:135], v[212:215], v[92:95]
	v_mfma_f32_16x16x32_bf16 v[88:91], v[140:143], v[212:215], v[88:91]
	v_mfma_f32_16x16x32_bf16 v[76:79], v[132:135], v[228:231], v[76:79]
	v_mfma_f32_16x16x32_bf16 v[72:75], v[140:143], v[228:231], v[72:75]
	v_mfma_f32_16x16x32_bf16 v[116:119], v[144:147], v[188:191], 0
	v_mfma_f32_16x16x32_bf16 v[112:115], v[164:167], v[188:191], 0
	v_mfma_f32_16x16x32_bf16 v[100:103], v[144:147], v[200:203], 0
	v_mfma_f32_16x16x32_bf16 v[96:99], v[164:167], v[200:203], 0
	v_mfma_f32_16x16x32_bf16 v[84:87], v[144:147], v[208:211], 0
	v_mfma_f32_16x16x32_bf16 v[80:83], v[164:167], v[208:211], 0
	v_mfma_f32_16x16x32_bf16 v[68:71], v[144:147], v[216:219], 0
	v_mfma_f32_16x16x32_bf16 v[64:67], v[164:167], v[216:219], 0
	v_mfma_f32_16x16x32_bf16 v[116:119], v[148:151], v[192:195], v[116:119]
	v_mfma_f32_16x16x32_bf16 v[112:115], v[184:187], v[192:195], v[112:115]
	v_mfma_f32_16x16x32_bf16 v[100:103], v[148:151], v[204:207], v[100:103]
	v_mfma_f32_16x16x32_bf16 v[96:99], v[184:187], v[204:207], v[96:99]
	v_mfma_f32_16x16x32_bf16 v[84:87], v[148:151], v[212:215], v[84:87]
	v_mfma_f32_16x16x32_bf16 v[80:83], v[184:187], v[212:215], v[80:83]
	v_mfma_f32_16x16x32_bf16 v[68:71], v[148:151], v[228:231], v[68:71]
	v_mfma_f32_16x16x32_bf16 v[64:67], v[184:187], v[228:231], v[64:67]
	s_barrier
	s_setprio 0
	s_add_i32 s0, s0, s56
	v_lshl_add_u64 v[232:233], s[52:53], 0, v[170:171]
	s_mov_b32 m0, s0
	ds_read_b128 v[188:191], v198 offset:16384
	ds_read_b128 v[192:195], v198 offset:17408
	ds_read_b128 v[200:203], v198 offset:18432
	ds_read_b128 v[204:207], v198 offset:19456
	ds_read_b128 v[208:211], v198 offset:20480
	ds_read_b128 v[212:215], v198 offset:21504
	ds_read_b128 v[216:219], v198 offset:22528
	ds_read_b128 v[228:231], v198 offset:23552
	global_load_lds_dwordx4 v[232:233], off
	s_add_i32 m0, s0, 0x2000
	s_add_u32 s0, s52, 0x40000
	v_lshl_add_u64 v[234:235], s[52:53], 0, v[156:157]
	s_addc_u32 s1, s53, 0
	s_add_i32 s12, s12, s56
	global_load_lds_dwordx4 v[234:235], off
	s_mov_b32 m0, s12
	v_lshl_add_u64 v[238:239], s[54:55], 0, v[154:155]
	global_load_lds_dwordx4 v170, s[0:1]
	s_add_i32 m0, s12, 0x2000
	s_nop 0
	global_load_lds_dwordx4 v156, s[0:1]
	v_lshl_add_u64 v[236:237], s[54:55], 0, v[152:153]
	s_cmp_eq_u32 s99, 1
	s_cbranch_scc0 .Lft_776
	s_waitcnt vmcnt(6)
	s_mov_b32 s99, 0
.Lft_776:
	s_waitcnt lgkmcnt(0)
	s_setprio 1
	s_barrier
	v_mfma_f32_16x16x32_bf16 v[60:63], v[128:131], v[188:191], 0
	v_mfma_f32_16x16x32_bf16 v[56:59], v[136:139], v[188:191], 0
	v_mfma_f32_16x16x32_bf16 v[44:47], v[128:131], v[200:203], 0
	v_mfma_f32_16x16x32_bf16 v[40:43], v[136:139], v[200:203], 0
	v_mfma_f32_16x16x32_bf16 v[28:31], v[128:131], v[208:211], 0
	v_mfma_f32_16x16x32_bf16 v[24:27], v[136:139], v[208:211], 0
	v_mfma_f32_16x16x32_bf16 v[12:15], v[128:131], v[216:219], 0
	v_mfma_f32_16x16x32_bf16 v[8:11], v[136:139], v[216:219], 0
	v_mfma_f32_16x16x32_bf16 v[60:63], v[132:135], v[192:195], v[60:63]
	v_mfma_f32_16x16x32_bf16 v[56:59], v[140:143], v[192:195], v[56:59]
	v_mfma_f32_16x16x32_bf16 v[44:47], v[132:135], v[204:207], v[44:47]
	v_mfma_f32_16x16x32_bf16 v[40:43], v[140:143], v[204:207], v[40:43]
	v_mfma_f32_16x16x32_bf16 v[28:31], v[132:135], v[212:215], v[28:31]
	v_mfma_f32_16x16x32_bf16 v[24:27], v[140:143], v[212:215], v[24:27]
	v_mfma_f32_16x16x32_bf16 v[12:15], v[132:135], v[228:231], v[12:15]
	v_mfma_f32_16x16x32_bf16 v[8:11], v[140:143], v[228:231], v[8:11]
	v_mfma_f32_16x16x32_bf16 v[52:55], v[144:147], v[188:191], 0
	v_mfma_f32_16x16x32_bf16 v[48:51], v[164:167], v[188:191], 0
	v_mfma_f32_16x16x32_bf16 v[36:39], v[144:147], v[200:203], 0
	v_mfma_f32_16x16x32_bf16 v[32:35], v[164:167], v[200:203], 0
	v_mfma_f32_16x16x32_bf16 v[20:23], v[144:147], v[208:211], 0
	v_mfma_f32_16x16x32_bf16 v[16:19], v[164:167], v[208:211], 0
	v_mfma_f32_16x16x32_bf16 v[4:7], v[144:147], v[216:219], 0
	v_mfma_f32_16x16x32_bf16 v[0:3], v[164:167], v[216:219], 0
	v_mfma_f32_16x16x32_bf16 v[52:55], v[148:151], v[192:195], v[52:55]
	v_mfma_f32_16x16x32_bf16 v[48:51], v[184:187], v[192:195], v[48:51]
	v_mfma_f32_16x16x32_bf16 v[36:39], v[148:151], v[204:207], v[36:39]
	v_mfma_f32_16x16x32_bf16 v[32:35], v[184:187], v[204:207], v[32:35]
	v_mfma_f32_16x16x32_bf16 v[20:23], v[148:151], v[212:215], v[20:23]
	v_mfma_f32_16x16x32_bf16 v[16:19], v[184:187], v[212:215], v[16:19]
	v_mfma_f32_16x16x32_bf16 v[4:7], v[148:151], v[228:231], v[4:7]
	v_mfma_f32_16x16x32_bf16 v[0:3], v[184:187], v[228:231], v[0:3]
	s_barrier
	s_setprio 0
	s_add_i32 s12, 0, 0x18000
	s_add_i32 s13, 0, 0x1c000
	v_add_u32_e32 v140, s12, v197
	v_add_u32_e32 v184, s13, v197
	ds_read_b128 v[128:131], v140
	ds_read_b128 v[132:135], v140 offset:1024
	ds_read_b128 v[136:139], v140 offset:2048
	ds_read_b128 v[140:143], v140 offset:3072
	ds_read_b128 v[144:147], v184
	ds_read_b128 v[148:151], v184 offset:1024
	ds_read_b128 v[164:167], v184 offset:2048
	ds_read_b128 v[184:187], v184 offset:3072
	s_add_u32 s0, s54, 0x40000
	s_addc_u32 s1, s55, 0
	s_mov_b32 m0, s58
	ds_read_b128 v[188:191], v198 offset:32768
	ds_read_b128 v[192:195], v198 offset:33792
	ds_read_b128 v[200:203], v198 offset:34816
	ds_read_b128 v[204:207], v198 offset:35840
	ds_read_b128 v[208:211], v198 offset:36864
	ds_read_b128 v[212:215], v198 offset:37888
	ds_read_b128 v[216:219], v198 offset:38912
	ds_read_b128 v[228:231], v198 offset:39936
	global_load_lds_dwordx4 v152, s[0:1]
	s_mov_b32 m0, s59
	s_nop 0
	global_load_lds_dwordx4 v154, s[0:1]
	s_mov_b32 m0, s47
	s_nop 0
	global_load_lds_dwordx4 v[236:237], off
	s_mov_b32 m0, s57
	s_nop 0
	global_load_lds_dwordx4 v[238:239], off
	s_waitcnt vmcnt(8)
	s_waitcnt lgkmcnt(0)
	s_setprio 1
	s_barrier
	v_mfma_f32_16x16x32_bf16 v[124:127], v[128:131], v[188:191], v[124:127]
	v_mfma_f32_16x16x32_bf16 v[120:123], v[136:139], v[188:191], v[120:123]
	v_mfma_f32_16x16x32_bf16 v[108:111], v[128:131], v[200:203], v[108:111]
	v_mfma_f32_16x16x32_bf16 v[104:107], v[136:139], v[200:203], v[104:107]
	v_mfma_f32_16x16x32_bf16 v[92:95], v[128:131], v[208:211], v[92:95]
	v_mfma_f32_16x16x32_bf16 v[88:91], v[136:139], v[208:211], v[88:91]
	v_mfma_f32_16x16x32_bf16 v[76:79], v[128:131], v[216:219], v[76:79]
	v_mfma_f32_16x16x32_bf16 v[72:75], v[136:139], v[216:219], v[72:75]
	v_mfma_f32_16x16x32_bf16 v[124:127], v[132:135], v[192:195], v[124:127]
	v_mfma_f32_16x16x32_bf16 v[120:123], v[140:143], v[192:195], v[120:123]
	v_mfma_f32_16x16x32_bf16 v[108:111], v[132:135], v[204:207], v[108:111]
	v_mfma_f32_16x16x32_bf16 v[104:107], v[140:143], v[204:207], v[104:107]
	v_mfma_f32_16x16x32_bf16 v[92:95], v[132:135], v[212:215], v[92:95]
	v_mfma_f32_16x16x32_bf16 v[88:91], v[140:143], v[212:215], v[88:91]
	v_mfma_f32_16x16x32_bf16 v[76:79], v[132:135], v[228:231], v[76:79]
	v_mfma_f32_16x16x32_bf16 v[72:75], v[140:143], v[228:231], v[72:75]
	v_mfma_f32_16x16x32_bf16 v[116:119], v[144:147], v[188:191], v[116:119]
	v_mfma_f32_16x16x32_bf16 v[112:115], v[164:167], v[188:191], v[112:115]
	v_mfma_f32_16x16x32_bf16 v[100:103], v[144:147], v[200:203], v[100:103]
	v_mfma_f32_16x16x32_bf16 v[96:99], v[164:167], v[200:203], v[96:99]
	v_mfma_f32_16x16x32_bf16 v[84:87], v[144:147], v[208:211], v[84:87]
	v_mfma_f32_16x16x32_bf16 v[80:83], v[164:167], v[208:211], v[80:83]
	v_mfma_f32_16x16x32_bf16 v[68:71], v[144:147], v[216:219], v[68:71]
	v_mfma_f32_16x16x32_bf16 v[64:67], v[164:167], v[216:219], v[64:67]
	v_mfma_f32_16x16x32_bf16 v[116:119], v[148:151], v[192:195], v[116:119]
	v_mfma_f32_16x16x32_bf16 v[112:115], v[184:187], v[192:195], v[112:115]
	v_mfma_f32_16x16x32_bf16 v[100:103], v[148:151], v[204:207], v[100:103]
	v_mfma_f32_16x16x32_bf16 v[96:99], v[184:187], v[204:207], v[96:99]
	v_mfma_f32_16x16x32_bf16 v[84:87], v[148:151], v[212:215], v[84:87]
	v_mfma_f32_16x16x32_bf16 v[80:83], v[184:187], v[212:215], v[80:83]
	v_mfma_f32_16x16x32_bf16 v[68:71], v[148:151], v[228:231], v[68:71]
	v_mfma_f32_16x16x32_bf16 v[64:67], v[184:187], v[228:231], v[64:67]
	s_barrier
	s_setprio 0
	s_add_i32 s0, s12, s56
	v_lshl_add_u64 v[232:233], v[232:233], 0, s[16:17]
	s_mov_b32 m0, s0
	ds_read_b128 v[188:191], v198 offset:49152
	ds_read_b128 v[192:195], v198 offset:50176
	ds_read_b128 v[200:203], v198 offset:51200
	ds_read_b128 v[204:207], v198 offset:52224
	ds_read_b128 v[208:211], v198 offset:53248
	ds_read_b128 v[212:215], v198 offset:54272
	ds_read_b128 v[216:219], v198 offset:55296
	ds_read_b128 v[228:231], v198 offset:56320
	global_load_lds_dwordx4 v[232:233], off
	s_add_i32 m0, s0, 0x2000
	s_add_u32 s0, s52, 0x40080
	v_lshl_add_u64 v[232:233], v[234:235], 0, s[16:17]
	s_addc_u32 s1, s53, 0
	s_add_i32 s12, s13, s56
	global_load_lds_dwordx4 v[232:233], off
	s_mov_b32 m0, s12
	s_nop 0
	global_load_lds_dwordx4 v170, s[0:1]
	s_add_i32 m0, s12, 0x2000
	s_nop 0
	global_load_lds_dwordx4 v156, s[0:1]
	v_lshl_add_u64 v[232:233], v[236:237], 0, s[16:17]
	s_mov_b32 m0, s60
	s_nop 0
	global_load_lds_dwordx4 v[232:233], off
	v_lshl_add_u64 v[232:233], v[238:239], 0, s[16:17]
	s_mov_b32 m0, s61
	s_nop 0
	global_load_lds_dwordx4 v[232:233], off
	s_waitcnt vmcnt(6)
	s_waitcnt lgkmcnt(0)
	s_setprio 1
	s_barrier
	v_mfma_f32_16x16x32_bf16 v[60:63], v[128:131], v[188:191], v[60:63]
	v_mfma_f32_16x16x32_bf16 v[56:59], v[136:139], v[188:191], v[56:59]
	v_mfma_f32_16x16x32_bf16 v[44:47], v[128:131], v[200:203], v[44:47]
	v_mfma_f32_16x16x32_bf16 v[40:43], v[136:139], v[200:203], v[40:43]
	v_mfma_f32_16x16x32_bf16 v[28:31], v[128:131], v[208:211], v[28:31]
	v_mfma_f32_16x16x32_bf16 v[24:27], v[136:139], v[208:211], v[24:27]
	v_mfma_f32_16x16x32_bf16 v[12:15], v[128:131], v[216:219], v[12:15]
	v_mfma_f32_16x16x32_bf16 v[8:11], v[136:139], v[216:219], v[8:11]
	v_mfma_f32_16x16x32_bf16 v[60:63], v[132:135], v[192:195], v[60:63]
	v_mfma_f32_16x16x32_bf16 v[56:59], v[140:143], v[192:195], v[56:59]
	v_mfma_f32_16x16x32_bf16 v[44:47], v[132:135], v[204:207], v[44:47]
	v_mfma_f32_16x16x32_bf16 v[40:43], v[140:143], v[204:207], v[40:43]
	v_mfma_f32_16x16x32_bf16 v[28:31], v[132:135], v[212:215], v[28:31]
	v_mfma_f32_16x16x32_bf16 v[24:27], v[140:143], v[212:215], v[24:27]
	v_mfma_f32_16x16x32_bf16 v[12:15], v[132:135], v[228:231], v[12:15]
	v_mfma_f32_16x16x32_bf16 v[8:11], v[140:143], v[228:231], v[8:11]
	v_mfma_f32_16x16x32_bf16 v[52:55], v[144:147], v[188:191], v[52:55]
	v_mfma_f32_16x16x32_bf16 v[48:51], v[164:167], v[188:191], v[48:51]
	v_mfma_f32_16x16x32_bf16 v[36:39], v[144:147], v[200:203], v[36:39]
	v_mfma_f32_16x16x32_bf16 v[32:35], v[164:167], v[200:203], v[32:35]
	v_mfma_f32_16x16x32_bf16 v[20:23], v[144:147], v[208:211], v[20:23]
	v_mfma_f32_16x16x32_bf16 v[16:19], v[164:167], v[208:211], v[16:19]
	v_mfma_f32_16x16x32_bf16 v[4:7], v[144:147], v[216:219], v[4:7]
	v_mfma_f32_16x16x32_bf16 v[0:3], v[164:167], v[216:219], v[0:3]
	v_mfma_f32_16x16x32_bf16 v[52:55], v[148:151], v[192:195], v[52:55]
	v_mfma_f32_16x16x32_bf16 v[48:51], v[184:187], v[192:195], v[48:51]
	v_mfma_f32_16x16x32_bf16 v[36:39], v[148:151], v[204:207], v[36:39]
	v_mfma_f32_16x16x32_bf16 v[32:35], v[184:187], v[204:207], v[32:35]
	v_mfma_f32_16x16x32_bf16 v[20:23], v[148:151], v[212:215], v[20:23]
	v_mfma_f32_16x16x32_bf16 v[16:19], v[184:187], v[212:215], v[16:19]
	v_mfma_f32_16x16x32_bf16 v[4:7], v[148:151], v[228:231], v[4:7]
	v_mfma_f32_16x16x32_bf16 v[0:3], v[184:187], v[228:231], v[0:3]
	s_barrier
	s_setprio 0
	s_add_i32 s66, s66, 2
	s_add_u32 s64, s64, 0x100
	s_addc_u32 s65, s65, 0
	s_cmp_gt_u32 s66, 13
	s_mov_b64 s[48:49], s[50:51]

.LBB0_857:
	s_mul_hi_u32 s15, s26, 0xff580000
	s_mul_i32 s14, s27, 0xff580000
	s_sub_i32 s15, s15, s26
	s_add_i32 s15, s15, s14
	s_mul_i32 s14, s26, 0xff580000
	s_add_u32 s12, s12, s14
	s_addc_u32 s13, s13, s15
	s_add_u32 s26, s12, 0x140000
	s_addc_u32 s27, s13, 0
	s_lshl_b64 s[12:13], s[2:3], 2
	s_add_u32 s34, s4, s12
	s_addc_u32 s35, s5, s13
	s_lshl_b64 s[4:5], s[30:31], 2
	s_add_u32 s36, s6, s4
	s_addc_u32 s37, s7, s5
	s_add_u32 s40, s8, 0x1e000000
	s_addc_u32 s41, s9, 0
	s_add_u32 s80, s8, 0x36000000
	s_addc_u32 s14, s9, 0
	s_lshl_b32 s4, s22, 5
	s_and_b32 s8, s4, 0x60
	s_add_i32 m0, s59, 0x18000
	v_lshl_add_u64 v[6:7], v[6:7], 0, s[16:17]
	s_lshl_b32 s15, s1, 6
	s_lshl_b32 s1, s1, 13
	s_lshl_b32 s6, s8, 7
	s_waitcnt vmcnt(2)
	s_barrier
	global_load_lds_dwordx4 v[6:7], off
	v_lshl_add_u64 v[4:5], v[4:5], 0, s[16:17]
	s_add_i32 m0, s59, 0x1a000
	s_add_i32 s75, s59, 0x8000
	s_add_i32 s91, s59, 0xa000
	global_load_lds_dwordx4 v[4:5], off
	v_lshl_add_u64 v[0:1], v[0:1], 0, s[16:17]
	s_mov_b32 m0, s75
	s_add_u32 s4, s62, 0x40080
	global_load_lds_dwordx4 v[0:1], off
	v_lshl_add_u64 v[0:1], v[2:3], 0, s[16:17]
	s_mov_b32 m0, s91
	s_addc_u32 s5, s63, 0
	global_load_lds_dwordx4 v[0:1], off
	s_add_i32 m0, s59, 0x1c000
	v_lshl_add_u64 v[0:1], s[4:5], 0, v[170:171]
	global_load_lds_dwordx4 v[0:1], off
	v_lshl_add_u64 v[0:1], s[4:5], 0, v[188:189]
	s_add_i32 m0, s59, 0x1e000
	s_cmpk_lt_u32 s0, 0x100
	global_load_lds_dwordx4 v[0:1], off
	v_lshrrev_b32_e32 v1, 1, v8
	v_and_b32_e32 v0, 15, v8
	v_and_b32_e32 v1, 24, v1
	v_lshlrev_b32_e32 v2, 1, v1
	v_lshlrev_b32_e32 v227, 2, v0
	v_lshl_or_b32 v2, v0, 6, v2
	v_and_b32_e32 v3, 32, v227
	v_bitop3_b32 v228, v2, s6, v3 bitop3:0xde
	v_cmp_ne_u32_e64 s[4:5], 0, v0
	v_cmp_eq_u32_e64 s[6:7], 15, v0
	v_add_u32_e32 v0, v9, v10
	v_add_lshl_u32 v0, v0, v11, 11
	v_or_b32_e32 v229, s8, v1
	v_add3_u32 v0, v0, v12, v13
	v_mov_b32_e32 v1, v171
	s_cselect_b64 s[42:43], -1, 0
	s_add_u32 s44, s34, 0x2c00
	v_lshl_add_u64 v[190:191], v[0:1], 0, s[18:19]
	v_add_u32_e32 v0, v14, v15
	s_waitcnt vmcnt(6)
	s_mov_b32 s99, 1
	s_addc_u32 s45, s35, 0
	v_add_lshl_u32 v0, v0, v16, 11
	v_bitop3_b32 v4, v2, s1, v3 bitop3:0xde
	s_add_u32 s46, s34, 0x5800
	v_add3_u32 v0, v0, v17, v18
	s_addc_u32 s47, s35, 0
	s_mov_b32 s22, 0
	v_lshl_add_u64 v[192:193], v[0:1], 0, s[18:19]
	v_add_u32_e32 v230, 0, v4
	s_barrier
	s_branch .LBB0_860

.Lrestag_863:
	s_add_u32 s62, s60, 0x100
	s_addc_u32 s63, s61, 0
	s_add_i32 s0, 0, 0x10000
	s_cmp_eq_u32 s12, 12
	s_cselect_b32 s67, s23, s63
	s_cselect_b32 s66, s51, s62
	s_cselect_b32 s65, s49, vcc_hi
	s_cselect_b32 s64, s57, vcc_lo
	s_add_i32 s13, 0, 0x14000
	v_add_u32_e32 v64, s0, v228
	v_add_u32_e32 v92, s13, v228
	ds_read_b128 v[48:51], v64
	ds_read_b128 v[52:55], v64 offset:1024
	ds_read_b128 v[60:63], v64 offset:2048
	ds_read_b128 v[64:67], v64 offset:3072
	ds_read_b128 v[72:75], v92
	ds_read_b128 v[80:83], v92 offset:1024
	ds_read_b128 v[84:87], v92 offset:2048
	ds_read_b128 v[92:95], v92 offset:3072
	s_add_i32 m0, s59, 0xc000
	ds_read_b128 v[112:115], v230
	ds_read_b128 v[164:167], v230 offset:1024
	ds_read_b128 v[194:197], v230 offset:2048
	ds_read_b128 v[198:201], v230 offset:3072
	ds_read_b128 v[202:205], v230 offset:4096
	ds_read_b128 v[206:209], v230 offset:5120
	ds_read_b128 v[210:213], v230 offset:6144
	ds_read_b128 v[214:217], v230 offset:7168
	global_load_lds_dwordx4 v190, s[60:61]
	s_add_i32 m0, s59, 0xe000
	s_nop 0
	global_load_lds_dwordx4 v192, s[60:61]
	s_nop 0
	s_waitcnt lgkmcnt(0)
	s_setprio 1
	s_barrier
	v_mfma_f32_16x16x32_bf16 v[160:163], v[48:51], v[112:115], 0
	v_mfma_f32_16x16x32_bf16 v[156:159], v[60:63], v[112:115], 0
	v_mfma_f32_16x16x32_bf16 v[128:131], v[48:51], v[194:197], 0
	v_mfma_f32_16x16x32_bf16 v[124:127], v[60:63], v[194:197], 0
	v_mfma_f32_16x16x32_bf16 v[108:111], v[48:51], v[202:205], 0
	v_mfma_f32_16x16x32_bf16 v[104:107], v[60:63], v[202:205], 0
	v_mfma_f32_16x16x32_bf16 v[100:103], v[48:51], v[210:213], 0
	v_mfma_f32_16x16x32_bf16 v[96:99], v[60:63], v[210:213], 0
	v_mfma_f32_16x16x32_bf16 v[160:163], v[52:55], v[164:167], v[160:163]
	v_mfma_f32_16x16x32_bf16 v[156:159], v[64:67], v[164:167], v[156:159]
	v_mfma_f32_16x16x32_bf16 v[128:131], v[52:55], v[198:201], v[128:131]
	v_mfma_f32_16x16x32_bf16 v[124:127], v[64:67], v[198:201], v[124:127]
	v_mfma_f32_16x16x32_bf16 v[108:111], v[52:55], v[206:209], v[108:111]
	v_mfma_f32_16x16x32_bf16 v[104:107], v[64:67], v[206:209], v[104:107]
	v_mfma_f32_16x16x32_bf16 v[100:103], v[52:55], v[214:217], v[100:103]
	v_mfma_f32_16x16x32_bf16 v[96:99], v[64:67], v[214:217], v[96:99]
	v_mfma_f32_16x16x32_bf16 v[152:155], v[72:75], v[112:115], 0
	v_mfma_f32_16x16x32_bf16 v[120:123], v[72:75], v[194:197], 0
	v_mfma_f32_16x16x32_bf16 v[116:119], v[84:87], v[194:197], 0
	v_mfma_f32_16x16x32_bf16 v[144:147], v[72:75], v[202:205], 0
	v_mfma_f32_16x16x32_bf16 v[140:143], v[84:87], v[202:205], 0
	v_mfma_f32_16x16x32_bf16 v[136:139], v[72:75], v[210:213], 0
	v_mfma_f32_16x16x32_bf16 v[132:135], v[84:87], v[210:213], 0
	v_mfma_f32_16x16x32_bf16 v[152:155], v[80:83], v[164:167], v[152:155]
	v_mfma_f32_16x16x32_bf16 v[112:115], v[84:87], v[112:115], 0
	v_mfma_f32_16x16x32_bf16 v[120:123], v[80:83], v[198:201], v[120:123]
	v_mfma_f32_16x16x32_bf16 v[116:119], v[92:95], v[198:201], v[116:119]
	v_mfma_f32_16x16x32_bf16 v[144:147], v[80:83], v[206:209], v[144:147]
	v_mfma_f32_16x16x32_bf16 v[140:143], v[92:95], v[206:209], v[140:143]
	v_mfma_f32_16x16x32_bf16 v[136:139], v[80:83], v[214:217], v[136:139]
	v_mfma_f32_16x16x32_bf16 v[132:135], v[92:95], v[214:217], v[132:135]
	v_mfma_f32_16x16x32_bf16 v[112:115], v[92:95], v[164:167], v[112:115]
	s_barrier
	s_setprio 0
	s_add_i32 s0, s0, s96
	v_lshl_add_u64 v[218:219], s[64:65], 0, v[170:171]
	s_mov_b32 m0, s0
	ds_read_b128 v[148:151], v230 offset:16384
	ds_read_b128 v[164:167], v230 offset:17408
	ds_read_b128 v[194:197], v230 offset:18432
	ds_read_b128 v[198:201], v230 offset:19456
	ds_read_b128 v[202:205], v230 offset:20480
	ds_read_b128 v[206:209], v230 offset:21504
	ds_read_b128 v[210:213], v230 offset:22528
	ds_read_b128 v[214:217], v230 offset:23552
	global_load_lds_dwordx4 v[218:219], off
	s_add_i32 m0, s0, 0x2000
	s_add_u32 s0, s64, 0x40000
	v_lshl_add_u64 v[232:233], s[64:65], 0, v[188:189]
	s_addc_u32 s1, s65, 0
	s_add_i32 s13, s13, s96
	global_load_lds_dwordx4 v[232:233], off
	s_mov_b32 m0, s13
	v_lshl_add_u64 v[236:237], s[66:67], 0, v[186:187]
	global_load_lds_dwordx4 v170, s[0:1]
	s_add_i32 m0, s13, 0x2000
	s_nop 0
	global_load_lds_dwordx4 v188, s[0:1]
	v_lshl_add_u64 v[234:235], s[66:67], 0, v[184:185]
	s_cmp_eq_u32 s99, 1
	s_cbranch_scc0 .Lft_863
	s_waitcnt vmcnt(6)
	s_mov_b32 s99, 0
.Lft_863:
	s_waitcnt lgkmcnt(0)
	s_setprio 1
	s_barrier
	v_mfma_f32_16x16x32_bf16 v[88:91], v[48:51], v[148:151], 0
	v_mfma_f32_16x16x32_bf16 v[76:79], v[60:63], v[148:151], 0
	v_mfma_f32_16x16x32_bf16 v[28:31], v[48:51], v[194:197], 0
	v_mfma_f32_16x16x32_bf16 v[24:27], v[60:63], v[194:197], 0
	v_mfma_f32_16x16x32_bf16 v[12:15], v[48:51], v[202:205], 0
	v_mfma_f32_16x16x32_bf16 v[8:11], v[60:63], v[202:205], 0
	v_mfma_f32_16x16x32_bf16 v[4:7], v[48:51], v[210:213], 0
	v_mfma_f32_16x16x32_bf16 v[0:3], v[60:63], v[210:213], 0
	v_mfma_f32_16x16x32_bf16 v[88:91], v[52:55], v[164:167], v[88:91]
	v_mfma_f32_16x16x32_bf16 v[76:79], v[64:67], v[164:167], v[76:79]
	v_mfma_f32_16x16x32_bf16 v[28:31], v[52:55], v[198:201], v[28:31]
	v_mfma_f32_16x16x32_bf16 v[24:27], v[64:67], v[198:201], v[24:27]
	v_mfma_f32_16x16x32_bf16 v[12:15], v[52:55], v[206:209], v[12:15]
	v_mfma_f32_16x16x32_bf16 v[8:11], v[64:67], v[206:209], v[8:11]
	v_mfma_f32_16x16x32_bf16 v[4:7], v[52:55], v[214:217], v[4:7]
	v_mfma_f32_16x16x32_bf16 v[0:3], v[64:67], v[214:217], v[0:3]
	v_mfma_f32_16x16x32_bf16 v[20:23], v[72:75], v[194:197], 0
	v_mfma_f32_16x16x32_bf16 v[16:19], v[84:87], v[194:197], 0
	v_mfma_f32_16x16x32_bf16 v[44:47], v[72:75], v[202:205], 0
	v_mfma_f32_16x16x32_bf16 v[40:43], v[84:87], v[202:205], 0
	v_mfma_f32_16x16x32_bf16 v[36:39], v[72:75], v[210:213], 0
	v_mfma_f32_16x16x32_bf16 v[32:35], v[84:87], v[210:213], 0
	v_mfma_f32_16x16x32_bf16 v[48:51], v[72:75], v[148:151], 0
	v_mfma_f32_16x16x32_bf16 v[52:55], v[84:87], v[148:151], 0
	v_mfma_f32_16x16x32_bf16 v[20:23], v[80:83], v[198:201], v[20:23]
	v_mfma_f32_16x16x32_bf16 v[16:19], v[92:95], v[198:201], v[16:19]
	v_mfma_f32_16x16x32_bf16 v[44:47], v[80:83], v[206:209], v[44:47]
	v_mfma_f32_16x16x32_bf16 v[40:43], v[92:95], v[206:209], v[40:43]
	v_mfma_f32_16x16x32_bf16 v[36:39], v[80:83], v[214:217], v[36:39]
	v_mfma_f32_16x16x32_bf16 v[32:35], v[92:95], v[214:217], v[32:35]
	v_mfma_f32_16x16x32_bf16 v[48:51], v[80:83], v[164:167], v[48:51]
	v_mfma_f32_16x16x32_bf16 v[52:55], v[92:95], v[164:167], v[52:55]
	s_barrier
	s_setprio 0
	s_add_i32 s13, 0, 0x18000
	s_add_i32 s60, 0, 0x1c000
	v_add_u32_e32 v68, s13, v228
	v_add_u32_e32 v92, s60, v228
	ds_read_b128 v[56:59], v68
	ds_read_b128 v[60:63], v68 offset:1024
	ds_read_b128 v[64:67], v68 offset:2048
	ds_read_b128 v[68:71], v68 offset:3072
	ds_read_b128 v[72:75], v92
	ds_read_b128 v[80:83], v92 offset:1024
	ds_read_b128 v[84:87], v92 offset:2048
	ds_read_b128 v[92:95], v92 offset:3072
	s_add_u32 s0, s66, 0x40000
	s_addc_u32 s1, s67, 0
	s_mov_b32 m0, s39
	ds_read_b128 v[148:151], v230 offset:32768
	ds_read_b128 v[164:167], v230 offset:33792
	ds_read_b128 v[194:197], v230 offset:34816
	ds_read_b128 v[198:201], v230 offset:35840
	ds_read_b128 v[202:205], v230 offset:36864
	ds_read_b128 v[206:209], v230 offset:37888
	ds_read_b128 v[210:213], v230 offset:38912
	ds_read_b128 v[214:217], v230 offset:39936
	global_load_lds_dwordx4 v184, s[0:1]
	s_mov_b32 m0, s76
	s_nop 0
	global_load_lds_dwordx4 v186, s[0:1]
	s_mov_b32 m0, s59
	s_nop 0
	global_load_lds_dwordx4 v[234:235], off
	s_mov_b32 m0, s97
	s_nop 0
	global_load_lds_dwordx4 v[236:237], off
	s_waitcnt vmcnt(8)
	s_waitcnt lgkmcnt(0)
	s_setprio 1
	s_barrier
	v_mfma_f32_16x16x32_bf16 v[160:163], v[56:59], v[148:151], v[160:163]
	v_mfma_f32_16x16x32_bf16 v[156:159], v[64:67], v[148:151], v[156:159]
	v_mfma_f32_16x16x32_bf16 v[128:131], v[56:59], v[194:197], v[128:131]
	v_mfma_f32_16x16x32_bf16 v[124:127], v[64:67], v[194:197], v[124:127]
	v_mfma_f32_16x16x32_bf16 v[108:111], v[56:59], v[202:205], v[108:111]
	v_mfma_f32_16x16x32_bf16 v[104:107], v[64:67], v[202:205], v[104:107]
	v_mfma_f32_16x16x32_bf16 v[100:103], v[56:59], v[210:213], v[100:103]
	v_mfma_f32_16x16x32_bf16 v[96:99], v[64:67], v[210:213], v[96:99]
	v_mfma_f32_16x16x32_bf16 v[160:163], v[60:63], v[164:167], v[160:163]
	v_mfma_f32_16x16x32_bf16 v[156:159], v[68:71], v[164:167], v[156:159]
	v_mfma_f32_16x16x32_bf16 v[128:131], v[60:63], v[198:201], v[128:131]
	v_mfma_f32_16x16x32_bf16 v[124:127], v[68:71], v[198:201], v[124:127]
	v_mfma_f32_16x16x32_bf16 v[108:111], v[60:63], v[206:209], v[108:111]
	v_mfma_f32_16x16x32_bf16 v[104:107], v[68:71], v[206:209], v[104:107]
	v_mfma_f32_16x16x32_bf16 v[100:103], v[60:63], v[214:217], v[100:103]
	v_mfma_f32_16x16x32_bf16 v[96:99], v[68:71], v[214:217], v[96:99]
	v_mfma_f32_16x16x32_bf16 v[112:115], v[84:87], v[148:151], v[112:115]
	v_mfma_f32_16x16x32_bf16 v[152:155], v[72:75], v[148:151], v[152:155]
	v_mfma_f32_16x16x32_bf16 v[148:151], v[92:95], v[164:167], v[112:115]
	v_mfma_f32_16x16x32_bf16 v[112:115], v[72:75], v[194:197], v[120:123]
	v_mfma_f32_16x16x32_bf16 v[120:123], v[80:83], v[198:201], v[112:115]
	v_mfma_f32_16x16x32_bf16 v[112:115], v[84:87], v[194:197], v[116:119]
	v_mfma_f32_16x16x32_bf16 v[116:119], v[92:95], v[198:201], v[112:115]
	v_mfma_f32_16x16x32_bf16 v[112:115], v[72:75], v[202:205], v[144:147]
	v_mfma_f32_16x16x32_bf16 v[144:147], v[80:83], v[206:209], v[112:115]
	v_mfma_f32_16x16x32_bf16 v[112:115], v[84:87], v[202:205], v[140:143]
	v_mfma_f32_16x16x32_bf16 v[140:143], v[92:95], v[206:209], v[112:115]
	v_mfma_f32_16x16x32_bf16 v[112:115], v[72:75], v[210:213], v[136:139]
	v_mfma_f32_16x16x32_bf16 v[136:139], v[80:83], v[214:217], v[112:115]
	v_mfma_f32_16x16x32_bf16 v[112:115], v[84:87], v[210:213], v[132:135]
	v_mfma_f32_16x16x32_bf16 v[152:155], v[80:83], v[164:167], v[152:155]
	v_mfma_f32_16x16x32_bf16 v[132:135], v[92:95], v[214:217], v[112:115]
	s_barrier
	s_setprio 0
	s_add_i32 s0, s13, s96
	v_lshl_add_u64 v[218:219], v[218:219], 0, s[16:17]
	s_mov_b32 m0, s0
	s_nop 0
	ds_read_b128 v[112:115], v230 offset:49152
	ds_read_b128 v[164:167], v230 offset:50176
	ds_read_b128 v[194:197], v230 offset:51200
	ds_read_b128 v[198:201], v230 offset:52224
	ds_read_b128 v[202:205], v230 offset:53248
	ds_read_b128 v[206:209], v230 offset:54272
	ds_read_b128 v[210:213], v230 offset:55296
	ds_read_b128 v[214:217], v230 offset:56320
	global_load_lds_dwordx4 v[218:219], off
	s_add_i32 m0, s0, 0x2000
	s_add_u32 s0, s64, 0x40080
	v_lshl_add_u64 v[218:219], v[232:233], 0, s[16:17]
	s_addc_u32 s1, s65, 0
	s_add_i32 s13, s60, s96
	global_load_lds_dwordx4 v[218:219], off
	s_mov_b32 m0, s13
	s_nop 0
	global_load_lds_dwordx4 v170, s[0:1]
	s_add_i32 m0, s13, 0x2000
	s_nop 0
	global_load_lds_dwordx4 v188, s[0:1]
	v_lshl_add_u64 v[218:219], v[234:235], 0, s[16:17]
	s_mov_b32 m0, s75
	s_nop 0
	global_load_lds_dwordx4 v[218:219], off
	v_lshl_add_u64 v[218:219], v[236:237], 0, s[16:17]
	s_mov_b32 m0, s91
	s_nop 0
	global_load_lds_dwordx4 v[218:219], off
	s_waitcnt vmcnt(6)
	s_waitcnt lgkmcnt(0)
	s_setprio 1
	s_barrier
	v_mfma_f32_16x16x32_bf16 v[88:91], v[56:59], v[112:115], v[88:91]
	v_mfma_f32_16x16x32_bf16 v[76:79], v[64:67], v[112:115], v[76:79]
	v_mfma_f32_16x16x32_bf16 v[28:31], v[56:59], v[194:197], v[28:31]
	v_mfma_f32_16x16x32_bf16 v[24:27], v[64:67], v[194:197], v[24:27]
	v_mfma_f32_16x16x32_bf16 v[12:15], v[56:59], v[202:205], v[12:15]
	v_mfma_f32_16x16x32_bf16 v[8:11], v[64:67], v[202:205], v[8:11]
	v_mfma_f32_16x16x32_bf16 v[4:7], v[56:59], v[210:213], v[4:7]
	v_mfma_f32_16x16x32_bf16 v[0:3], v[64:67], v[210:213], v[0:3]
	v_mfma_f32_16x16x32_bf16 v[88:91], v[60:63], v[164:167], v[88:91]
	v_mfma_f32_16x16x32_bf16 v[76:79], v[68:71], v[164:167], v[76:79]
	v_mfma_f32_16x16x32_bf16 v[28:31], v[60:63], v[198:201], v[28:31]
	v_mfma_f32_16x16x32_bf16 v[24:27], v[68:71], v[198:201], v[24:27]
	v_mfma_f32_16x16x32_bf16 v[12:15], v[60:63], v[206:209], v[12:15]
	v_mfma_f32_16x16x32_bf16 v[8:11], v[68:71], v[206:209], v[8:11]
	v_mfma_f32_16x16x32_bf16 v[4:7], v[60:63], v[214:217], v[4:7]
	v_mfma_f32_16x16x32_bf16 v[0:3], v[68:71], v[214:217], v[0:3]
	v_mfma_f32_16x16x32_bf16 v[48:51], v[72:75], v[112:115], v[48:51]
	v_mfma_f32_16x16x32_bf16 v[68:71], v[80:83], v[164:167], v[48:51]
	v_mfma_f32_16x16x32_bf16 v[48:51], v[84:87], v[112:115], v[52:55]
	v_mfma_f32_16x16x32_bf16 v[20:23], v[72:75], v[194:197], v[20:23]
	v_mfma_f32_16x16x32_bf16 v[16:19], v[84:87], v[194:197], v[16:19]
	v_mfma_f32_16x16x32_bf16 v[44:47], v[72:75], v[202:205], v[44:47]
	v_mfma_f32_16x16x32_bf16 v[40:43], v[84:87], v[202:205], v[40:43]
	v_mfma_f32_16x16x32_bf16 v[36:39], v[72:75], v[210:213], v[36:39]
	v_mfma_f32_16x16x32_bf16 v[32:35], v[84:87], v[210:213], v[32:35]
	v_mfma_f32_16x16x32_bf16 v[56:59], v[92:95], v[164:167], v[48:51]
	v_mfma_f32_16x16x32_bf16 v[20:23], v[80:83], v[198:201], v[20:23]
	v_mfma_f32_16x16x32_bf16 v[16:19], v[92:95], v[198:201], v[16:19]
	v_mfma_f32_16x16x32_bf16 v[44:47], v[80:83], v[206:209], v[44:47]
	v_mfma_f32_16x16x32_bf16 v[40:43], v[92:95], v[206:209], v[40:43]
	v_mfma_f32_16x16x32_bf16 v[36:39], v[80:83], v[214:217], v[36:39]
	v_mfma_f32_16x16x32_bf16 v[32:35], v[92:95], v[214:217], v[32:35]
	s_barrier
	s_setprio 0
	s_add_i32 s12, s12, 2
	s_add_u32 vcc_lo, vcc_lo, 0x100
	s_addc_u32 vcc_hi, vcc_hi, 0
	s_cmp_gt_u32 s12, 13
	s_mov_b64 s[60:61], s[62:63]

.LBB0_1015:
	s_lshl_b32 s13, s13, 5
	s_and_b32 s13, s13, 0x60
	s_add_i32 m0, s43, 0x18000
	v_lshl_add_u64 v[10:11], v[10:11], 0, s[16:17]
	s_lshl_b32 s26, s1, 13
	s_lshl_b32 s27, s13, 7
	s_waitcnt vmcnt(2)
	s_barrier
	global_load_lds_dwordx4 v[10:11], off
	v_lshl_add_u64 v[8:9], v[8:9], 0, s[16:17]
	s_add_i32 m0, s43, 0x1a000
	s_add_i32 s47, s43, 0x8000
	s_add_i32 s48, s43, 0xa000
	global_load_lds_dwordx4 v[8:9], off
	v_lshl_add_u64 v[4:5], v[4:5], 0, s[16:17]
	s_mov_b32 m0, s47
	s_add_u32 s24, s34, 0xb0080
	global_load_lds_dwordx4 v[4:5], off
	v_lshl_add_u64 v[4:5], v[6:7], 0, s[16:17]
	s_mov_b32 m0, s48
	s_addc_u32 s25, s35, 0
	global_load_lds_dwordx4 v[4:5], off
	s_add_i32 m0, s43, 0x1c000
	v_lshl_add_u64 v[4:5], s[24:25], 0, v[170:171]
	global_load_lds_dwordx4 v[4:5], off
	v_lshl_add_u64 v[4:5], s[24:25], 0, v[136:137]
	s_add_i32 m0, s43, 0x1e000
	s_cmpk_lt_u32 s0, 0x100
	global_load_lds_dwordx4 v[4:5], off
	v_lshrrev_b32_e32 v4, 1, v1
	v_and_b32_e32 v6, 24, v4
	v_and_b32_e32 v5, 15, v1
	v_lshlrev_b32_e32 v4, 1, v6
	v_lshlrev_b32_e32 v1, 2, v1
	s_cselect_b64 s[24:25], -1, 0
	s_lshl_b32 s0, s13, 1
	v_lshl_or_b32 v152, s1, 6, v5
	v_lshl_or_b32 v5, v5, 6, v4
	v_and_b32_e32 v1, 32, v1
	s_add_u32 s0, s6, s0
	v_bitop3_b32 v7, v5, s26, v1 bitop3:0xde
	v_bitop3_b32 v153, v5, s27, v1 bitop3:0xde
	s_addc_u32 s1, s7, 0
	v_mov_b32_e32 v5, v171
	v_lshl_add_u64 v[4:5], s[0:1], 0, v[4:5]
	s_mov_b64 s[0:1], 0x10000000
	v_lshl_add_u64 v[138:139], v[4:5], 0, s[0:1]
	s_lshl_b32 s0, s13, 2
	s_add_u32 s0, s4, s0
	s_addc_u32 s1, s5, 0
	v_lshlrev_b32_e32 v4, 2, v6
	v_mov_b32_e32 v5, v171
	v_lshl_add_u64 v[140:141], s[0:1], 0, v[4:5]
	v_lshrrev_b32_e32 v1, 1, v3
	v_mul_lo_u32 v4, v12, s88
	s_mov_b32 s4, 0x16000
	v_mad_u64_u32 v[4:5], s[0:1], v1, s4, v[4:5]
	v_add3_u32 v0, v4, v0, v13
	v_mov_b32_e32 v1, v171
	s_mov_b64 s[6:7], 0xb0080
	v_lshl_add_u64 v[142:143], v[0:1], 0, s[6:7]
	v_lshrrev_b32_e32 v1, 1, v14
	v_mul_lo_u32 v0, v15, s88
	s_waitcnt vmcnt(6)
	s_mov_b32 s99, 1
	v_mad_u64_u32 v[0:1], s[0:1], v1, s4, v[0:1]
	v_add3_u32 v0, v0, v2, v16
	v_mov_b32_e32 v1, v171
	s_sext_i32_i8 s53, s12
	v_lshl_add_u64 v[144:145], v[0:1], 0, s[6:7]
	s_mov_b32 s49, 0
	v_add_u32_e32 v154, 0, v7
	s_barrier
	s_branch .LBB0_1018

.Lrestag_1029:
	s_add_u32 s34, s30, 0x100
	s_addc_u32 s35, s31, 0
	s_add_i32 s0, 0, 0x10000
	s_cmp_eq_u32 s12, 40
	s_cselect_b32 s41, s7, s35
	s_cselect_b32 s40, s6, s34
	v_add_u32_e32 v150, s0, v153
	s_cselect_b32 s37, s27, s55
	s_cselect_b32 s36, s26, s54
	s_add_i32 s13, 0, 0x14000
	ds_read_b128 v[128:131], v150
	ds_read_b128 v[146:149], v150 offset:1024
	ds_read_b128 v[156:159], v150 offset:2048
	ds_read_b128 v[160:163], v150 offset:3072
	v_add_u32_e32 v150, s13, v153
	ds_read_b128 v[164:167], v150
	ds_read_b128 v[184:187], v150 offset:1024
	ds_read_b128 v[188:191], v150 offset:2048
	ds_read_b128 v[192:195], v150 offset:3072
	s_add_i32 m0, s43, 0xc000
	ds_read_b128 v[196:199], v154
	ds_read_b128 v[200:203], v154 offset:1024
	ds_read_b128 v[204:207], v154 offset:2048
	ds_read_b128 v[208:211], v154 offset:3072
	ds_read_b128 v[212:215], v154 offset:4096
	ds_read_b128 v[216:219], v154 offset:5120
	ds_read_b128 v[228:231], v154 offset:6144
	ds_read_b128 v[232:235], v154 offset:7168
	global_load_lds_dwordx4 v142, s[30:31]
	s_add_i32 m0, s43, 0xe000
	s_nop 0
	global_load_lds_dwordx4 v144, s[30:31]
	s_nop 0
	s_waitcnt lgkmcnt(0)
	s_setprio 1
	s_barrier
	v_mfma_f32_16x16x32_bf16 v[124:127], v[128:131], v[196:199], 0
	v_mfma_f32_16x16x32_bf16 v[120:123], v[156:159], v[196:199], 0
	v_mfma_f32_16x16x32_bf16 v[112:115], v[128:131], v[204:207], 0
	v_mfma_f32_16x16x32_bf16 v[104:107], v[156:159], v[204:207], 0
	v_mfma_f32_16x16x32_bf16 v[96:99], v[128:131], v[212:215], 0
	v_mfma_f32_16x16x32_bf16 v[88:91], v[156:159], v[212:215], 0
	v_mfma_f32_16x16x32_bf16 v[80:83], v[128:131], v[228:231], 0
	v_mfma_f32_16x16x32_bf16 v[72:75], v[156:159], v[228:231], 0
	v_mfma_f32_16x16x32_bf16 v[124:127], v[146:149], v[200:203], v[124:127]
	v_mfma_f32_16x16x32_bf16 v[120:123], v[160:163], v[200:203], v[120:123]
	v_mfma_f32_16x16x32_bf16 v[112:115], v[146:149], v[208:211], v[112:115]
	v_mfma_f32_16x16x32_bf16 v[104:107], v[160:163], v[208:211], v[104:107]
	v_mfma_f32_16x16x32_bf16 v[96:99], v[146:149], v[216:219], v[96:99]
	v_mfma_f32_16x16x32_bf16 v[88:91], v[160:163], v[216:219], v[88:91]
	v_mfma_f32_16x16x32_bf16 v[80:83], v[146:149], v[232:235], v[80:83]
	v_mfma_f32_16x16x32_bf16 v[72:75], v[160:163], v[232:235], v[72:75]
	v_mfma_f32_16x16x32_bf16 v[116:119], v[164:167], v[196:199], 0
	v_mfma_f32_16x16x32_bf16 v[108:111], v[188:191], v[196:199], 0
	v_mfma_f32_16x16x32_bf16 v[100:103], v[164:167], v[204:207], 0
	v_mfma_f32_16x16x32_bf16 v[92:95], v[188:191], v[204:207], 0
	v_mfma_f32_16x16x32_bf16 v[84:87], v[164:167], v[212:215], 0
	v_mfma_f32_16x16x32_bf16 v[76:79], v[188:191], v[212:215], 0
	v_mfma_f32_16x16x32_bf16 v[68:71], v[164:167], v[228:231], 0
	v_mfma_f32_16x16x32_bf16 v[64:67], v[188:191], v[228:231], 0
	v_mfma_f32_16x16x32_bf16 v[116:119], v[184:187], v[200:203], v[116:119]
	v_mfma_f32_16x16x32_bf16 v[108:111], v[192:195], v[200:203], v[108:111]
	v_mfma_f32_16x16x32_bf16 v[100:103], v[184:187], v[208:211], v[100:103]
	v_mfma_f32_16x16x32_bf16 v[92:95], v[192:195], v[208:211], v[92:95]
	v_mfma_f32_16x16x32_bf16 v[84:87], v[184:187], v[216:219], v[84:87]
	v_mfma_f32_16x16x32_bf16 v[76:79], v[192:195], v[216:219], v[76:79]
	v_mfma_f32_16x16x32_bf16 v[68:71], v[184:187], v[232:235], v[68:71]
	v_mfma_f32_16x16x32_bf16 v[64:67], v[192:195], v[232:235], v[64:67]
	s_barrier
	s_setprio 0
	s_add_i32 s0, s0, s42
	v_lshl_add_u64 v[150:151], s[36:37], 0, v[170:171]
	s_mov_b32 m0, s0
	ds_read_b128 v[196:199], v154 offset:16384
	ds_read_b128 v[200:203], v154 offset:17408
	ds_read_b128 v[204:207], v154 offset:18432
	ds_read_b128 v[208:211], v154 offset:19456
	ds_read_b128 v[212:215], v154 offset:20480
	ds_read_b128 v[216:219], v154 offset:21504
	ds_read_b128 v[228:231], v154 offset:22528
	ds_read_b128 v[232:235], v154 offset:23552
	global_load_lds_dwordx4 v[150:151], off
	s_add_i32 m0, s0, 0x2000
	s_add_u32 s0, s36, 0xb0000
	v_lshl_add_u64 v[236:237], s[36:37], 0, v[136:137]
	s_addc_u32 s1, s37, 0
	s_add_i32 s13, s13, s42
	global_load_lds_dwordx4 v[236:237], off
	s_mov_b32 m0, s13
	v_lshl_add_u64 v[240:241], s[40:41], 0, v[134:135]
	global_load_lds_dwordx4 v170, s[0:1]
	s_add_i32 m0, s13, 0x2000
	s_nop 0
	global_load_lds_dwordx4 v136, s[0:1]
	v_lshl_add_u64 v[238:239], s[40:41], 0, v[132:133]
	s_cmp_eq_u32 s99, 1
	s_cbranch_scc0 .Lft_1029
	s_waitcnt vmcnt(6)
	s_mov_b32 s99, 0
.Lft_1029:
	s_waitcnt lgkmcnt(0)
	s_setprio 1
	s_barrier
	v_mfma_f32_16x16x32_bf16 v[60:63], v[128:131], v[196:199], 0
	v_mfma_f32_16x16x32_bf16 v[56:59], v[156:159], v[196:199], 0
	v_mfma_f32_16x16x32_bf16 v[48:51], v[128:131], v[204:207], 0
	v_mfma_f32_16x16x32_bf16 v[40:43], v[156:159], v[204:207], 0
	v_mfma_f32_16x16x32_bf16 v[32:35], v[128:131], v[212:215], 0
	v_mfma_f32_16x16x32_bf16 v[24:27], v[156:159], v[212:215], 0
	v_mfma_f32_16x16x32_bf16 v[16:19], v[128:131], v[228:231], 0
	v_mfma_f32_16x16x32_bf16 v[8:11], v[156:159], v[228:231], 0
	v_mfma_f32_16x16x32_bf16 v[60:63], v[146:149], v[200:203], v[60:63]
	v_mfma_f32_16x16x32_bf16 v[56:59], v[160:163], v[200:203], v[56:59]
	v_mfma_f32_16x16x32_bf16 v[48:51], v[146:149], v[208:211], v[48:51]
	v_mfma_f32_16x16x32_bf16 v[40:43], v[160:163], v[208:211], v[40:43]
	v_mfma_f32_16x16x32_bf16 v[32:35], v[146:149], v[216:219], v[32:35]
	v_mfma_f32_16x16x32_bf16 v[24:27], v[160:163], v[216:219], v[24:27]
	v_mfma_f32_16x16x32_bf16 v[16:19], v[146:149], v[232:235], v[16:19]
	v_mfma_f32_16x16x32_bf16 v[8:11], v[160:163], v[232:235], v[8:11]
	v_mfma_f32_16x16x32_bf16 v[52:55], v[164:167], v[196:199], 0
	v_mfma_f32_16x16x32_bf16 v[44:47], v[188:191], v[196:199], 0
	v_mfma_f32_16x16x32_bf16 v[36:39], v[164:167], v[204:207], 0
	v_mfma_f32_16x16x32_bf16 v[28:31], v[188:191], v[204:207], 0
	v_mfma_f32_16x16x32_bf16 v[20:23], v[164:167], v[212:215], 0
	v_mfma_f32_16x16x32_bf16 v[12:15], v[188:191], v[212:215], 0
	v_mfma_f32_16x16x32_bf16 v[4:7], v[164:167], v[228:231], 0
	v_mfma_f32_16x16x32_bf16 v[0:3], v[188:191], v[228:231], 0
	v_mfma_f32_16x16x32_bf16 v[52:55], v[184:187], v[200:203], v[52:55]
	v_mfma_f32_16x16x32_bf16 v[44:47], v[192:195], v[200:203], v[44:47]
	v_mfma_f32_16x16x32_bf16 v[36:39], v[184:187], v[208:211], v[36:39]
	v_mfma_f32_16x16x32_bf16 v[28:31], v[192:195], v[208:211], v[28:31]
	v_mfma_f32_16x16x32_bf16 v[20:23], v[184:187], v[216:219], v[20:23]
	v_mfma_f32_16x16x32_bf16 v[12:15], v[192:195], v[216:219], v[12:15]
	v_mfma_f32_16x16x32_bf16 v[4:7], v[184:187], v[232:235], v[4:7]
	v_mfma_f32_16x16x32_bf16 v[0:3], v[192:195], v[232:235], v[0:3]
	s_barrier
	s_setprio 0
	s_add_i32 s13, 0, 0x18000
	v_add_u32_e32 v155, s13, v153
	s_add_i32 s30, 0, 0x1c000
	ds_read_b128 v[128:131], v155
	ds_read_b128 v[146:149], v155 offset:1024
	ds_read_b128 v[156:159], v155 offset:2048
	ds_read_b128 v[160:163], v155 offset:3072
	v_add_u32_e32 v155, s30, v153
	ds_read_b128 v[164:167], v155
	ds_read_b128 v[184:187], v155 offset:1024
	ds_read_b128 v[188:191], v155 offset:2048
	ds_read_b128 v[192:195], v155 offset:3072
	s_add_u32 s0, s40, 0xb0000
	s_addc_u32 s1, s41, 0
	s_mov_b32 m0, s45
	ds_read_b128 v[196:199], v154 offset:32768
	ds_read_b128 v[200:203], v154 offset:33792
	ds_read_b128 v[204:207], v154 offset:34816
	ds_read_b128 v[208:211], v154 offset:35840
	ds_read_b128 v[212:215], v154 offset:36864
	ds_read_b128 v[216:219], v154 offset:37888
	ds_read_b128 v[228:231], v154 offset:38912
	ds_read_b128 v[232:235], v154 offset:39936
	global_load_lds_dwordx4 v132, s[0:1]
	s_mov_b32 m0, s46
	s_nop 0
	global_load_lds_dwordx4 v134, s[0:1]
	s_mov_b32 m0, s43
	s_nop 0
	global_load_lds_dwordx4 v[238:239], off
	s_mov_b32 m0, s44
	s_nop 0
	global_load_lds_dwordx4 v[240:241], off
	s_waitcnt vmcnt(8)
	s_waitcnt lgkmcnt(0)
	s_setprio 1
	s_barrier
	v_mfma_f32_16x16x32_bf16 v[124:127], v[128:131], v[196:199], v[124:127]
	v_mfma_f32_16x16x32_bf16 v[120:123], v[156:159], v[196:199], v[120:123]
	v_mfma_f32_16x16x32_bf16 v[112:115], v[128:131], v[204:207], v[112:115]
	v_mfma_f32_16x16x32_bf16 v[104:107], v[156:159], v[204:207], v[104:107]
	v_mfma_f32_16x16x32_bf16 v[96:99], v[128:131], v[212:215], v[96:99]
	v_mfma_f32_16x16x32_bf16 v[88:91], v[156:159], v[212:215], v[88:91]
	v_mfma_f32_16x16x32_bf16 v[80:83], v[128:131], v[228:231], v[80:83]
	v_mfma_f32_16x16x32_bf16 v[72:75], v[156:159], v[228:231], v[72:75]
	v_mfma_f32_16x16x32_bf16 v[124:127], v[146:149], v[200:203], v[124:127]
	v_mfma_f32_16x16x32_bf16 v[120:123], v[160:163], v[200:203], v[120:123]
	v_mfma_f32_16x16x32_bf16 v[112:115], v[146:149], v[208:211], v[112:115]
	v_mfma_f32_16x16x32_bf16 v[104:107], v[160:163], v[208:211], v[104:107]
	v_mfma_f32_16x16x32_bf16 v[96:99], v[146:149], v[216:219], v[96:99]
	v_mfma_f32_16x16x32_bf16 v[88:91], v[160:163], v[216:219], v[88:91]
	v_mfma_f32_16x16x32_bf16 v[80:83], v[146:149], v[232:235], v[80:83]
	v_mfma_f32_16x16x32_bf16 v[72:75], v[160:163], v[232:235], v[72:75]
	v_mfma_f32_16x16x32_bf16 v[116:119], v[164:167], v[196:199], v[116:119]
	v_mfma_f32_16x16x32_bf16 v[108:111], v[188:191], v[196:199], v[108:111]
	v_mfma_f32_16x16x32_bf16 v[100:103], v[164:167], v[204:207], v[100:103]
	v_mfma_f32_16x16x32_bf16 v[92:95], v[188:191], v[204:207], v[92:95]
	v_mfma_f32_16x16x32_bf16 v[84:87], v[164:167], v[212:215], v[84:87]
	v_mfma_f32_16x16x32_bf16 v[76:79], v[188:191], v[212:215], v[76:79]
	v_mfma_f32_16x16x32_bf16 v[68:71], v[164:167], v[228:231], v[68:71]
	v_mfma_f32_16x16x32_bf16 v[64:67], v[188:191], v[228:231], v[64:67]
	v_mfma_f32_16x16x32_bf16 v[116:119], v[184:187], v[200:203], v[116:119]
	v_mfma_f32_16x16x32_bf16 v[108:111], v[192:195], v[200:203], v[108:111]
	v_mfma_f32_16x16x32_bf16 v[100:103], v[184:187], v[208:211], v[100:103]
	v_mfma_f32_16x16x32_bf16 v[92:95], v[192:195], v[208:211], v[92:95]
	v_mfma_f32_16x16x32_bf16 v[84:87], v[184:187], v[216:219], v[84:87]
	v_mfma_f32_16x16x32_bf16 v[76:79], v[192:195], v[216:219], v[76:79]
	v_mfma_f32_16x16x32_bf16 v[68:71], v[184:187], v[232:235], v[68:71]
	v_mfma_f32_16x16x32_bf16 v[64:67], v[192:195], v[232:235], v[64:67]
	s_barrier
	s_setprio 0
	s_add_i32 s0, s13, s42
	v_lshl_add_u64 v[150:151], v[150:151], 0, s[16:17]
	s_mov_b32 m0, s0
	ds_read_b128 v[196:199], v154 offset:49152
	ds_read_b128 v[200:203], v154 offset:50176
	ds_read_b128 v[204:207], v154 offset:51200
	ds_read_b128 v[208:211], v154 offset:52224
	ds_read_b128 v[212:215], v154 offset:53248
	ds_read_b128 v[216:219], v154 offset:54272
	ds_read_b128 v[228:231], v154 offset:55296
	ds_read_b128 v[232:235], v154 offset:56320
	global_load_lds_dwordx4 v[150:151], off
	s_add_i32 m0, s0, 0x2000
	s_add_u32 s0, s36, 0xb0080
	v_lshl_add_u64 v[150:151], v[236:237], 0, s[16:17]
	s_addc_u32 s1, s37, 0
	s_add_i32 s13, s30, s42
	global_load_lds_dwordx4 v[150:151], off
	s_mov_b32 m0, s13
	s_nop 0
	global_load_lds_dwordx4 v170, s[0:1]
	s_add_i32 m0, s13, 0x2000
	s_nop 0
	global_load_lds_dwordx4 v136, s[0:1]
	v_lshl_add_u64 v[150:151], v[238:239], 0, s[16:17]
	s_mov_b32 m0, s47
	s_nop 0
	global_load_lds_dwordx4 v[150:151], off
	v_lshl_add_u64 v[150:151], v[240:241], 0, s[16:17]
	s_mov_b32 m0, s48
	s_nop 0
	global_load_lds_dwordx4 v[150:151], off
	s_waitcnt vmcnt(6)
	s_waitcnt lgkmcnt(0)
	s_setprio 1
	s_barrier
	v_mfma_f32_16x16x32_bf16 v[60:63], v[128:131], v[196:199], v[60:63]
	v_mfma_f32_16x16x32_bf16 v[56:59], v[156:159], v[196:199], v[56:59]
	v_mfma_f32_16x16x32_bf16 v[48:51], v[128:131], v[204:207], v[48:51]
	v_mfma_f32_16x16x32_bf16 v[40:43], v[156:159], v[204:207], v[40:43]
	v_mfma_f32_16x16x32_bf16 v[32:35], v[128:131], v[212:215], v[32:35]
	v_mfma_f32_16x16x32_bf16 v[24:27], v[156:159], v[212:215], v[24:27]
	v_mfma_f32_16x16x32_bf16 v[16:19], v[128:131], v[228:231], v[16:19]
	v_mfma_f32_16x16x32_bf16 v[8:11], v[156:159], v[228:231], v[8:11]
	v_mfma_f32_16x16x32_bf16 v[60:63], v[146:149], v[200:203], v[60:63]
	v_mfma_f32_16x16x32_bf16 v[56:59], v[160:163], v[200:203], v[56:59]
	v_mfma_f32_16x16x32_bf16 v[48:51], v[146:149], v[208:211], v[48:51]
	v_mfma_f32_16x16x32_bf16 v[40:43], v[160:163], v[208:211], v[40:43]
	v_mfma_f32_16x16x32_bf16 v[32:35], v[146:149], v[216:219], v[32:35]
	v_mfma_f32_16x16x32_bf16 v[24:27], v[160:163], v[216:219], v[24:27]
	v_mfma_f32_16x16x32_bf16 v[16:19], v[146:149], v[232:235], v[16:19]
	v_mfma_f32_16x16x32_bf16 v[8:11], v[160:163], v[232:235], v[8:11]
	v_mfma_f32_16x16x32_bf16 v[52:55], v[164:167], v[196:199], v[52:55]
	v_mfma_f32_16x16x32_bf16 v[44:47], v[188:191], v[196:199], v[44:47]
	v_mfma_f32_16x16x32_bf16 v[36:39], v[164:167], v[204:207], v[36:39]
	v_mfma_f32_16x16x32_bf16 v[28:31], v[188:191], v[204:207], v[28:31]
	v_mfma_f32_16x16x32_bf16 v[20:23], v[164:167], v[212:215], v[20:23]
	v_mfma_f32_16x16x32_bf16 v[12:15], v[188:191], v[212:215], v[12:15]
	v_mfma_f32_16x16x32_bf16 v[4:7], v[164:167], v[228:231], v[4:7]
	v_mfma_f32_16x16x32_bf16 v[0:3], v[188:191], v[228:231], v[0:3]
	v_mfma_f32_16x16x32_bf16 v[52:55], v[184:187], v[200:203], v[52:55]
	v_mfma_f32_16x16x32_bf16 v[44:47], v[192:195], v[200:203], v[44:47]
	v_mfma_f32_16x16x32_bf16 v[36:39], v[184:187], v[208:211], v[36:39]
	v_mfma_f32_16x16x32_bf16 v[28:31], v[192:195], v[208:211], v[28:31]
	v_mfma_f32_16x16x32_bf16 v[20:23], v[184:187], v[216:219], v[20:23]
	v_mfma_f32_16x16x32_bf16 v[12:15], v[192:195], v[216:219], v[12:15]
	v_mfma_f32_16x16x32_bf16 v[4:7], v[184:187], v[232:235], v[4:7]
	v_mfma_f32_16x16x32_bf16 v[0:3], v[192:195], v[232:235], v[0:3]
	s_barrier
	s_setprio 0
	s_add_i32 s12, s12, 2
	s_add_u32 s54, s54, 0x100
	s_addc_u32 s55, s55, 0
	s_cmp_gt_u32 s12, 41
	s_mov_b64 s[30:31], s[34:35]

.LBB0_1047:
	s_add_u32 s26, s4, 0x180000
	s_addc_u32 s27, s5, 0
	s_lshl_b32 s6, s6, 5
	s_and_b32 s9, s6, 0x60
	s_add_i32 m0, s47, 0x18000
	v_lshl_add_u64 v[10:11], v[10:11], 0, s[16:17]
	s_lshl_b32 s8, s1, 13
	s_lshl_b32 s12, s9, 7
	s_waitcnt vmcnt(2)
	s_barrier
	global_load_lds_dwordx4 v[10:11], off
	v_lshl_add_u64 v[8:9], v[8:9], 0, s[16:17]
	s_add_i32 m0, s47, 0x1a000
	s_add_i32 s51, s47, 0x8000
	s_add_i32 s52, s47, 0xa000
	global_load_lds_dwordx4 v[8:9], off
	v_lshl_add_u64 v[4:5], v[4:5], 0, s[16:17]
	s_mov_b32 m0, s51
	s_add_u32 s6, s40, 0xb0080
	global_load_lds_dwordx4 v[4:5], off
	v_lshl_add_u64 v[4:5], v[6:7], 0, s[16:17]
	s_mov_b32 m0, s52
	s_addc_u32 s7, s41, 0
	global_load_lds_dwordx4 v[4:5], off
	s_add_i32 m0, s47, 0x1c000
	v_lshl_add_u64 v[4:5], s[6:7], 0, v[170:171]
	global_load_lds_dwordx4 v[4:5], off
	v_lshl_add_u64 v[4:5], s[6:7], 0, v[156:157]
	s_add_i32 m0, s47, 0x1e000
	v_bfe_u32 v6, v1, 4, 2
	global_load_lds_dwordx4 v[4:5], off
	s_cmpk_lt_u32 s0, 0x100
	v_and_b32_e32 v5, 15, v1
	v_lshlrev_b32_e32 v4, 4, v6
	v_lshlrev_b32_e32 v1, 2, v1
	s_cselect_b64 s[30:31], -1, 0
	s_lshl_b32 s0, s9, 1
	v_lshl_or_b32 v196, s1, 6, v5
	v_lshl_or_b32 v5, v5, 6, v4
	v_and_b32_e32 v1, 32, v1
	s_add_u32 s0, s4, s0
	v_bitop3_b32 v7, v5, s8, v1 bitop3:0xde
	v_bitop3_b32 v197, v5, s12, v1 bitop3:0xde
	s_addc_u32 s1, s5, 0
	v_mov_b32_e32 v5, v171
	v_lshl_add_u64 v[4:5], s[0:1], 0, v[4:5]
	s_mov_b64 s[0:1], 0x10000000
	v_lshl_add_u64 v[158:159], v[4:5], 0, s[0:1]
	v_lshrrev_b32_e32 v1, 1, v3
	v_mul_lo_u32 v4, v12, s88
	s_mov_b32 s6, 0x16000
	v_mad_u64_u32 v[4:5], s[0:1], v1, s6, v[4:5]
	v_add3_u32 v0, v4, v0, v13
	v_mov_b32_e32 v1, v171
	s_mov_b64 s[8:9], 0xb0080
	v_lshl_add_u64 v[160:161], v[0:1], 0, s[8:9]
	v_lshrrev_b32_e32 v1, 1, v14
	v_mul_lo_u32 v0, v15, s88
	s_waitcnt vmcnt(6)
	s_mov_b32 s99, 1
	v_mad_u64_u32 v[0:1], s[0:1], v1, s6, v[0:1]
	v_add3_u32 v0, v0, v2, v16
	v_mov_b32_e32 v1, v171
	s_mov_b32 s53, 0
	v_cmp_eq_u32_e64 s[4:5], 0, v6
	v_lshl_add_u64 v[162:163], v[0:1], 0, s[8:9]
	v_add_u32_e32 v198, 0, v7
	s_barrier
	s_branch .LBB0_1050

.Lrestag_1061:
	s_add_u32 s40, s36, 0x100
	s_addc_u32 s41, s37, 0
	s_add_i32 s0, 0, 0x10000
	s_cmp_eq_u32 s12, 40
	s_cselect_b32 s45, s9, s41
	s_cselect_b32 s44, s8, s40
	s_cselect_b32 s43, s35, s59
	s_cselect_b32 s42, s34, s58
	s_add_i32 s13, 0, 0x14000
	v_add_u32_e32 v140, s0, v197
	v_add_u32_e32 v184, s13, v197
	ds_read_b128 v[128:131], v140
	ds_read_b128 v[132:135], v140 offset:1024
	ds_read_b128 v[136:139], v140 offset:2048
	ds_read_b128 v[140:143], v140 offset:3072
	ds_read_b128 v[144:147], v184
	ds_read_b128 v[148:151], v184 offset:1024
	ds_read_b128 v[164:167], v184 offset:2048
	ds_read_b128 v[184:187], v184 offset:3072
	s_add_i32 m0, s47, 0xc000
	ds_read_b128 v[188:191], v198
	ds_read_b128 v[192:195], v198 offset:1024
	ds_read_b128 v[200:203], v198 offset:2048
	ds_read_b128 v[204:207], v198 offset:3072
	ds_read_b128 v[208:211], v198 offset:4096
	ds_read_b128 v[212:215], v198 offset:5120
	ds_read_b128 v[216:219], v198 offset:6144
	ds_read_b128 v[228:231], v198 offset:7168
	global_load_lds_dwordx4 v160, s[36:37]
	s_add_i32 m0, s47, 0xe000
	s_nop 0
	global_load_lds_dwordx4 v162, s[36:37]
	s_nop 0
	s_waitcnt lgkmcnt(0)
	s_setprio 1
	s_barrier
	v_mfma_f32_16x16x32_bf16 v[124:127], v[128:131], v[188:191], 0
	v_mfma_f32_16x16x32_bf16 v[120:123], v[136:139], v[188:191], 0
	v_mfma_f32_16x16x32_bf16 v[108:111], v[128:131], v[200:203], 0
	v_mfma_f32_16x16x32_bf16 v[104:107], v[136:139], v[200:203], 0
	v_mfma_f32_16x16x32_bf16 v[92:95], v[128:131], v[208:211], 0
	v_mfma_f32_16x16x32_bf16 v[88:91], v[136:139], v[208:211], 0
	v_mfma_f32_16x16x32_bf16 v[76:79], v[128:131], v[216:219], 0
	v_mfma_f32_16x16x32_bf16 v[72:75], v[136:139], v[216:219], 0
	v_mfma_f32_16x16x32_bf16 v[124:127], v[132:135], v[192:195], v[124:127]
	v_mfma_f32_16x16x32_bf16 v[120:123], v[140:143], v[192:195], v[120:123]
	v_mfma_f32_16x16x32_bf16 v[108:111], v[132:135], v[204:207], v[108:111]
	v_mfma_f32_16x16x32_bf16 v[104:107], v[140:143], v[204:207], v[104:107]
	v_mfma_f32_16x16x32_bf16 v[92:95], v[132:135], v[212:215], v[92:95]
	v_mfma_f32_16x16x32_bf16 v[88:91], v[140:143], v[212:215], v[88:91]
	v_mfma_f32_16x16x32_bf16 v[76:79], v[132:135], v[228:231], v[76:79]
	v_mfma_f32_16x16x32_bf16 v[72:75], v[140:143], v[228:231], v[72:75]
	v_mfma_f32_16x16x32_bf16 v[116:119], v[144:147], v[188:191], 0
	v_mfma_f32_16x16x32_bf16 v[112:115], v[164:167], v[188:191], 0
	v_mfma_f32_16x16x32_bf16 v[100:103], v[144:147], v[200:203], 0
	v_mfma_f32_16x16x32_bf16 v[96:99], v[164:167], v[200:203], 0
	v_mfma_f32_16x16x32_bf16 v[84:87], v[144:147], v[208:211], 0
	v_mfma_f32_16x16x32_bf16 v[80:83], v[164:167], v[208:211], 0
	v_mfma_f32_16x16x32_bf16 v[68:71], v[144:147], v[216:219], 0
	v_mfma_f32_16x16x32_bf16 v[64:67], v[164:167], v[216:219], 0
	v_mfma_f32_16x16x32_bf16 v[116:119], v[148:151], v[192:195], v[116:119]
	v_mfma_f32_16x16x32_bf16 v[112:115], v[184:187], v[192:195], v[112:115]
	v_mfma_f32_16x16x32_bf16 v[100:103], v[148:151], v[204:207], v[100:103]
	v_mfma_f32_16x16x32_bf16 v[96:99], v[184:187], v[204:207], v[96:99]
	v_mfma_f32_16x16x32_bf16 v[84:87], v[148:151], v[212:215], v[84:87]
	v_mfma_f32_16x16x32_bf16 v[80:83], v[184:187], v[212:215], v[80:83]
	v_mfma_f32_16x16x32_bf16 v[68:71], v[148:151], v[228:231], v[68:71]
	v_mfma_f32_16x16x32_bf16 v[64:67], v[184:187], v[228:231], v[64:67]
	s_barrier
	s_setprio 0
	s_add_i32 s0, s0, s46
	v_lshl_add_u64 v[232:233], s[42:43], 0, v[170:171]
	s_mov_b32 m0, s0
	ds_read_b128 v[188:191], v198 offset:16384
	ds_read_b128 v[192:195], v198 offset:17408
	ds_read_b128 v[200:203], v198 offset:18432
	ds_read_b128 v[204:207], v198 offset:19456
	ds_read_b128 v[208:211], v198 offset:20480
	ds_read_b128 v[212:215], v198 offset:21504
	ds_read_b128 v[216:219], v198 offset:22528
	ds_read_b128 v[228:231], v198 offset:23552
	global_load_lds_dwordx4 v[232:233], off
	s_add_i32 m0, s0, 0x2000
	s_add_u32 s0, s42, 0xb0000
	v_lshl_add_u64 v[234:235], s[42:43], 0, v[156:157]
	s_addc_u32 s1, s43, 0
	s_add_i32 s13, s13, s46
	global_load_lds_dwordx4 v[234:235], off
	s_mov_b32 m0, s13
	v_lshl_add_u64 v[238:239], s[44:45], 0, v[154:155]
	global_load_lds_dwordx4 v170, s[0:1]
	s_add_i32 m0, s13, 0x2000
	s_nop 0
	global_load_lds_dwordx4 v156, s[0:1]
	v_lshl_add_u64 v[236:237], s[44:45], 0, v[152:153]
	s_cmp_eq_u32 s99, 1
	s_cbranch_scc0 .Lft_1061
	s_waitcnt vmcnt(6)
	s_mov_b32 s99, 0
.Lft_1061:
	s_waitcnt lgkmcnt(0)
	s_setprio 1
	s_barrier
	v_mfma_f32_16x16x32_bf16 v[60:63], v[128:131], v[188:191], 0
	v_mfma_f32_16x16x32_bf16 v[56:59], v[136:139], v[188:191], 0
	v_mfma_f32_16x16x32_bf16 v[44:47], v[128:131], v[200:203], 0
	v_mfma_f32_16x16x32_bf16 v[40:43], v[136:139], v[200:203], 0
	v_mfma_f32_16x16x32_bf16 v[28:31], v[128:131], v[208:211], 0
	v_mfma_f32_16x16x32_bf16 v[24:27], v[136:139], v[208:211], 0
	v_mfma_f32_16x16x32_bf16 v[12:15], v[128:131], v[216:219], 0
	v_mfma_f32_16x16x32_bf16 v[8:11], v[136:139], v[216:219], 0
	v_mfma_f32_16x16x32_bf16 v[60:63], v[132:135], v[192:195], v[60:63]
	v_mfma_f32_16x16x32_bf16 v[56:59], v[140:143], v[192:195], v[56:59]
	v_mfma_f32_16x16x32_bf16 v[44:47], v[132:135], v[204:207], v[44:47]
	v_mfma_f32_16x16x32_bf16 v[40:43], v[140:143], v[204:207], v[40:43]
	v_mfma_f32_16x16x32_bf16 v[28:31], v[132:135], v[212:215], v[28:31]
	v_mfma_f32_16x16x32_bf16 v[24:27], v[140:143], v[212:215], v[24:27]
	v_mfma_f32_16x16x32_bf16 v[12:15], v[132:135], v[228:231], v[12:15]
	v_mfma_f32_16x16x32_bf16 v[8:11], v[140:143], v[228:231], v[8:11]
	v_mfma_f32_16x16x32_bf16 v[52:55], v[144:147], v[188:191], 0
	v_mfma_f32_16x16x32_bf16 v[48:51], v[164:167], v[188:191], 0
	v_mfma_f32_16x16x32_bf16 v[36:39], v[144:147], v[200:203], 0
	v_mfma_f32_16x16x32_bf16 v[32:35], v[164:167], v[200:203], 0
	v_mfma_f32_16x16x32_bf16 v[20:23], v[144:147], v[208:211], 0
	v_mfma_f32_16x16x32_bf16 v[16:19], v[164:167], v[208:211], 0
	v_mfma_f32_16x16x32_bf16 v[4:7], v[144:147], v[216:219], 0
	v_mfma_f32_16x16x32_bf16 v[0:3], v[164:167], v[216:219], 0
	v_mfma_f32_16x16x32_bf16 v[52:55], v[148:151], v[192:195], v[52:55]
	v_mfma_f32_16x16x32_bf16 v[48:51], v[184:187], v[192:195], v[48:51]
	v_mfma_f32_16x16x32_bf16 v[36:39], v[148:151], v[204:207], v[36:39]
	v_mfma_f32_16x16x32_bf16 v[32:35], v[184:187], v[204:207], v[32:35]
	v_mfma_f32_16x16x32_bf16 v[20:23], v[148:151], v[212:215], v[20:23]
	v_mfma_f32_16x16x32_bf16 v[16:19], v[184:187], v[212:215], v[16:19]
	v_mfma_f32_16x16x32_bf16 v[4:7], v[148:151], v[228:231], v[4:7]
	v_mfma_f32_16x16x32_bf16 v[0:3], v[184:187], v[228:231], v[0:3]
	s_barrier
	s_setprio 0
	s_add_i32 s13, 0, 0x18000
	s_add_i32 s36, 0, 0x1c000
	v_add_u32_e32 v140, s13, v197
	v_add_u32_e32 v184, s36, v197
	ds_read_b128 v[128:131], v140
	ds_read_b128 v[132:135], v140 offset:1024
	ds_read_b128 v[136:139], v140 offset:2048
	ds_read_b128 v[140:143], v140 offset:3072
	ds_read_b128 v[144:147], v184
	ds_read_b128 v[148:151], v184 offset:1024
	ds_read_b128 v[164:167], v184 offset:2048
	ds_read_b128 v[184:187], v184 offset:3072
	s_add_u32 s0, s44, 0xb0000
	s_addc_u32 s1, s45, 0
	s_mov_b32 m0, s49
	ds_read_b128 v[188:191], v198 offset:32768
	ds_read_b128 v[192:195], v198 offset:33792
	ds_read_b128 v[200:203], v198 offset:34816
	ds_read_b128 v[204:207], v198 offset:35840
	ds_read_b128 v[208:211], v198 offset:36864
	ds_read_b128 v[212:215], v198 offset:37888
	ds_read_b128 v[216:219], v198 offset:38912
	ds_read_b128 v[228:231], v198 offset:39936
	global_load_lds_dwordx4 v152, s[0:1]
	s_mov_b32 m0, s50
	s_nop 0
	global_load_lds_dwordx4 v154, s[0:1]
	s_mov_b32 m0, s47
	s_nop 0
	global_load_lds_dwordx4 v[236:237], off
	s_mov_b32 m0, s48
	s_nop 0
	global_load_lds_dwordx4 v[238:239], off
	s_waitcnt vmcnt(8)
	s_waitcnt lgkmcnt(0)
	s_setprio 1
	s_barrier
	v_mfma_f32_16x16x32_bf16 v[124:127], v[128:131], v[188:191], v[124:127]
	v_mfma_f32_16x16x32_bf16 v[120:123], v[136:139], v[188:191], v[120:123]
	v_mfma_f32_16x16x32_bf16 v[108:111], v[128:131], v[200:203], v[108:111]
	v_mfma_f32_16x16x32_bf16 v[104:107], v[136:139], v[200:203], v[104:107]
	v_mfma_f32_16x16x32_bf16 v[92:95], v[128:131], v[208:211], v[92:95]
	v_mfma_f32_16x16x32_bf16 v[88:91], v[136:139], v[208:211], v[88:91]
	v_mfma_f32_16x16x32_bf16 v[76:79], v[128:131], v[216:219], v[76:79]
	v_mfma_f32_16x16x32_bf16 v[72:75], v[136:139], v[216:219], v[72:75]
	v_mfma_f32_16x16x32_bf16 v[124:127], v[132:135], v[192:195], v[124:127]
	v_mfma_f32_16x16x32_bf16 v[120:123], v[140:143], v[192:195], v[120:123]
	v_mfma_f32_16x16x32_bf16 v[108:111], v[132:135], v[204:207], v[108:111]
	v_mfma_f32_16x16x32_bf16 v[104:107], v[140:143], v[204:207], v[104:107]
	v_mfma_f32_16x16x32_bf16 v[92:95], v[132:135], v[212:215], v[92:95]
	v_mfma_f32_16x16x32_bf16 v[88:91], v[140:143], v[212:215], v[88:91]
	v_mfma_f32_16x16x32_bf16 v[76:79], v[132:135], v[228:231], v[76:79]
	v_mfma_f32_16x16x32_bf16 v[72:75], v[140:143], v[228:231], v[72:75]
	v_mfma_f32_16x16x32_bf16 v[116:119], v[144:147], v[188:191], v[116:119]
	v_mfma_f32_16x16x32_bf16 v[112:115], v[164:167], v[188:191], v[112:115]
	v_mfma_f32_16x16x32_bf16 v[100:103], v[144:147], v[200:203], v[100:103]
	v_mfma_f32_16x16x32_bf16 v[96:99], v[164:167], v[200:203], v[96:99]
	v_mfma_f32_16x16x32_bf16 v[84:87], v[144:147], v[208:211], v[84:87]
	v_mfma_f32_16x16x32_bf16 v[80:83], v[164:167], v[208:211], v[80:83]
	v_mfma_f32_16x16x32_bf16 v[68:71], v[144:147], v[216:219], v[68:71]
	v_mfma_f32_16x16x32_bf16 v[64:67], v[164:167], v[216:219], v[64:67]
	v_mfma_f32_16x16x32_bf16 v[116:119], v[148:151], v[192:195], v[116:119]
	v_mfma_f32_16x16x32_bf16 v[112:115], v[184:187], v[192:195], v[112:115]
	v_mfma_f32_16x16x32_bf16 v[100:103], v[148:151], v[204:207], v[100:103]
	v_mfma_f32_16x16x32_bf16 v[96:99], v[184:187], v[204:207], v[96:99]
	v_mfma_f32_16x16x32_bf16 v[84:87], v[148:151], v[212:215], v[84:87]
	v_mfma_f32_16x16x32_bf16 v[80:83], v[184:187], v[212:215], v[80:83]
	v_mfma_f32_16x16x32_bf16 v[68:71], v[148:151], v[228:231], v[68:71]
	v_mfma_f32_16x16x32_bf16 v[64:67], v[184:187], v[228:231], v[64:67]
	s_barrier
	s_setprio 0
	s_add_i32 s0, s13, s46
	v_lshl_add_u64 v[232:233], v[232:233], 0, s[16:17]
	s_mov_b32 m0, s0
	ds_read_b128 v[188:191], v198 offset:49152
	ds_read_b128 v[192:195], v198 offset:50176
	ds_read_b128 v[200:203], v198 offset:51200
	ds_read_b128 v[204:207], v198 offset:52224
	ds_read_b128 v[208:211], v198 offset:53248
	ds_read_b128 v[212:215], v198 offset:54272
	ds_read_b128 v[216:219], v198 offset:55296
	ds_read_b128 v[228:231], v198 offset:56320
	global_load_lds_dwordx4 v[232:233], off
	s_add_i32 m0, s0, 0x2000
	s_add_u32 s0, s42, 0xb0080
	v_lshl_add_u64 v[232:233], v[234:235], 0, s[16:17]
	s_addc_u32 s1, s43, 0
	s_add_i32 s13, s36, s46
	global_load_lds_dwordx4 v[232:233], off
	s_mov_b32 m0, s13
	s_nop 0
	global_load_lds_dwordx4 v170, s[0:1]
	s_add_i32 m0, s13, 0x2000
	s_nop 0
	global_load_lds_dwordx4 v156, s[0:1]
	v_lshl_add_u64 v[232:233], v[236:237], 0, s[16:17]
	s_mov_b32 m0, s51
	s_nop 0
	global_load_lds_dwordx4 v[232:233], off
	v_lshl_add_u64 v[232:233], v[238:239], 0, s[16:17]
	s_mov_b32 m0, s52
	s_nop 0
	global_load_lds_dwordx4 v[232:233], off
	s_waitcnt vmcnt(6)
	s_waitcnt lgkmcnt(0)
	s_setprio 1
	s_barrier
	v_mfma_f32_16x16x32_bf16 v[60:63], v[128:131], v[188:191], v[60:63]
	v_mfma_f32_16x16x32_bf16 v[56:59], v[136:139], v[188:191], v[56:59]
	v_mfma_f32_16x16x32_bf16 v[44:47], v[128:131], v[200:203], v[44:47]
	v_mfma_f32_16x16x32_bf16 v[40:43], v[136:139], v[200:203], v[40:43]
	v_mfma_f32_16x16x32_bf16 v[28:31], v[128:131], v[208:211], v[28:31]
	v_mfma_f32_16x16x32_bf16 v[24:27], v[136:139], v[208:211], v[24:27]
	v_mfma_f32_16x16x32_bf16 v[12:15], v[128:131], v[216:219], v[12:15]
	v_mfma_f32_16x16x32_bf16 v[8:11], v[136:139], v[216:219], v[8:11]
	v_mfma_f32_16x16x32_bf16 v[60:63], v[132:135], v[192:195], v[60:63]
	v_mfma_f32_16x16x32_bf16 v[56:59], v[140:143], v[192:195], v[56:59]
	v_mfma_f32_16x16x32_bf16 v[44:47], v[132:135], v[204:207], v[44:47]
	v_mfma_f32_16x16x32_bf16 v[40:43], v[140:143], v[204:207], v[40:43]
	v_mfma_f32_16x16x32_bf16 v[28:31], v[132:135], v[212:215], v[28:31]
	v_mfma_f32_16x16x32_bf16 v[24:27], v[140:143], v[212:215], v[24:27]
	v_mfma_f32_16x16x32_bf16 v[12:15], v[132:135], v[228:231], v[12:15]
	v_mfma_f32_16x16x32_bf16 v[8:11], v[140:143], v[228:231], v[8:11]
	v_mfma_f32_16x16x32_bf16 v[52:55], v[144:147], v[188:191], v[52:55]
	v_mfma_f32_16x16x32_bf16 v[48:51], v[164:167], v[188:191], v[48:51]
	v_mfma_f32_16x16x32_bf16 v[36:39], v[144:147], v[200:203], v[36:39]
	v_mfma_f32_16x16x32_bf16 v[32:35], v[164:167], v[200:203], v[32:35]
	v_mfma_f32_16x16x32_bf16 v[20:23], v[144:147], v[208:211], v[20:23]
	v_mfma_f32_16x16x32_bf16 v[16:19], v[164:167], v[208:211], v[16:19]
	v_mfma_f32_16x16x32_bf16 v[4:7], v[144:147], v[216:219], v[4:7]
	v_mfma_f32_16x16x32_bf16 v[0:3], v[164:167], v[216:219], v[0:3]
	v_mfma_f32_16x16x32_bf16 v[52:55], v[148:151], v[192:195], v[52:55]
	v_mfma_f32_16x16x32_bf16 v[48:51], v[184:187], v[192:195], v[48:51]
	v_mfma_f32_16x16x32_bf16 v[36:39], v[148:151], v[204:207], v[36:39]
	v_mfma_f32_16x16x32_bf16 v[32:35], v[184:187], v[204:207], v[32:35]
	v_mfma_f32_16x16x32_bf16 v[20:23], v[148:151], v[212:215], v[20:23]
	v_mfma_f32_16x16x32_bf16 v[16:19], v[184:187], v[212:215], v[16:19]
	v_mfma_f32_16x16x32_bf16 v[4:7], v[148:151], v[228:231], v[4:7]
	v_mfma_f32_16x16x32_bf16 v[0:3], v[184:187], v[228:231], v[0:3]
	s_barrier
	s_setprio 0
	s_add_i32 s12, s12, 2
	s_add_u32 s58, s58, 0x100
	s_addc_u32 s59, s59, 0
	s_cmp_gt_u32 s12, 41
	s_mov_b64 s[36:37], s[40:41]
